# attention (fox+DSA) tile loop: hoisted LDS reads, max3 tree, PV MFMAs interleaved with exp; removed redundant accumulator zeroing in 4 GEMM phases
# speedup vs baseline: 1.2293x; 1.2293x over previous
; #define PG8_STAGE(bufoff, gbase, voff) do { _Pragma("unroll") for (int _i = 0; _i < 2; ++_i) \
;         __builtin_amdgcn_global_load_lds((const unsigned*)((const char*)(gbase) + (voff)[_i]), (PG8_LAS unsigned*)(lds + (bufoff) + ldsw + _i * 8192), 16, 0, 0); } while (0)
; #define PG8_LDA(dst, b, h) do { _Pragma("unroll") for (int m = 0; m < 4; ++m) _Pragma("unroll") for (int k = 0; k < 2; ++k) dst[m][k] = *(const PG8_LAS bf16x8*)(lds + PG8_SA(b, h) + aoff + m * 2048 + k * 1024); } while (0)
; #define PG8_LDB(dst, b, h) do { _Pragma("unroll") for (int n = 0; n < 2; ++n) _Pragma("unroll") for (int k = 0; k < 2; ++k) dst[n][k] = *(const PG8_LAS bf16x8*)(lds + PG8_SB(b, h) + boff + n * 2048 + k * 1024); } while (0)
; #define PG8_MMA(ai, bj, At, Bt) do { __builtin_amdgcn_s_setprio(1); _Pragma("unroll") for (int m = 0; m < 4; ++m) _Pragma("unroll") for (int n = 0; n < 2; ++n) _Pragma("unroll") for (int k = 0; k < 2; ++k) \
;         acc[ai][bj][m][n] = __builtin_amdgcn_mfma_f32_16x16x32_bf16(Bt[n][k], At[m][k], acc[ai][bj][m][n], 0, 0, 0); __builtin_amdgcn_s_setprio(0); } while (0)
; #define PG8_WAIT_V(n) asm volatile("s_waitcnt vmcnt(" #n ")" ::: "memory")
; #define PG8_BAR __builtin_amdgcn_s_barrier()
; template <class Epi, class Sched, bool ALIGN_EPI = false, bool SP2 = false>
; __device__ __forceinline__ void gemm_phase(PG8_LAS unsigned char* lds, const Gemm g, const Sched& S, const Epi& E) {
;     ...
;         for (int t = t0; t < t1; t += 2) {
;             const bool last = (t == nt - 2);
;             const char* a1 = cA + (size_t)(t + 1) * kstep;
;             const char* a2 = last ? nA : cA + (size_t)(t + 2) * kstep; const char* b2 = last ? nB : cB + (size_t)(t + 2) * kstep;
;             const char* a3 = a2 + kstep; const char* b3 = b2 + kstep;
;             if (last && has_next) S.a_ready(nxt);
;             if constexpr (SP2) {
;             PG8_LDB(B0, 0, 0); PG8_LDB(B1, 0, 1); PG8_SCHED; PG8_LDA(At, 0, 0); PG8_STAGE(PG8_SA(1, 1), a1 + hstep, voffA);
;             PG8_WAIT_V(8); PG8_WAIT_L(0); PG8_BAR; PG8_MMA(0, 0, At, B0); PG8_MMA(0, 1, At, B1); PG8_BAR; PG8_SCHED;
;     ...
; #pragma unroll
;         for (int a = 0; a < 2; ++a)
; #pragma unroll
;             for (int b = 0; b < 2; ++b)
; #pragma unroll
;                 for (int m = 0; m < 4; ++m)
; #pragma unroll
;                     for (int n = 0; n < 2; ++n) acc[a][b][m][n] = (f32x4){0.f, 0.f, 0.f, 0.f};
.LBB0_131:
	v_mov_b32_e32 v129, 0
	s_andn2_b64 vcc, exec, s[36:37]
	v_mov_b32_e32 v128, v129
	v_mov_b32_e32 v127, v129
	v_mov_b32_e32 v126, v129
	v_mov_b32_e32 v125, v129
	v_mov_b32_e32 v124, v129
	v_mov_b32_e32 v123, v129
	v_mov_b32_e32 v122, v129
	v_mov_b32_e32 v113, v129
	v_mov_b32_e32 v112, v129
	v_mov_b32_e32 v111, v129
	v_mov_b32_e32 v110, v129
	v_mov_b32_e32 v109, v129
	v_mov_b32_e32 v108, v129
	v_mov_b32_e32 v107, v129
	v_mov_b32_e32 v106, v129
	v_mov_b32_e32 v97, v129
	v_mov_b32_e32 v96, v129
	v_mov_b32_e32 v95, v129
	v_mov_b32_e32 v94, v129
	v_mov_b32_e32 v93, v129
	v_mov_b32_e32 v92, v129
	v_mov_b32_e32 v91, v129
	v_mov_b32_e32 v90, v129
	v_mov_b32_e32 v81, v129
	v_mov_b32_e32 v80, v129
	v_mov_b32_e32 v79, v129
	v_mov_b32_e32 v78, v129
	v_mov_b32_e32 v77, v129
	v_mov_b32_e32 v76, v129
	v_mov_b32_e32 v75, v129
	v_mov_b32_e32 v74, v129
	v_mov_b32_e32 v121, v129
	v_mov_b32_e32 v120, v129
	v_mov_b32_e32 v119, v129
	v_mov_b32_e32 v118, v129
	v_mov_b32_e32 v117, v129
	v_mov_b32_e32 v116, v129
	v_mov_b32_e32 v115, v129
	v_mov_b32_e32 v114, v129
	v_mov_b32_e32 v105, v129
	v_mov_b32_e32 v104, v129
	v_mov_b32_e32 v103, v129
	v_mov_b32_e32 v102, v129
	v_mov_b32_e32 v101, v129
	v_mov_b32_e32 v100, v129
	v_mov_b32_e32 v99, v129
	v_mov_b32_e32 v98, v129
	v_mov_b32_e32 v89, v129
	v_mov_b32_e32 v88, v129
	v_mov_b32_e32 v87, v129
	v_mov_b32_e32 v86, v129
	v_mov_b32_e32 v85, v129
	v_mov_b32_e32 v84, v129
	v_mov_b32_e32 v83, v129
	v_mov_b32_e32 v82, v129
	v_mov_b32_e32 v73, v129
	v_mov_b32_e32 v72, v129
	v_mov_b32_e32 v71, v129
	v_mov_b32_e32 v70, v129
	v_mov_b32_e32 v69, v129
	v_mov_b32_e32 v68, v129
	v_mov_b32_e32 v67, v129
	v_mov_b32_e32 v66, v129
	s_waitcnt vmcnt(0)
	v_mov_b32_e32 v65, v129
	v_mov_b32_e32 v64, v129
	v_mov_b32_e32 v63, v129
	v_mov_b32_e32 v62, v129
	v_mov_b32_e32 v61, v129
	v_mov_b32_e32 v60, v129
	v_mov_b32_e32 v59, v129
	v_mov_b32_e32 v58, v129
	v_mov_b32_e32 v49, v129
	v_mov_b32_e32 v48, v129
	v_mov_b32_e32 v47, v129
	v_mov_b32_e32 v46, v129
	v_mov_b32_e32 v45, v129
	v_mov_b32_e32 v44, v129
	v_mov_b32_e32 v43, v129
	v_mov_b32_e32 v42, v129
	v_mov_b32_e32 v33, v129
	v_mov_b32_e32 v32, v129
	v_mov_b32_e32 v31, v129
	v_mov_b32_e32 v30, v129
	v_mov_b32_e32 v29, v129
	v_mov_b32_e32 v28, v129
	v_mov_b32_e32 v27, v129
	v_mov_b32_e32 v26, v129
	v_mov_b32_e32 v17, v129
	v_mov_b32_e32 v16, v129
	v_mov_b32_e32 v15, v129
	v_mov_b32_e32 v14, v129
	v_mov_b32_e32 v13, v129
	v_mov_b32_e32 v12, v129
	v_mov_b32_e32 v11, v129
	v_mov_b32_e32 v10, v129
	v_mov_b32_e32 v57, v129
	v_mov_b32_e32 v56, v129
	v_mov_b32_e32 v55, v129
	v_mov_b32_e32 v54, v129
	v_mov_b32_e32 v53, v129
	v_mov_b32_e32 v52, v129
	v_mov_b32_e32 v51, v129
	v_mov_b32_e32 v50, v129
	v_mov_b32_e32 v41, v129
	v_mov_b32_e32 v40, v129
	v_mov_b32_e32 v39, v129
	v_mov_b32_e32 v38, v129
	v_mov_b32_e32 v37, v129
	v_mov_b32_e32 v36, v129
	v_mov_b32_e32 v35, v129
	v_mov_b32_e32 v34, v129
	v_mov_b32_e32 v25, v129
	v_mov_b32_e32 v24, v129
	v_mov_b32_e32 v23, v129
	v_mov_b32_e32 v22, v129
	v_mov_b32_e32 v21, v129
	v_mov_b32_e32 v20, v129
	v_mov_b32_e32 v19, v129
	v_mov_b32_e32 v18, v129
	v_mov_b32_e32 v9, v129
	v_mov_b32_e32 v8, v129
	v_mov_b32_e32 v7, v129
	v_mov_b32_e32 v6, v129
	v_mov_b32_e32 v5, v129
	v_mov_b32_e32 v4, v129
	v_mov_b32_e32 v3, v129
	v_mov_b32_e32 v2, v129
	s_cbranch_vccnz .LBB0_134
	s_add_u32 s10, s4, 0x100
	s_addc_u32 s11, s5, 0
	s_add_u32 s2, s6, 0x80
	v_mov_b32_e32 v2, 0
	s_addc_u32 s3, s7, 0
	s_mov_b32 s4, 0
.LBB0_133:
	s_add_i32 s6, s4, 2
	s_add_u32 s7, s2, 0x80
	s_addc_u32 s5, s3, 0
	s_add_i32 s14, 0, 0x10000
	s_cmp_eq_u32 s71, s4
	s_cselect_b32 s5, s41, s5
	s_cselect_b32 s4, s40, s7
	s_cselect_b32 s13, s43, s11
	s_cselect_b32 s12, s42, s10
	s_add_i32 s7, 0, 0x14000
	v_add_u32_e32 v142, s14, v183
	v_add_u32_e32 v158, s7, v183
	ds_read_b128 v[130:133], v142
	ds_read_b128 v[134:137], v142 offset:1024
	ds_read_b128 v[138:141], v142 offset:2048
	ds_read_b128 v[142:145], v142 offset:3072
	ds_read_b128 v[146:149], v158
	ds_read_b128 v[150:153], v158 offset:1024
	ds_read_b128 v[154:157], v158 offset:2048
	ds_read_b128 v[158:161], v158 offset:3072
	v_lshl_add_u64 v[214:215], s[2:3], 0, v[172:173]
	s_add_i32 m0, s61, 0xc000
	ds_read_b128 v[174:177], v184
	ds_read_b128 v[178:181], v184 offset:1024
	ds_read_b128 v[186:189], v184 offset:2048
	ds_read_b128 v[190:193], v184 offset:3072
	ds_read_b128 v[196:199], v184 offset:4096
	ds_read_b128 v[200:203], v184 offset:5120
	ds_read_b128 v[206:209], v184 offset:6144
	ds_read_b128 v[210:213], v184 offset:7168
	global_load_lds_dwordx4 v[214:215], off
	v_lshl_add_u64 v[214:215], s[2:3], 0, v[170:171]
	s_add_i32 m0, s61, 0xe000
	s_nop 0
	global_load_lds_dwordx4 v[214:215], off
	s_waitcnt vmcnt(8)
	s_waitcnt lgkmcnt(0)
	s_barrier
; #define PG8_STAGE(bufoff, gbase, voff) do { _Pragma("unroll") for (int _i = 0; _i < 2; ++_i) \
;         __builtin_amdgcn_global_load_lds((const unsigned*)((const char*)(gbase) + (voff)[_i]), (PG8_LAS unsigned*)(lds + (bufoff) + ldsw + _i * 8192), 16, 0, 0); } while (0)
; #define PG8_LDA(dst, b, h) do { _Pragma("unroll") for (int m = 0; m < 4; ++m) _Pragma("unroll") for (int k = 0; k < 2; ++k) dst[m][k] = *(const PG8_LAS bf16x8*)(lds + PG8_SA(b, h) + aoff + m * 2048 + k * 1024); } while (0)
; #define PG8_MMA(ai, bj, At, Bt) do { __builtin_amdgcn_s_setprio(1); _Pragma("unroll") for (int m = 0; m < 4; ++m) _Pragma("unroll") for (int n = 0; n < 2; ++n) _Pragma("unroll") for (int k = 0; k < 2; ++k) \
;         acc[ai][bj][m][n] = __builtin_amdgcn_mfma_f32_16x16x32_bf16(Bt[n][k], At[m][k], acc[ai][bj][m][n], 0, 0, 0); __builtin_amdgcn_s_setprio(0); } while (0)
; #define PG8_WAIT_V(n) asm volatile("s_waitcnt vmcnt(" #n ")" ::: "memory")
; #define PG8_WAIT_L(n) asm volatile("s_waitcnt lgkmcnt(" #n ")" ::: "memory")
; #define PG8_BAR __builtin_amdgcn_s_barrier()
; #define PG8_SCHED __builtin_amdgcn_sched_barrier(0)
; template <class Epi, class Sched, bool ALIGN_EPI = false, bool SP2 = false>
; __device__ __forceinline__ void gemm_phase(PG8_LAS unsigned char* lds, const Gemm g, const Sched& S, const Epi& E) {
;     ...
;             PG8_WAIT_V(8); PG8_WAIT_L(0); PG8_BAR; PG8_MMA(0, 0, At, B0); PG8_MMA(0, 1, At, B1); PG8_BAR; PG8_SCHED;
;             PG8_LDA(At, 0, 1); PG8_STAGE(PG8_SB(0, 0), b2, voffB); PG8_STAGE(PG8_SB(0, 1), b2 + hstep, voffB); PG8_STAGE(PG8_SA(0, 0), a2, voffA);
;             PG8_WAIT_V(8); PG8_WAIT_L(0); PG8_BAR; PG8_MMA(1, 0, At, B0); PG8_MMA(1, 1, At, B1); PG8_BAR; PG8_SCHED;
	s_setprio 1
	s_waitcnt lgkmcnt(0)
	v_mfma_f32_16x16x32_bf16 v[126:129], v[130:133], v[174:177], v[126:129]
	v_mfma_f32_16x16x32_bf16 v[122:125], v[138:141], v[174:177], v[122:125]
	v_mfma_f32_16x16x32_bf16 v[110:113], v[130:133], v[186:189], v[110:113]
	v_mfma_f32_16x16x32_bf16 v[106:109], v[138:141], v[186:189], v[106:109]
	v_mfma_f32_16x16x32_bf16 v[94:97], v[130:133], v[196:199], v[94:97]
	v_mfma_f32_16x16x32_bf16 v[90:93], v[138:141], v[196:199], v[90:93]
	v_mfma_f32_16x16x32_bf16 v[78:81], v[130:133], v[206:209], v[78:81]
	v_mfma_f32_16x16x32_bf16 v[74:77], v[138:141], v[206:209], v[74:77]
	v_mfma_f32_16x16x32_bf16 v[126:129], v[134:137], v[178:181], v[126:129]
	v_mfma_f32_16x16x32_bf16 v[122:125], v[142:145], v[178:181], v[122:125]
	v_mfma_f32_16x16x32_bf16 v[110:113], v[134:137], v[190:193], v[110:113]
	v_mfma_f32_16x16x32_bf16 v[106:109], v[142:145], v[190:193], v[106:109]
	v_mfma_f32_16x16x32_bf16 v[94:97], v[134:137], v[200:203], v[94:97]
	v_mfma_f32_16x16x32_bf16 v[90:93], v[142:145], v[200:203], v[90:93]
	v_mfma_f32_16x16x32_bf16 v[78:81], v[134:137], v[210:213], v[78:81]
	v_mfma_f32_16x16x32_bf16 v[74:77], v[142:145], v[210:213], v[74:77]
	s_setprio 0
	s_setprio 1
	v_mfma_f32_16x16x32_bf16 v[118:121], v[146:149], v[174:177], v[118:121]
	v_mfma_f32_16x16x32_bf16 v[114:117], v[154:157], v[174:177], v[114:117]
	v_mfma_f32_16x16x32_bf16 v[102:105], v[146:149], v[186:189], v[102:105]
	v_mfma_f32_16x16x32_bf16 v[98:101], v[154:157], v[186:189], v[98:101]
	v_mfma_f32_16x16x32_bf16 v[86:89], v[146:149], v[196:199], v[86:89]
	v_mfma_f32_16x16x32_bf16 v[82:85], v[154:157], v[196:199], v[82:85]
	v_mfma_f32_16x16x32_bf16 v[70:73], v[146:149], v[206:209], v[70:73]
	v_mfma_f32_16x16x32_bf16 v[66:69], v[154:157], v[206:209], v[66:69]
	v_mfma_f32_16x16x32_bf16 v[118:121], v[150:153], v[178:181], v[118:121]
	v_mfma_f32_16x16x32_bf16 v[114:117], v[158:161], v[178:181], v[114:117]
	v_mfma_f32_16x16x32_bf16 v[102:105], v[150:153], v[190:193], v[102:105]
	v_mfma_f32_16x16x32_bf16 v[98:101], v[158:161], v[190:193], v[98:101]
	v_mfma_f32_16x16x32_bf16 v[86:89], v[150:153], v[200:203], v[86:89]
	v_mfma_f32_16x16x32_bf16 v[82:85], v[158:161], v[200:203], v[82:85]
	v_mfma_f32_16x16x32_bf16 v[70:73], v[150:153], v[210:213], v[70:73]
	v_mfma_f32_16x16x32_bf16 v[66:69], v[158:161], v[210:213], v[66:69]
	s_setprio 0
	s_barrier
	s_add_i32 s14, s14, s60
	v_lshl_add_u64 v[214:215], s[12:13], 0, v[164:165]
	s_mov_b32 m0, s14
	ds_read_b128 v[174:177], v184 offset:16384
	ds_read_b128 v[178:181], v184 offset:17408
	ds_read_b128 v[186:189], v184 offset:18432
	ds_read_b128 v[190:193], v184 offset:19456
	ds_read_b128 v[196:199], v184 offset:20480
	ds_read_b128 v[200:203], v184 offset:21504
	ds_read_b128 v[206:209], v184 offset:22528
	ds_read_b128 v[210:213], v184 offset:23552
	global_load_lds_dwordx4 v[214:215], off
	s_add_i32 m0, s14, 0x2000
	v_lshl_add_u64 v[216:217], s[12:13], 0, v[168:169]
	s_add_u32 s12, s12, s18
	s_addc_u32 s13, s13, s19
	s_add_i32 s7, s7, s60
	global_load_lds_dwordx4 v[216:217], off
	v_lshl_add_u64 v[218:219], s[12:13], 0, v[164:165]
	s_mov_b32 m0, s7
	v_lshl_add_u64 v[234:235], s[12:13], 0, v[168:169]
	global_load_lds_dwordx4 v[218:219], off
	s_add_i32 m0, s7, 0x2000
	v_lshl_add_u64 v[236:237], s[4:5], 0, v[162:163]
	global_load_lds_dwordx4 v[234:235], off
	s_mov_b32 m0, s61
	v_lshl_add_u64 v[238:239], s[4:5], 0, v[166:167]
	global_load_lds_dwordx4 v[236:237], off
	s_mov_b32 m0, s62
	s_nop 0
	global_load_lds_dwordx4 v[238:239], off
	s_waitcnt vmcnt(8)
	s_waitcnt lgkmcnt(0)
	s_barrier
	s_setprio 1
	s_waitcnt lgkmcnt(0)
	v_mfma_f32_16x16x32_bf16 v[62:65], v[130:133], v[174:177], v[62:65]
	v_mfma_f32_16x16x32_bf16 v[58:61], v[138:141], v[174:177], v[58:61]
	v_mfma_f32_16x16x32_bf16 v[46:49], v[130:133], v[186:189], v[46:49]
	v_mfma_f32_16x16x32_bf16 v[42:45], v[138:141], v[186:189], v[42:45]
	v_mfma_f32_16x16x32_bf16 v[30:33], v[130:133], v[196:199], v[30:33]
	v_mfma_f32_16x16x32_bf16 v[26:29], v[138:141], v[196:199], v[26:29]
	v_mfma_f32_16x16x32_bf16 v[14:17], v[130:133], v[206:209], v[14:17]
	v_mfma_f32_16x16x32_bf16 v[10:13], v[138:141], v[206:209], v[10:13]
	v_mfma_f32_16x16x32_bf16 v[62:65], v[134:137], v[178:181], v[62:65]
	v_mfma_f32_16x16x32_bf16 v[58:61], v[142:145], v[178:181], v[58:61]
	v_mfma_f32_16x16x32_bf16 v[46:49], v[134:137], v[190:193], v[46:49]
	v_mfma_f32_16x16x32_bf16 v[42:45], v[142:145], v[190:193], v[42:45]
	v_mfma_f32_16x16x32_bf16 v[30:33], v[134:137], v[200:203], v[30:33]
	v_mfma_f32_16x16x32_bf16 v[26:29], v[142:145], v[200:203], v[26:29]
	v_mfma_f32_16x16x32_bf16 v[14:17], v[134:137], v[210:213], v[14:17]
	v_mfma_f32_16x16x32_bf16 v[10:13], v[142:145], v[210:213], v[10:13]
	s_setprio 0
	s_setprio 1
	v_mfma_f32_16x16x32_bf16 v[54:57], v[146:149], v[174:177], v[54:57]
	v_mfma_f32_16x16x32_bf16 v[50:53], v[154:157], v[174:177], v[50:53]
	v_mfma_f32_16x16x32_bf16 v[38:41], v[146:149], v[186:189], v[38:41]
	v_mfma_f32_16x16x32_bf16 v[34:37], v[154:157], v[186:189], v[34:37]
	v_mfma_f32_16x16x32_bf16 v[22:25], v[146:149], v[196:199], v[22:25]
	v_mfma_f32_16x16x32_bf16 v[18:21], v[154:157], v[196:199], v[18:21]
	v_mfma_f32_16x16x32_bf16 v[6:9], v[146:149], v[206:209], v[6:9]
	v_mfma_f32_16x16x32_bf16 v[2:5], v[154:157], v[206:209], v[2:5]
	v_mfma_f32_16x16x32_bf16 v[54:57], v[150:153], v[178:181], v[54:57]
	v_mfma_f32_16x16x32_bf16 v[50:53], v[158:161], v[178:181], v[50:53]
	v_mfma_f32_16x16x32_bf16 v[38:41], v[150:153], v[190:193], v[38:41]
	v_mfma_f32_16x16x32_bf16 v[34:37], v[158:161], v[190:193], v[34:37]
	v_mfma_f32_16x16x32_bf16 v[22:25], v[150:153], v[200:203], v[22:25]
	v_mfma_f32_16x16x32_bf16 v[18:21], v[158:161], v[200:203], v[18:21]
	v_mfma_f32_16x16x32_bf16 v[6:9], v[150:153], v[210:213], v[6:9]
	v_mfma_f32_16x16x32_bf16 v[2:5], v[158:161], v[210:213], v[2:5]
	s_setprio 0
	s_barrier
; #define PG8_STAGE(bufoff, gbase, voff) do { _Pragma("unroll") for (int _i = 0; _i < 2; ++_i) \
;         __builtin_amdgcn_global_load_lds((const unsigned*)((const char*)(gbase) + (voff)[_i]), (PG8_LAS unsigned*)(lds + (bufoff) + ldsw + _i * 8192), 16, 0, 0); } while (0)
; #define PG8_LDA(dst, b, h) do { _Pragma("unroll") for (int m = 0; m < 4; ++m) _Pragma("unroll") for (int k = 0; k < 2; ++k) dst[m][k] = *(const PG8_LAS bf16x8*)(lds + PG8_SA(b, h) + aoff + m * 2048 + k * 1024); } while (0)
; #define PG8_LDB(dst, b, h) do { _Pragma("unroll") for (int n = 0; n < 2; ++n) _Pragma("unroll") for (int k = 0; k < 2; ++k) dst[n][k] = *(const PG8_LAS bf16x8*)(lds + PG8_SB(b, h) + boff + n * 2048 + k * 1024); } while (0)
; #define PG8_MMA(ai, bj, At, Bt) do { __builtin_amdgcn_s_setprio(1); _Pragma("unroll") for (int m = 0; m < 4; ++m) _Pragma("unroll") for (int n = 0; n < 2; ++n) _Pragma("unroll") for (int k = 0; k < 2; ++k) \
;         acc[ai][bj][m][n] = __builtin_amdgcn_mfma_f32_16x16x32_bf16(Bt[n][k], At[m][k], acc[ai][bj][m][n], 0, 0, 0); __builtin_amdgcn_s_setprio(0); } while (0)
; #define PG8_WAIT_V(n) asm volatile("s_waitcnt vmcnt(" #n ")" ::: "memory")
; #define PG8_WAIT_L(n) asm volatile("s_waitcnt lgkmcnt(" #n ")" ::: "memory")
; #define PG8_BAR __builtin_amdgcn_s_barrier()
; #define PG8_SCHED __builtin_amdgcn_sched_barrier(0)
; template <class Epi, class Sched, bool ALIGN_EPI = false, bool SP2 = false>
; __device__ __forceinline__ void gemm_phase(PG8_LAS unsigned char* lds, const Gemm g, const Sched& S, const Epi& E) {
;     ...
;             PG8_LDB(B0, 1, 0); PG8_LDB(B1, 1, 1); PG8_SCHED; PG8_LDA(At, 1, 0); PG8_STAGE(PG8_SA(0, 1), a2 + hstep, voffA);
;             PG8_WAIT_V(8); PG8_WAIT_L(0); PG8_BAR; PG8_MMA(0, 0, At, B0); PG8_MMA(0, 1, At, B1); PG8_BAR; PG8_SCHED;
	s_add_i32 s7, 0, 0x18000
	s_add_i32 s12, 0, 0x1c000
	v_add_u32_e32 v142, s7, v183
	v_add_u32_e32 v158, s12, v183
	ds_read_b128 v[130:133], v142
	ds_read_b128 v[134:137], v142 offset:1024
	ds_read_b128 v[138:141], v142 offset:2048
	ds_read_b128 v[142:145], v142 offset:3072
	ds_read_b128 v[146:149], v158
	ds_read_b128 v[150:153], v158 offset:1024
	ds_read_b128 v[154:157], v158 offset:2048
	ds_read_b128 v[158:161], v158 offset:3072
	s_add_u32 s4, s4, s18
	s_addc_u32 s5, s5, s19
	s_mov_b32 m0, s63
	v_lshl_add_u64 v[240:241], s[4:5], 0, v[162:163]
	ds_read_b128 v[174:177], v184 offset:32768
	ds_read_b128 v[178:181], v184 offset:33792
	ds_read_b128 v[186:189], v184 offset:34816
	ds_read_b128 v[190:193], v184 offset:35840
	ds_read_b128 v[196:199], v184 offset:36864
	ds_read_b128 v[200:203], v184 offset:37888
	ds_read_b128 v[206:209], v184 offset:38912
	ds_read_b128 v[210:213], v184 offset:39936
	global_load_lds_dwordx4 v[240:241], off
	v_lshl_add_u64 v[240:241], s[4:5], 0, v[166:167]
	s_mov_b32 m0, s64
	s_nop 0
	global_load_lds_dwordx4 v[240:241], off
	s_waitcnt vmcnt(8)
	s_waitcnt lgkmcnt(0)
	s_barrier
	s_setprio 1
	s_waitcnt lgkmcnt(0)
	v_mfma_f32_16x16x32_bf16 v[126:129], v[130:133], v[174:177], v[126:129]
	v_mfma_f32_16x16x32_bf16 v[122:125], v[138:141], v[174:177], v[122:125]
	v_mfma_f32_16x16x32_bf16 v[110:113], v[130:133], v[186:189], v[110:113]
	v_mfma_f32_16x16x32_bf16 v[106:109], v[138:141], v[186:189], v[106:109]
	v_mfma_f32_16x16x32_bf16 v[94:97], v[130:133], v[196:199], v[94:97]
	v_mfma_f32_16x16x32_bf16 v[90:93], v[138:141], v[196:199], v[90:93]
	v_mfma_f32_16x16x32_bf16 v[78:81], v[130:133], v[206:209], v[78:81]
	v_mfma_f32_16x16x32_bf16 v[74:77], v[138:141], v[206:209], v[74:77]
	v_mfma_f32_16x16x32_bf16 v[126:129], v[134:137], v[178:181], v[126:129]
	v_mfma_f32_16x16x32_bf16 v[122:125], v[142:145], v[178:181], v[122:125]
	v_mfma_f32_16x16x32_bf16 v[110:113], v[134:137], v[190:193], v[110:113]
	v_mfma_f32_16x16x32_bf16 v[106:109], v[142:145], v[190:193], v[106:109]
	v_mfma_f32_16x16x32_bf16 v[94:97], v[134:137], v[200:203], v[94:97]
	v_mfma_f32_16x16x32_bf16 v[90:93], v[142:145], v[200:203], v[90:93]
	v_mfma_f32_16x16x32_bf16 v[78:81], v[134:137], v[210:213], v[78:81]
	v_mfma_f32_16x16x32_bf16 v[74:77], v[142:145], v[210:213], v[74:77]
	s_setprio 0
	s_setprio 1
	v_mfma_f32_16x16x32_bf16 v[118:121], v[146:149], v[174:177], v[118:121]
	v_mfma_f32_16x16x32_bf16 v[114:117], v[154:157], v[174:177], v[114:117]
	v_mfma_f32_16x16x32_bf16 v[102:105], v[146:149], v[186:189], v[102:105]
	v_mfma_f32_16x16x32_bf16 v[98:101], v[154:157], v[186:189], v[98:101]
	v_mfma_f32_16x16x32_bf16 v[86:89], v[146:149], v[196:199], v[86:89]
	v_mfma_f32_16x16x32_bf16 v[82:85], v[154:157], v[196:199], v[82:85]
	v_mfma_f32_16x16x32_bf16 v[70:73], v[146:149], v[206:209], v[70:73]
	v_mfma_f32_16x16x32_bf16 v[66:69], v[154:157], v[206:209], v[66:69]
	v_mfma_f32_16x16x32_bf16 v[118:121], v[150:153], v[178:181], v[118:121]
	v_mfma_f32_16x16x32_bf16 v[114:117], v[158:161], v[178:181], v[114:117]
	v_mfma_f32_16x16x32_bf16 v[102:105], v[150:153], v[190:193], v[102:105]
	v_mfma_f32_16x16x32_bf16 v[98:101], v[158:161], v[190:193], v[98:101]
	v_mfma_f32_16x16x32_bf16 v[86:89], v[150:153], v[200:203], v[86:89]
	v_mfma_f32_16x16x32_bf16 v[82:85], v[158:161], v[200:203], v[82:85]
	v_mfma_f32_16x16x32_bf16 v[70:73], v[150:153], v[210:213], v[70:73]
	v_mfma_f32_16x16x32_bf16 v[66:69], v[158:161], v[210:213], v[66:69]
	s_setprio 0
	s_barrier
; #define PG8_STAGE(bufoff, gbase, voff) do { _Pragma("unroll") for (int _i = 0; _i < 2; ++_i) \
;         __builtin_amdgcn_global_load_lds((const unsigned*)((const char*)(gbase) + (voff)[_i]), (PG8_LAS unsigned*)(lds + (bufoff) + ldsw + _i * 8192), 16, 0, 0); } while (0)
; #define PG8_LDA(dst, b, h) do { _Pragma("unroll") for (int m = 0; m < 4; ++m) _Pragma("unroll") for (int k = 0; k < 2; ++k) dst[m][k] = *(const PG8_LAS bf16x8*)(lds + PG8_SA(b, h) + aoff + m * 2048 + k * 1024); } while (0)
; #define PG8_MMA(ai, bj, At, Bt) do { __builtin_amdgcn_s_setprio(1); _Pragma("unroll") for (int m = 0; m < 4; ++m) _Pragma("unroll") for (int n = 0; n < 2; ++n) _Pragma("unroll") for (int k = 0; k < 2; ++k) \
;         acc[ai][bj][m][n] = __builtin_amdgcn_mfma_f32_16x16x32_bf16(Bt[n][k], At[m][k], acc[ai][bj][m][n], 0, 0, 0); __builtin_amdgcn_s_setprio(0); } while (0)
; #define PG8_WAIT_V(n) asm volatile("s_waitcnt vmcnt(" #n ")" ::: "memory")
; #define PG8_WAIT_L(n) asm volatile("s_waitcnt lgkmcnt(" #n ")" ::: "memory")
; #define PG8_BAR __builtin_amdgcn_s_barrier()
; #define PG8_SCHED __builtin_amdgcn_sched_barrier(0)
; template <class Epi, class Sched, bool ALIGN_EPI = false, bool SP2 = false>
; __device__ __forceinline__ void gemm_phase(PG8_LAS unsigned char* lds, const Gemm g, const Sched& S, const Epi& E) {
;     ...
;             PG8_LDA(At, 1, 1); PG8_STAGE(PG8_SB(1, 0), b3, voffB); PG8_STAGE(PG8_SB(1, 1), b3 + hstep, voffB); PG8_STAGE(PG8_SA(1, 0), a3, voffA);
;             PG8_WAIT_V(8); PG8_WAIT_L(0); PG8_BAR; PG8_MMA(1, 0, At, B0); PG8_MMA(1, 1, At, B1); PG8_BAR; PG8_SCHED;
	s_add_i32 s4, s7, s60
	v_lshl_add_u64 v[214:215], v[214:215], 0, s[20:21]
	s_mov_b32 m0, s4
	ds_read_b128 v[174:177], v184 offset:49152
	ds_read_b128 v[178:181], v184 offset:50176
	ds_read_b128 v[186:189], v184 offset:51200
	ds_read_b128 v[190:193], v184 offset:52224
	ds_read_b128 v[196:199], v184 offset:53248
	ds_read_b128 v[200:203], v184 offset:54272
	ds_read_b128 v[206:209], v184 offset:55296
	ds_read_b128 v[210:213], v184 offset:56320
	global_load_lds_dwordx4 v[214:215], off
	v_lshl_add_u64 v[214:215], v[216:217], 0, s[20:21]
	s_add_i32 m0, s4, 0x2000
	s_add_i32 s4, s12, s60
	global_load_lds_dwordx4 v[214:215], off
	v_lshl_add_u64 v[214:215], v[218:219], 0, s[20:21]
	s_mov_b32 m0, s4
	s_nop 0
	global_load_lds_dwordx4 v[214:215], off
	v_lshl_add_u64 v[214:215], v[234:235], 0, s[20:21]
	s_add_i32 m0, s4, 0x2000
	s_nop 0
	global_load_lds_dwordx4 v[214:215], off
	v_lshl_add_u64 v[214:215], v[236:237], 0, s[20:21]
	s_mov_b32 m0, s67
	s_nop 0
	global_load_lds_dwordx4 v[214:215], off
	v_lshl_add_u64 v[214:215], v[238:239], 0, s[20:21]
	s_mov_b32 m0, s68
	s_nop 0
	global_load_lds_dwordx4 v[214:215], off
	s_waitcnt vmcnt(8)
	s_waitcnt lgkmcnt(0)
	s_barrier
	s_setprio 1
	s_waitcnt lgkmcnt(0)
	v_mfma_f32_16x16x32_bf16 v[62:65], v[130:133], v[174:177], v[62:65]
	v_mfma_f32_16x16x32_bf16 v[58:61], v[138:141], v[174:177], v[58:61]
	v_mfma_f32_16x16x32_bf16 v[46:49], v[130:133], v[186:189], v[46:49]
	v_mfma_f32_16x16x32_bf16 v[42:45], v[138:141], v[186:189], v[42:45]
	v_mfma_f32_16x16x32_bf16 v[30:33], v[130:133], v[196:199], v[30:33]
	v_mfma_f32_16x16x32_bf16 v[26:29], v[138:141], v[196:199], v[26:29]
	v_mfma_f32_16x16x32_bf16 v[14:17], v[130:133], v[206:209], v[14:17]
	v_mfma_f32_16x16x32_bf16 v[10:13], v[138:141], v[206:209], v[10:13]
	v_mfma_f32_16x16x32_bf16 v[62:65], v[134:137], v[178:181], v[62:65]
	v_mfma_f32_16x16x32_bf16 v[58:61], v[142:145], v[178:181], v[58:61]
	v_mfma_f32_16x16x32_bf16 v[46:49], v[134:137], v[190:193], v[46:49]
	v_mfma_f32_16x16x32_bf16 v[42:45], v[142:145], v[190:193], v[42:45]
	v_mfma_f32_16x16x32_bf16 v[30:33], v[134:137], v[200:203], v[30:33]
	v_mfma_f32_16x16x32_bf16 v[26:29], v[142:145], v[200:203], v[26:29]
	v_mfma_f32_16x16x32_bf16 v[14:17], v[134:137], v[210:213], v[14:17]
	v_mfma_f32_16x16x32_bf16 v[10:13], v[142:145], v[210:213], v[10:13]
	s_setprio 0
	s_setprio 1
	v_mfma_f32_16x16x32_bf16 v[54:57], v[146:149], v[174:177], v[54:57]
	v_mfma_f32_16x16x32_bf16 v[50:53], v[154:157], v[174:177], v[50:53]
	v_mfma_f32_16x16x32_bf16 v[38:41], v[146:149], v[186:189], v[38:41]
	v_mfma_f32_16x16x32_bf16 v[34:37], v[154:157], v[186:189], v[34:37]
	v_mfma_f32_16x16x32_bf16 v[22:25], v[146:149], v[196:199], v[22:25]
	v_mfma_f32_16x16x32_bf16 v[18:21], v[154:157], v[196:199], v[18:21]
	v_mfma_f32_16x16x32_bf16 v[6:9], v[146:149], v[206:209], v[6:9]
	v_mfma_f32_16x16x32_bf16 v[2:5], v[154:157], v[206:209], v[2:5]
	v_mfma_f32_16x16x32_bf16 v[54:57], v[150:153], v[178:181], v[54:57]
	v_mfma_f32_16x16x32_bf16 v[50:53], v[158:161], v[178:181], v[50:53]
	v_mfma_f32_16x16x32_bf16 v[38:41], v[150:153], v[190:193], v[38:41]
	v_mfma_f32_16x16x32_bf16 v[34:37], v[158:161], v[190:193], v[34:37]
	v_mfma_f32_16x16x32_bf16 v[22:25], v[150:153], v[200:203], v[22:25]
	v_mfma_f32_16x16x32_bf16 v[18:21], v[158:161], v[200:203], v[18:21]
	v_mfma_f32_16x16x32_bf16 v[6:9], v[150:153], v[210:213], v[6:9]
	v_mfma_f32_16x16x32_bf16 v[2:5], v[158:161], v[210:213], v[2:5]
	s_setprio 0
	s_barrier
	s_add_u32 s10, s10, 0x100
	s_addc_u32 s11, s11, 0
	s_add_u32 s2, s2, 0x100
	s_addc_u32 s3, s3, 0
	s_cmp_ge_i32 s6, s69
	s_mov_b32 s4, s6
	s_cbranch_scc0 .LBB0_133

.LBB0_824:
	s_add_i32 s12, s13, 2
	s_min_i32 s4, s12, s10
	v_mad_u64_u32 v[34:35], s[4:5], s4, v231, v[98:99]
	global_load_dwordx4 v[90:93], v[34:35], off offset:768
	global_load_dwordx4 v[94:97], v[34:35], off offset:1536
	s_cmp_gt_i32 s13, s9
	s_cbranch_scc1 .LBB0_832
	ds_read_b128 v[34:37], v110
	ds_read_b128 v[38:41], v110 offset:32
	ds_read_b128 v[42:45], v110 offset:64
	ds_read_b128 v[46:49], v110 offset:96
	ds_read_b128 v[50:53], v110 offset:128
	ds_read_b128 v[54:57], v110 offset:160
	ds_read_b128 v[58:61], v110 offset:192
	ds_read_b128 v[62:65], v110 offset:224
	ds_read_b128 v[116:119], v113
	ds_read_b128 v[186:189], v113 offset:4608
	ds_read_b128 v[120:123], v113 offset:32
	ds_read_b128 v[190:193], v113 offset:4640
	ds_read_b128 v[124:127], v113 offset:64
	ds_read_b128 v[242:245], v113 offset:4672
	v_sub_f32_e32 v1, v105, v112
	s_waitcnt lgkmcnt(10)
	v_sub_f32_e32 v34, v1, v34
	v_sub_f32_e32 v35, v1, v35
	v_sub_f32_e32 v36, v1, v36
	v_sub_f32_e32 v37, v1, v37
	v_sub_f32_e32 v38, v1, v38
	v_sub_f32_e32 v39, v1, v39
	v_sub_f32_e32 v40, v1, v40
	v_sub_f32_e32 v41, v1, v41
	v_sub_f32_e32 v42, v1, v42
	v_sub_f32_e32 v43, v1, v43
	v_sub_f32_e32 v44, v1, v44
	v_sub_f32_e32 v45, v1, v45
	v_sub_f32_e32 v46, v1, v46
	v_sub_f32_e32 v47, v1, v47
	v_sub_f32_e32 v48, v1, v48
	v_sub_f32_e32 v49, v1, v49
	ds_read_b128 v[182:185], v113 offset:96
	ds_read_b128 v[246:249], v113 offset:4704
	s_waitcnt lgkmcnt(8)
	v_sub_f32_e32 v50, v1, v50
	v_sub_f32_e32 v51, v1, v51
	v_sub_f32_e32 v52, v1, v52
	v_sub_f32_e32 v53, v1, v53
	v_sub_f32_e32 v54, v1, v54
	v_sub_f32_e32 v55, v1, v55
	v_sub_f32_e32 v56, v1, v56
	v_sub_f32_e32 v57, v1, v57
	v_sub_f32_e32 v58, v1, v58
	v_sub_f32_e32 v59, v1, v59
	v_sub_f32_e32 v60, v1, v60
	v_sub_f32_e32 v61, v1, v61
	v_sub_f32_e32 v62, v1, v62
	v_sub_f32_e32 v63, v1, v63
	v_sub_f32_e32 v64, v1, v64
	v_sub_f32_e32 v65, v1, v65
	s_waitcnt vmcnt(4) lgkmcnt(6)
	v_mfma_f32_32x32x16_bf16 v[34:49], v[116:119], v[66:69], v[34:49]
	v_mfma_f32_32x32x16_bf16 v[50:65], v[186:189], v[66:69], v[50:65]
	s_waitcnt lgkmcnt(4)
	v_mfma_f32_32x32x16_bf16 v[34:49], v[120:123], v[70:73], v[34:49]
	v_mfma_f32_32x32x16_bf16 v[50:65], v[190:193], v[70:73], v[50:65]
	s_waitcnt lgkmcnt(2)
	v_mfma_f32_32x32x16_bf16 v[34:49], v[124:127], v[74:77], v[34:49]
	v_mfma_f32_32x32x16_bf16 v[50:65], v[242:245], v[74:77], v[50:65]
	s_waitcnt lgkmcnt(0)
	v_mfma_f32_32x32x16_bf16 v[34:49], v[182:185], v[78:81], v[34:49]
	v_mfma_f32_32x32x16_bf16 v[50:65], v[246:249], v[78:81], v[50:65]
	ds_read_b64_tr_b16 v[198:199], v108 offset:9216
	ds_read_b64_tr_b16 v[200:201], v108 offset:10368
	ds_read_b64_tr_b16 v[202:203], v108 offset:11520
	ds_read_b64_tr_b16 v[204:205], v108 offset:12672
	ds_read_b64_tr_b16 v[206:207], v108 offset:13824
	ds_read_b64_tr_b16 v[208:209], v108 offset:14976
	ds_read_b64_tr_b16 v[210:211], v108 offset:16128
	ds_read_b64_tr_b16 v[212:213], v108 offset:17280
	ds_read_b64_tr_b16 v[214:215], v108 offset:9280
	ds_read_b64_tr_b16 v[216:217], v108 offset:10432
	ds_read_b64_tr_b16 v[218:219], v108 offset:11584
	ds_read_b64_tr_b16 v[220:221], v108 offset:12736
	ds_read_b64_tr_b16 v[234:235], v108 offset:13888
	ds_read_b64_tr_b16 v[236:237], v108 offset:15040
	ds_read_b64_tr_b16 v[238:239], v108 offset:16192
	ds_read_b64_tr_b16 v[240:241], v108 offset:17344
	s_cmp_lg_u32 s9, s13
	s_cbranch_scc1 .LBB0_827
	v_add_u32_e32 v104, 0xffffffa5, v111
	v_add_u32_e32 v1, 0xffffff85, v111
	v_cmp_le_i32_e32 vcc, v104, v102
	s_nop 7
	v_cndmask_b32_e32 v50, v232, v50, vcc
	v_cmp_lt_i32_e32 vcc, v1, v102
	s_nop 1
	v_cndmask_b32_e32 v35, v232, v35, vcc
	v_cmp_le_i32_e32 vcc, v1, v102
	v_add_u32_e32 v1, 0xffffffa6, v111
	s_nop 0
	v_cndmask_b32_e32 v34, v232, v34, vcc
	v_cmp_le_i32_e32 vcc, v1, v102
	v_add_u32_e32 v1, 0xffffff87, v111
	s_nop 0
	v_cndmask_b32_e32 v51, v232, v51, vcc
	v_cmp_le_i32_e32 vcc, v1, v102
	v_add_u32_e32 v1, 0xffffffa7, v111
	s_nop 0
	v_cndmask_b32_e32 v36, v232, v36, vcc
	v_cmp_le_i32_e32 vcc, v1, v102
	v_add_u32_e32 v1, 0xffffff88, v111
	s_nop 0
	v_cndmask_b32_e32 v52, v232, v52, vcc
	v_cmp_le_i32_e32 vcc, v1, v102
	v_add_u32_e32 v1, 0xffffffa8, v111
	s_nop 0
	v_cndmask_b32_e32 v37, v232, v37, vcc
	v_cmp_le_i32_e32 vcc, v1, v102
	v_add_u32_e32 v1, 0xffffff8d, v111
	s_nop 0
	v_cndmask_b32_e32 v53, v232, v53, vcc
	v_cmp_le_i32_e32 vcc, v1, v102
	v_add_u32_e32 v1, 0xffffffad, v111
	s_nop 0
	v_cndmask_b32_e32 v38, v232, v38, vcc
	v_cmp_le_i32_e32 vcc, v1, v102
	v_add_u32_e32 v1, 0xffffff8e, v111
	s_nop 0
	v_cndmask_b32_e32 v54, v232, v54, vcc
	v_cmp_le_i32_e32 vcc, v1, v102
	v_add_u32_e32 v1, 0xffffffae, v111
	s_nop 0
	v_cndmask_b32_e32 v39, v232, v39, vcc
	v_cmp_le_i32_e32 vcc, v1, v102
	v_add_u32_e32 v1, 0xffffff8f, v111
	s_nop 0
	v_cndmask_b32_e32 v55, v232, v55, vcc
	v_cmp_le_i32_e32 vcc, v1, v102
	v_add_u32_e32 v1, 0xffffffaf, v111
	s_nop 0
	v_cndmask_b32_e32 v40, v232, v40, vcc
	v_cmp_le_i32_e32 vcc, v1, v102
	v_add_u32_e32 v1, 0xffffff90, v111
	s_nop 0
	v_cndmask_b32_e32 v56, v232, v56, vcc
	v_cmp_le_i32_e32 vcc, v1, v102
	v_add_u32_e32 v1, 0xffffffb0, v111
	s_nop 0
	v_cndmask_b32_e32 v41, v232, v41, vcc
	v_cmp_le_i32_e32 vcc, v1, v102
	v_add_u32_e32 v1, 0xffffff95, v111
	s_nop 0
	v_cndmask_b32_e32 v57, v232, v57, vcc
	v_cmp_le_i32_e32 vcc, v1, v102
	v_add_u32_e32 v1, 0xffffffb5, v111
	s_nop 0
	v_cndmask_b32_e32 v42, v232, v42, vcc
	v_cmp_le_i32_e32 vcc, v1, v102
	v_add_u32_e32 v1, 0xffffff96, v111
	s_nop 0
	v_cndmask_b32_e32 v58, v232, v58, vcc
	v_cmp_le_i32_e32 vcc, v1, v102
	v_add_u32_e32 v1, 0xffffffb6, v111
	s_nop 0
	v_cndmask_b32_e32 v43, v232, v43, vcc
	v_cmp_le_i32_e32 vcc, v1, v102
	v_add_u32_e32 v1, 0xffffff97, v111
	s_nop 0
	v_cndmask_b32_e32 v59, v232, v59, vcc
	v_cmp_le_i32_e32 vcc, v1, v102
	v_add_u32_e32 v1, 0xffffffb7, v111
	s_nop 0
	v_cndmask_b32_e32 v44, v232, v44, vcc
	v_cmp_le_i32_e32 vcc, v1, v102
	v_add_u32_e32 v1, 0xffffff98, v111
	s_nop 0
	v_cndmask_b32_e32 v60, v232, v60, vcc
	v_cmp_le_i32_e32 vcc, v1, v102
	v_add_u32_e32 v1, 0xffffffb8, v111
	s_nop 0
	v_cndmask_b32_e32 v45, v232, v45, vcc
	v_cmp_le_i32_e32 vcc, v1, v102
	v_add_u32_e32 v1, 0xffffff9d, v111
	s_nop 0
	v_cndmask_b32_e32 v61, v232, v61, vcc
	v_cmp_le_i32_e32 vcc, v1, v102
	v_add_u32_e32 v1, 0xffffffbd, v111
	s_nop 0
	v_cndmask_b32_e32 v46, v232, v46, vcc
	v_cmp_le_i32_e32 vcc, v1, v102
	v_add_u32_e32 v1, 0xffffff9e, v111
	s_nop 0
	v_cndmask_b32_e32 v62, v232, v62, vcc
	v_cmp_le_i32_e32 vcc, v1, v102
	v_add_u32_e32 v1, 0xffffffbe, v111
	s_nop 0
	v_cndmask_b32_e32 v47, v232, v47, vcc
	v_cmp_le_i32_e32 vcc, v1, v102
	v_add_u32_e32 v1, 0xffffff9f, v111
	s_nop 0
	v_cndmask_b32_e32 v63, v232, v63, vcc
	v_cmp_le_i32_e32 vcc, v1, v102
	v_add_u32_e32 v1, 0xffffffbf, v111
	s_nop 0
	v_cndmask_b32_e32 v48, v232, v48, vcc
	v_cmp_le_i32_e32 vcc, v1, v102
	v_add_u32_e32 v1, 0xffffffa0, v111
	s_nop 0
	v_cndmask_b32_e32 v64, v232, v64, vcc
	v_cmp_le_i32_e32 vcc, v1, v102
	v_subrev_u32_e32 v1, 64, v111
	s_nop 0
	v_cndmask_b32_e32 v49, v232, v49, vcc
	v_cmp_le_i32_e32 vcc, v1, v102
	s_nop 1
	v_cndmask_b32_e32 v65, v232, v65, vcc
.LBB0_827:
	v_max3_f32 v104, v34, v35, v36
	v_max3_f32 v106, v37, v38, v39
	v_max3_f32 v115, v40, v41, v42
	v_max3_f32 v1, v43, v44, v45
	v_max3_f32 v104, v104, v46, v47
	v_max3_f32 v106, v106, v48, v49
	v_max3_f32 v115, v115, v50, v51
	v_max3_f32 v1, v1, v52, v53
	v_max3_f32 v104, v104, v54, v55
	v_max3_f32 v106, v106, v56, v57
	v_max3_f32 v115, v115, v58, v59
	v_max3_f32 v1, v1, v60, v61
	v_max3_f32 v104, v104, v62, v63
	v_max3_f32 v106, v106, v64, v65
	v_max3_f32 v1, v1, v115, s82
	v_max3_f32 v1, v1, v104, v106
	ds_bpermute_b32 v104, v109, v1
	s_xor_b64 s[0:1], s[0:1], -1
	s_waitcnt lgkmcnt(0)
	v_max_f32_e32 v104, v104, v104
	v_max_f32_e32 v1, v1, v104
	s_and_saveexec_b64 s[4:5], s[0:1]
	s_xor_b64 s[0:1], exec, s[4:5]
	s_cbranch_execnz .LBB0_842
	s_or_saveexec_b64 s[4:5], s[0:1]
	s_mov_b64 s[0:1], 0
	s_xor_b64 exec, exec, s[4:5]
	s_cbranch_execnz .LBB0_845

.LBB0_831:
	v_exp_f32_e32 v34, v34
	v_exp_f32_e32 v35, v35
	v_exp_f32_e32 v36, v36
	v_exp_f32_e32 v37, v37
	v_exp_f32_e32 v38, v38
	v_exp_f32_e32 v39, v39
	v_exp_f32_e32 v40, v40
	v_exp_f32_e32 v41, v41
	v_add_f32_e32 v104, v34, v35
	v_add_f32_e32 v106, v36, v37
	v_add_f32_e32 v104, v104, v38
	v_add_f32_e32 v106, v106, v39
	v_add_f32_e32 v104, v104, v40
	v_add_f32_e32 v106, v106, v41
	v_cvt_pk_bf16_f32 v132, v34, v35
	v_cvt_pk_bf16_f32 v133, v36, v37
	v_cvt_pk_bf16_f32 v134, v38, v39
	v_cvt_pk_bf16_f32 v135, v40, v41
	v_exp_f32_e32 v42, v42
	v_exp_f32_e32 v43, v43
	v_mfma_f32_32x32x16_bf16 v[18:33], v[198:201], v[132:135], v[18:33]
	v_mfma_f32_32x32x16_bf16 v[2:17], v[214:217], v[132:135], v[2:17]
	v_exp_f32_e32 v44, v44
	v_exp_f32_e32 v45, v45
	v_exp_f32_e32 v46, v46
	v_exp_f32_e32 v47, v47
	v_exp_f32_e32 v48, v48
	v_exp_f32_e32 v49, v49
	v_add_f32_e32 v104, v104, v42
	v_add_f32_e32 v106, v106, v43
	v_add_f32_e32 v104, v104, v44
	v_add_f32_e32 v106, v106, v45
	v_add_f32_e32 v104, v104, v46
	v_add_f32_e32 v106, v106, v47
	v_add_f32_e32 v104, v104, v48
	v_add_f32_e32 v106, v106, v49
	v_cvt_pk_bf16_f32 v148, v42, v43
	v_cvt_pk_bf16_f32 v149, v44, v45
	v_cvt_pk_bf16_f32 v150, v46, v47
	v_cvt_pk_bf16_f32 v151, v48, v49
	v_exp_f32_e32 v50, v50
	v_exp_f32_e32 v51, v51
	v_mfma_f32_32x32x16_bf16 v[18:33], v[202:205], v[148:151], v[18:33]
	v_mfma_f32_32x32x16_bf16 v[2:17], v[218:221], v[148:151], v[2:17]
	v_exp_f32_e32 v52, v52
	v_exp_f32_e32 v53, v53
	v_exp_f32_e32 v54, v54
	v_exp_f32_e32 v55, v55
	v_exp_f32_e32 v56, v56
	v_exp_f32_e32 v57, v57
	v_add_f32_e32 v104, v104, v50
	v_add_f32_e32 v106, v106, v51
	v_add_f32_e32 v104, v104, v52
	v_add_f32_e32 v106, v106, v53
	v_add_f32_e32 v104, v104, v54
	v_add_f32_e32 v106, v106, v55
	v_add_f32_e32 v104, v104, v56
	v_add_f32_e32 v106, v106, v57
	v_cvt_pk_bf16_f32 v156, v50, v51
	v_cvt_pk_bf16_f32 v157, v52, v53
	v_cvt_pk_bf16_f32 v158, v54, v55
	v_cvt_pk_bf16_f32 v159, v56, v57
	v_exp_f32_e32 v58, v58
	v_exp_f32_e32 v59, v59
	v_mfma_f32_32x32x16_bf16 v[18:33], v[206:209], v[156:159], v[18:33]
	v_mfma_f32_32x32x16_bf16 v[2:17], v[234:237], v[156:159], v[2:17]
	v_exp_f32_e32 v60, v60
	v_exp_f32_e32 v61, v61
	v_exp_f32_e32 v62, v62
	v_exp_f32_e32 v63, v63
	v_exp_f32_e32 v64, v64
	v_exp_f32_e32 v65, v65
	v_add_f32_e32 v104, v104, v58
	v_add_f32_e32 v106, v106, v59
	v_add_f32_e32 v104, v104, v60
	v_add_f32_e32 v106, v106, v61
	v_add_f32_e32 v104, v104, v62
	v_add_f32_e32 v106, v106, v63
	v_add_f32_e32 v104, v104, v64
	v_add_f32_e32 v106, v106, v65
	v_cvt_pk_bf16_f32 v172, v58, v59
	v_cvt_pk_bf16_f32 v173, v60, v61
	v_cvt_pk_bf16_f32 v174, v62, v63
	v_cvt_pk_bf16_f32 v175, v64, v65
	v_add_f32_e32 v104, v104, v106
	v_add_f32_e32 v114, v114, v104
	v_mfma_f32_32x32x16_bf16 v[18:33], v[210:213], v[172:175], v[18:33]
	v_mfma_f32_32x32x16_bf16 v[2:17], v[238:241], v[172:175], v[2:17]
; #define LAS __attribute__((address_space(3)))
; #define STAGE_TILE(bufi, KR, VR) do { LAS bf16_t* Ks_ = (LAS bf16_t*)(lds + (bufi) * 18432); LAS bf16_t* Vs_ = (LAS bf16_t*)(lds + (bufi) * 18432 + 9216); \
;         *(LAS u32x4*)(Ks_ + skr * 72 + sch * 8) = KR; *(LAS u32x4*)(Vs_ + skr * 72 + sch * 8) = VR; } while (0)
; #define LOAD_TILE(KR, VR, tl) do { KR = *(const GAS u32x4*)(kg + (size_t)(tl) * 64 * LDH); VR = *(const GAS u32x4*)(vg + (size_t)(tl) * 64 * LDH); } while (0)
; template <int MODE> ...
;     ...
;         STAGE_TILE(1, kB, vB);
;         __syncthreads();
;         if (MODE == 1) { const u32x4 fa = *(const LAS u32x4*)flags, fb = *(const LAS u32x4*)(flags + 4); if ((fa.x & fa.y & fa.z & fa.w & fb.x & fb.y & fb.z & fb.w) != 0u) break; }
;         LOAD_TILE(kB, vB, TILE_OF(min(it + 3, ntiles - 1)));
;         COMPUTE_TILE(TILE_OF(it + 1), 1);
.LBB0_832:
	s_add_i32 s4, s13, 3
	s_min_i32 s4, s4, s10
	v_mad_u64_u32 v[34:35], s[4:5], s4, v231, v[98:99]
	s_waitcnt vmcnt(3)
	ds_write_b128 v107, v[82:85] offset:18432
	s_waitcnt vmcnt(2)
	ds_write_b128 v107, v[86:89] offset:27648
	s_waitcnt lgkmcnt(0)
	s_barrier
	global_load_dwordx4 v[82:85], v[34:35], off offset:768
	global_load_dwordx4 v[86:89], v[34:35], off offset:1536
	s_cmp_ge_i32 s13, s9
	s_cbranch_scc1 .LBB0_840
	ds_read_b128 v[34:37], v110 offset:256
	ds_read_b128 v[38:41], v110 offset:288
	ds_read_b128 v[42:45], v110 offset:320
	ds_read_b128 v[46:49], v110 offset:352
	ds_read_b128 v[50:53], v110 offset:384
	ds_read_b128 v[54:57], v110 offset:416
	ds_read_b128 v[58:61], v110 offset:448
	ds_read_b128 v[62:65], v110 offset:480
	ds_read_b128 v[116:119], v113 offset:18432
	ds_read_b128 v[186:189], v113 offset:23040
	ds_read_b128 v[120:123], v113 offset:18464
	ds_read_b128 v[190:193], v113 offset:23072
	ds_read_b128 v[124:127], v113 offset:18496
	ds_read_b128 v[242:245], v113 offset:23104
	v_sub_f32_e32 v1, v105, v112
	s_waitcnt lgkmcnt(10)
	v_sub_f32_e32 v34, v1, v34
	v_sub_f32_e32 v35, v1, v35
	v_sub_f32_e32 v36, v1, v36
	v_sub_f32_e32 v37, v1, v37
	v_sub_f32_e32 v38, v1, v38
	v_sub_f32_e32 v39, v1, v39
	v_sub_f32_e32 v40, v1, v40
	v_sub_f32_e32 v41, v1, v41
	v_sub_f32_e32 v42, v1, v42
	v_sub_f32_e32 v43, v1, v43
	v_sub_f32_e32 v44, v1, v44
	v_sub_f32_e32 v45, v1, v45
	v_sub_f32_e32 v46, v1, v46
	v_sub_f32_e32 v47, v1, v47
	v_sub_f32_e32 v48, v1, v48
	v_sub_f32_e32 v49, v1, v49
	ds_read_b128 v[182:185], v113 offset:18528
	ds_read_b128 v[246:249], v113 offset:23136
	s_waitcnt lgkmcnt(8)
	v_sub_f32_e32 v50, v1, v50
	v_sub_f32_e32 v51, v1, v51
	v_sub_f32_e32 v52, v1, v52
	v_sub_f32_e32 v53, v1, v53
	v_sub_f32_e32 v54, v1, v54
	v_sub_f32_e32 v55, v1, v55
	v_sub_f32_e32 v56, v1, v56
	v_sub_f32_e32 v57, v1, v57
	v_sub_f32_e32 v58, v1, v58
	v_sub_f32_e32 v59, v1, v59
	v_sub_f32_e32 v60, v1, v60
	v_sub_f32_e32 v61, v1, v61
	v_sub_f32_e32 v62, v1, v62
	v_sub_f32_e32 v63, v1, v63
	v_sub_f32_e32 v64, v1, v64
	v_sub_f32_e32 v65, v1, v65
	s_waitcnt lgkmcnt(6)
	v_mfma_f32_32x32x16_bf16 v[34:49], v[116:119], v[66:69], v[34:49]
	v_mfma_f32_32x32x16_bf16 v[50:65], v[186:189], v[66:69], v[50:65]
	s_waitcnt lgkmcnt(4)
	v_mfma_f32_32x32x16_bf16 v[34:49], v[120:123], v[70:73], v[34:49]
	v_mfma_f32_32x32x16_bf16 v[50:65], v[190:193], v[70:73], v[50:65]
	s_waitcnt lgkmcnt(2)
	v_mfma_f32_32x32x16_bf16 v[34:49], v[124:127], v[74:77], v[34:49]
	v_mfma_f32_32x32x16_bf16 v[50:65], v[242:245], v[74:77], v[50:65]
	s_waitcnt lgkmcnt(0)
	v_mfma_f32_32x32x16_bf16 v[34:49], v[182:185], v[78:81], v[34:49]
	v_mfma_f32_32x32x16_bf16 v[50:65], v[246:249], v[78:81], v[50:65]
	ds_read_b64_tr_b16 v[198:199], v108 offset:27648
	ds_read_b64_tr_b16 v[200:201], v108 offset:28800
	ds_read_b64_tr_b16 v[202:203], v108 offset:29952
	ds_read_b64_tr_b16 v[204:205], v108 offset:31104
	ds_read_b64_tr_b16 v[206:207], v108 offset:32256
	ds_read_b64_tr_b16 v[208:209], v108 offset:33408
	ds_read_b64_tr_b16 v[210:211], v108 offset:34560
	ds_read_b64_tr_b16 v[212:213], v108 offset:35712
	ds_read_b64_tr_b16 v[214:215], v108 offset:27712
	ds_read_b64_tr_b16 v[216:217], v108 offset:28864
	ds_read_b64_tr_b16 v[218:219], v108 offset:30016
	ds_read_b64_tr_b16 v[220:221], v108 offset:31168
	ds_read_b64_tr_b16 v[234:235], v108 offset:32320
	ds_read_b64_tr_b16 v[236:237], v108 offset:33472
	ds_read_b64_tr_b16 v[238:239], v108 offset:34624
	ds_read_b64_tr_b16 v[240:241], v108 offset:35776
	s_cmp_lg_u32 s11, s13
	s_cbranch_scc1 .LBB0_835
	v_subrev_u32_e32 v104, 27, v111
	v_subrev_u32_e32 v1, 59, v111
	v_cmp_le_i32_e32 vcc, v104, v102
	s_nop 7
	v_cndmask_b32_e32 v50, v232, v50, vcc
	v_cmp_lt_i32_e32 vcc, v1, v102
	s_nop 1
	v_cndmask_b32_e32 v35, v232, v35, vcc
	v_cmp_le_i32_e32 vcc, v1, v102
	v_subrev_u32_e32 v1, 26, v111
	s_nop 0
	v_cndmask_b32_e32 v34, v232, v34, vcc
	v_cmp_le_i32_e32 vcc, v1, v102
	v_subrev_u32_e32 v1, 57, v111
	s_nop 0
	v_cndmask_b32_e32 v51, v232, v51, vcc
	v_cmp_le_i32_e32 vcc, v1, v102
	v_subrev_u32_e32 v1, 25, v111
	s_nop 0
	v_cndmask_b32_e32 v36, v232, v36, vcc
	v_cmp_le_i32_e32 vcc, v1, v102
	v_subrev_u32_e32 v1, 56, v111
	s_nop 0
	v_cndmask_b32_e32 v52, v232, v52, vcc
	v_cmp_le_i32_e32 vcc, v1, v102
	v_subrev_u32_e32 v1, 24, v111
	s_nop 0
	v_cndmask_b32_e32 v37, v232, v37, vcc
	v_cmp_le_i32_e32 vcc, v1, v102
	v_subrev_u32_e32 v1, 51, v111
	s_nop 0
	v_cndmask_b32_e32 v53, v232, v53, vcc
	v_cmp_le_i32_e32 vcc, v1, v102
	v_subrev_u32_e32 v1, 19, v111
	s_nop 0
	v_cndmask_b32_e32 v38, v232, v38, vcc
	v_cmp_le_i32_e32 vcc, v1, v102
	v_subrev_u32_e32 v1, 50, v111
	s_nop 0
	v_cndmask_b32_e32 v54, v232, v54, vcc
	v_cmp_le_i32_e32 vcc, v1, v102
	v_subrev_u32_e32 v1, 18, v111
	s_nop 0
	v_cndmask_b32_e32 v39, v232, v39, vcc
	v_cmp_le_i32_e32 vcc, v1, v102
	v_subrev_u32_e32 v1, 49, v111
	s_nop 0
	v_cndmask_b32_e32 v55, v232, v55, vcc
	v_cmp_le_i32_e32 vcc, v1, v102
	v_subrev_u32_e32 v1, 17, v111
	s_nop 0
	v_cndmask_b32_e32 v40, v232, v40, vcc
	v_cmp_le_i32_e32 vcc, v1, v102
	v_subrev_u32_e32 v1, 48, v111
	s_nop 0
	v_cndmask_b32_e32 v56, v232, v56, vcc
	v_cmp_le_i32_e32 vcc, v1, v102
	v_add_u32_e32 v1, -16, v111
	s_nop 0
	v_cndmask_b32_e32 v41, v232, v41, vcc
	v_cmp_le_i32_e32 vcc, v1, v102
	v_subrev_u32_e32 v1, 43, v111
	s_nop 0
	v_cndmask_b32_e32 v57, v232, v57, vcc
	v_cmp_le_i32_e32 vcc, v1, v102
	v_add_u32_e32 v1, -11, v111
	s_nop 0
	v_cndmask_b32_e32 v42, v232, v42, vcc
	v_cmp_le_i32_e32 vcc, v1, v102
	v_subrev_u32_e32 v1, 42, v111
	s_nop 0
	v_cndmask_b32_e32 v58, v232, v58, vcc
	v_cmp_le_i32_e32 vcc, v1, v102
	v_add_u32_e32 v1, -10, v111
	s_nop 0
	v_cndmask_b32_e32 v43, v232, v43, vcc
	v_cmp_le_i32_e32 vcc, v1, v102
	v_subrev_u32_e32 v1, 41, v111
	s_nop 0
	v_cndmask_b32_e32 v59, v232, v59, vcc
	v_cmp_le_i32_e32 vcc, v1, v102
	v_add_u32_e32 v1, -9, v111
	s_nop 0
	v_cndmask_b32_e32 v44, v232, v44, vcc
	v_cmp_le_i32_e32 vcc, v1, v102
	v_subrev_u32_e32 v1, 40, v111
	s_nop 0
	v_cndmask_b32_e32 v60, v232, v60, vcc
	v_cmp_le_i32_e32 vcc, v1, v102
	v_add_u32_e32 v1, -8, v111
	s_nop 0
	v_cndmask_b32_e32 v45, v232, v45, vcc
	v_cmp_le_i32_e32 vcc, v1, v102
	v_subrev_u32_e32 v1, 35, v111
	s_nop 0
	v_cndmask_b32_e32 v61, v232, v61, vcc
	v_cmp_le_i32_e32 vcc, v1, v102
	v_add_u32_e32 v1, -3, v111
	s_nop 0
	v_cndmask_b32_e32 v46, v232, v46, vcc
	v_cmp_le_i32_e32 vcc, v1, v102
	v_subrev_u32_e32 v1, 34, v111
	s_nop 0
	v_cndmask_b32_e32 v62, v232, v62, vcc
	v_cmp_le_i32_e32 vcc, v1, v102
	v_add_u32_e32 v1, -2, v111
	s_nop 0
	v_cndmask_b32_e32 v47, v232, v47, vcc
	v_cmp_le_i32_e32 vcc, v1, v102
	v_subrev_u32_e32 v1, 33, v111
	s_nop 0
	v_cndmask_b32_e32 v63, v232, v63, vcc
	v_cmp_le_i32_e32 vcc, v1, v102
	v_add_u32_e32 v1, -1, v111
	s_nop 0
	v_cndmask_b32_e32 v48, v232, v48, vcc
	v_cmp_le_i32_e32 vcc, v1, v102
	v_subrev_u32_e32 v1, 32, v111
	s_nop 0
	v_cndmask_b32_e32 v64, v232, v64, vcc
	v_cmp_le_i32_e32 vcc, v1, v102
	s_nop 1
	v_cndmask_b32_e32 v49, v232, v49, vcc
	v_cmp_le_i32_e32 vcc, v111, v102
	s_nop 1
	v_cndmask_b32_e32 v65, v232, v65, vcc

.LBB0_920:
	s_add_i32 s19, s23, 2
	s_min_i32 s14, s19, s18
	v_mad_u64_u32 v[34:35], s[12:13], s14, v231, v[102:103]
	v_mad_u64_u32 v[36:37], s[12:13], s14, v231, v[104:105]
	global_load_dwordx4 v[90:93], v[34:35], off
	global_load_dwordx4 v[94:97], v[36:37], off
	s_cmp_gt_i32 s23, s17
	s_cbranch_scc1 .LBB0_926
	ds_read_b64 v[34:35], v109
	ds_read_b128 v[118:121], v113
	ds_read_b128 v[182:185], v113 offset:4608
	ds_read_b128 v[122:125], v113 offset:32
	ds_read_b128 v[186:189], v113 offset:4640
	ds_read_b128 v[126:129], v113 offset:64
	ds_read_b128 v[190:193], v113 offset:4672
	ds_read_b128 v[130:133], v113 offset:96
	ds_read_b128 v[242:245], v113 offset:4704
	v_sub_f32_e32 v1, 0, v112
	s_xor_b64 s[10:11], s[10:11], -1
	s_waitcnt lgkmcnt(8)
	v_lshrrev_b64 v[114:115], v100, v[34:35]
	v_lshrrev_b64 v[116:117], v106, v[34:35]
	v_bfe_i32 v34, v114, 0, 1
	v_bfe_i32 v50, v116, 0, 1
	v_bfe_i32 v35, v114, 1, 1
	v_bfe_i32 v51, v116, 1, 1
	v_bfe_i32 v36, v114, 2, 1
	v_bfe_i32 v52, v116, 2, 1
	v_bfe_i32 v37, v114, 3, 1
	v_bfe_i32 v53, v116, 3, 1
	v_bfe_i32 v38, v114, 8, 1
	v_bfe_i32 v54, v116, 8, 1
	v_bfe_i32 v39, v114, 9, 1
	v_bfe_i32 v55, v116, 9, 1
	v_bfe_i32 v40, v114, 10, 1
	v_bfe_i32 v56, v116, 10, 1
	v_bfe_i32 v41, v114, 11, 1
	v_bfe_i32 v57, v116, 11, 1
	v_bfe_i32 v42, v114, 16, 1
	v_bfe_i32 v58, v116, 16, 1
	v_bfe_i32 v43, v114, 17, 1
	v_bfe_i32 v59, v116, 17, 1
	v_bfe_i32 v44, v114, 18, 1
	v_bfe_i32 v60, v116, 18, 1
	v_bfe_i32 v45, v114, 19, 1
	v_bfe_i32 v61, v116, 19, 1
	v_bfe_i32 v46, v114, 24, 1
	v_bfe_i32 v62, v116, 24, 1
	v_bfe_i32 v47, v114, 25, 1
	v_bfe_i32 v63, v116, 25, 1
	v_bfe_i32 v48, v114, 26, 1
	v_bfe_i32 v64, v116, 26, 1
	v_bfe_i32 v49, v114, 27, 1
	v_bfe_i32 v65, v116, 27, 1
	v_bfi_b32 v34, v34, v1, v232
	v_bfi_b32 v35, v35, v1, v232
	v_bfi_b32 v36, v36, v1, v232
	v_bfi_b32 v37, v37, v1, v232
	v_bfi_b32 v38, v38, v1, v232
	v_bfi_b32 v39, v39, v1, v232
	v_bfi_b32 v40, v40, v1, v232
	v_bfi_b32 v41, v41, v1, v232
	v_bfi_b32 v42, v42, v1, v232
	v_bfi_b32 v43, v43, v1, v232
	v_bfi_b32 v44, v44, v1, v232
	v_bfi_b32 v45, v45, v1, v232
	v_bfi_b32 v46, v46, v1, v232
	v_bfi_b32 v47, v47, v1, v232
	v_bfi_b32 v48, v48, v1, v232
	v_bfi_b32 v49, v49, v1, v232
	v_bfi_b32 v50, v50, v1, v232
	v_bfi_b32 v51, v51, v1, v232
	v_bfi_b32 v52, v52, v1, v232
	v_bfi_b32 v53, v53, v1, v232
	v_bfi_b32 v54, v54, v1, v232
	v_bfi_b32 v55, v55, v1, v232
	v_bfi_b32 v56, v56, v1, v232
	v_bfi_b32 v57, v57, v1, v232
	v_bfi_b32 v58, v58, v1, v232
	v_bfi_b32 v59, v59, v1, v232
	v_bfi_b32 v60, v60, v1, v232
	v_bfi_b32 v61, v61, v1, v232
	v_bfi_b32 v62, v62, v1, v232
	v_bfi_b32 v63, v63, v1, v232
	v_bfi_b32 v64, v64, v1, v232
	v_bfi_b32 v65, v65, v1, v232
	s_waitcnt vmcnt(4) lgkmcnt(6)
	v_mfma_f32_32x32x16_bf16 v[34:49], v[118:121], v[74:77], v[34:49]
	v_mfma_f32_32x32x16_bf16 v[50:65], v[182:185], v[74:77], v[50:65]
	s_waitcnt lgkmcnt(4)
	v_mfma_f32_32x32x16_bf16 v[34:49], v[122:125], v[66:69], v[34:49]
	v_mfma_f32_32x32x16_bf16 v[50:65], v[186:189], v[66:69], v[50:65]
	s_waitcnt lgkmcnt(2)
	v_mfma_f32_32x32x16_bf16 v[34:49], v[126:129], v[70:73], v[34:49]
	v_mfma_f32_32x32x16_bf16 v[50:65], v[190:193], v[70:73], v[50:65]
	s_waitcnt lgkmcnt(0)
	v_mfma_f32_32x32x16_bf16 v[34:49], v[130:133], v[78:81], v[34:49]
	v_mfma_f32_32x32x16_bf16 v[50:65], v[242:245], v[78:81], v[50:65]
	ds_read_b64_tr_b16 v[198:199], v107 offset:9216
	ds_read_b64_tr_b16 v[200:201], v107 offset:10368
	ds_read_b64_tr_b16 v[202:203], v107 offset:11520
	ds_read_b64_tr_b16 v[204:205], v107 offset:12672
	ds_read_b64_tr_b16 v[206:207], v107 offset:13824
	ds_read_b64_tr_b16 v[208:209], v107 offset:14976
	ds_read_b64_tr_b16 v[210:211], v107 offset:16128
	ds_read_b64_tr_b16 v[212:213], v107 offset:17280
	ds_read_b64_tr_b16 v[214:215], v107 offset:9280
	ds_read_b64_tr_b16 v[216:217], v107 offset:10432
	ds_read_b64_tr_b16 v[218:219], v107 offset:11584
	ds_read_b64_tr_b16 v[220:221], v107 offset:12736
	ds_read_b64_tr_b16 v[234:235], v107 offset:13888
	ds_read_b64_tr_b16 v[236:237], v107 offset:15040
	ds_read_b64_tr_b16 v[238:239], v107 offset:16192
	ds_read_b64_tr_b16 v[240:241], v107 offset:17344
	v_max3_f32 v108, v34, v35, v36
	v_max3_f32 v110, v37, v38, v39
	v_max3_f32 v114, v40, v41, v42
	v_max3_f32 v1, v43, v44, v45
	v_max3_f32 v108, v108, v46, v47
	v_max3_f32 v110, v110, v48, v49
	v_max3_f32 v114, v114, v50, v51
	v_max3_f32 v1, v1, v52, v53
	v_max3_f32 v108, v108, v54, v55
	v_max3_f32 v110, v110, v56, v57
	v_max3_f32 v114, v114, v58, v59
	v_max3_f32 v1, v1, v60, v61
	v_max3_f32 v108, v108, v62, v63
	v_max3_f32 v110, v110, v64, v65
	v_max3_f32 v1, v1, v114, s82
	v_max3_f32 v1, v1, v108, v110
	v_and_b32_e32 v110, 64, v224
	v_xor_b32_e32 v108, 32, v224
	v_add_u32_e32 v110, 64, v110
	v_cmp_lt_i32_e32 vcc, v108, v110
	s_nop 1
	v_cndmask_b32_e32 v108, v224, v108, vcc
	v_lshlrev_b32_e32 v108, 2, v108
	ds_bpermute_b32 v108, v108, v1
	s_waitcnt lgkmcnt(0)
	v_max_f32_e32 v108, v108, v108
	v_max_f32_e32 v1, v1, v108
	s_and_saveexec_b64 s[12:13], s[10:11]
	s_xor_b64 s[10:11], exec, s[12:13]
	s_cbranch_execnz .LBB0_934
	s_or_saveexec_b64 s[12:13], s[10:11]
	s_mov_b64 s[10:11], 0
	s_xor_b64 exec, exec, s[12:13]
	s_cbranch_execnz .LBB0_937

.LBB0_925:
	v_exp_f32_e32 v34, v34
	v_exp_f32_e32 v35, v35
	v_exp_f32_e32 v36, v36
	v_exp_f32_e32 v37, v37
	v_exp_f32_e32 v38, v38
	v_exp_f32_e32 v39, v39
	v_exp_f32_e32 v40, v40
	v_exp_f32_e32 v41, v41
	v_add_f32_e32 v108, v34, v35
	v_add_f32_e32 v110, v36, v37
	v_add_f32_e32 v108, v108, v38
	v_add_f32_e32 v110, v110, v39
	v_add_f32_e32 v108, v108, v40
	v_add_f32_e32 v110, v110, v41
	v_cvt_pk_bf16_f32 v148, v34, v35
	v_cvt_pk_bf16_f32 v149, v36, v37
	v_cvt_pk_bf16_f32 v150, v38, v39
	v_cvt_pk_bf16_f32 v151, v40, v41
	v_exp_f32_e32 v42, v42
	v_exp_f32_e32 v43, v43
	v_mfma_f32_32x32x16_bf16 v[18:33], v[198:201], v[148:151], v[18:33]
	v_mfma_f32_32x32x16_bf16 v[2:17], v[214:217], v[148:151], v[2:17]
	v_exp_f32_e32 v44, v44
	v_exp_f32_e32 v45, v45
	v_exp_f32_e32 v46, v46
	v_exp_f32_e32 v47, v47
	v_exp_f32_e32 v48, v48
	v_exp_f32_e32 v49, v49
	v_add_f32_e32 v108, v108, v42
	v_add_f32_e32 v110, v110, v43
	v_add_f32_e32 v108, v108, v44
	v_add_f32_e32 v110, v110, v45
	v_add_f32_e32 v108, v108, v46
	v_add_f32_e32 v110, v110, v47
	v_add_f32_e32 v108, v108, v48
	v_add_f32_e32 v110, v110, v49
	v_cvt_pk_bf16_f32 v156, v42, v43
	v_cvt_pk_bf16_f32 v157, v44, v45
	v_cvt_pk_bf16_f32 v158, v46, v47
	v_cvt_pk_bf16_f32 v159, v48, v49
	v_exp_f32_e32 v50, v50
	v_exp_f32_e32 v51, v51
	v_mfma_f32_32x32x16_bf16 v[18:33], v[202:205], v[156:159], v[18:33]
	v_mfma_f32_32x32x16_bf16 v[2:17], v[218:221], v[156:159], v[2:17]
	v_exp_f32_e32 v52, v52
	v_exp_f32_e32 v53, v53
	v_exp_f32_e32 v54, v54
	v_exp_f32_e32 v55, v55
	v_exp_f32_e32 v56, v56
	v_exp_f32_e32 v57, v57
	v_add_f32_e32 v108, v108, v50
	v_add_f32_e32 v110, v110, v51
	v_add_f32_e32 v108, v108, v52
	v_add_f32_e32 v110, v110, v53
	v_add_f32_e32 v108, v108, v54
	v_add_f32_e32 v110, v110, v55
	v_add_f32_e32 v108, v108, v56
	v_add_f32_e32 v110, v110, v57
	v_cvt_pk_bf16_f32 v172, v50, v51
	v_cvt_pk_bf16_f32 v173, v52, v53
	v_cvt_pk_bf16_f32 v174, v54, v55
	v_cvt_pk_bf16_f32 v175, v56, v57
	v_exp_f32_e32 v58, v58
	v_exp_f32_e32 v59, v59
	v_mfma_f32_32x32x16_bf16 v[18:33], v[206:209], v[172:175], v[18:33]
	v_mfma_f32_32x32x16_bf16 v[2:17], v[234:237], v[172:175], v[2:17]
	v_exp_f32_e32 v60, v60
	v_exp_f32_e32 v61, v61
	v_exp_f32_e32 v62, v62
	v_exp_f32_e32 v63, v63
	v_exp_f32_e32 v64, v64
	v_exp_f32_e32 v65, v65
	v_add_f32_e32 v108, v108, v58
	v_add_f32_e32 v110, v110, v59
	v_add_f32_e32 v108, v108, v60
	v_add_f32_e32 v110, v110, v61
	v_add_f32_e32 v108, v108, v62
	v_add_f32_e32 v110, v110, v63
	v_add_f32_e32 v108, v108, v64
	v_add_f32_e32 v110, v110, v65
	v_cvt_pk_bf16_f32 v246, v58, v59
	v_cvt_pk_bf16_f32 v247, v60, v61
	v_cvt_pk_bf16_f32 v248, v62, v63
	v_cvt_pk_bf16_f32 v249, v64, v65
	v_add_f32_e32 v108, v108, v110
	v_add_f32_e32 v111, v111, v108
	v_mfma_f32_32x32x16_bf16 v[18:33], v[210:213], v[246:249], v[18:33]
	v_mfma_f32_32x32x16_bf16 v[2:17], v[238:241], v[246:249], v[2:17]
; #define LAS __attribute__((address_space(3)))
; #define STAGE_TILE(bufi, KR, VR) do { LAS bf16_t* Ks_ = (LAS bf16_t*)(lds + (bufi) * 18432); LAS bf16_t* Vs_ = (LAS bf16_t*)(lds + (bufi) * 18432 + 9216); \
;         *(LAS u32x4*)(Ks_ + skr * 72 + sch * 8) = KR; *(LAS u32x4*)(Vs_ + skr * 72 + sch * 8) = VR; } while (0)
; #define LOAD_TILE(KR, VR, tl) do { KR = *(const GAS u32x4*)(kg + (size_t)(tl) * 64 * LDH); VR = *(const GAS u32x4*)(vg + (size_t)(tl) * 64 * LDH); } while (0)
; template <int MODE> ...
;     ...
;         STAGE_TILE(1, kB, vB);
;         __syncthreads();
;         if (MODE == 1) { const u32x4 fa = *(const LAS u32x4*)flags, fb = *(const LAS u32x4*)(flags + 4); if ((fa.x & fa.y & fa.z & fa.w & fb.x & fb.y & fb.z & fb.w) != 0u) break; }
;         LOAD_TILE(kB, vB, TILE_OF(min(it + 3, ntiles - 1)));
;         COMPUTE_TILE(TILE_OF(it + 1), 1);
.LBB0_926:
	s_add_i32 s12, s23, 3
	s_min_i32 s14, s12, s18
	v_mad_u64_u32 v[34:35], s[12:13], s14, v231, v[102:103]
	s_waitcnt vmcnt(3)
	ds_write_b128 v101, v[82:85] offset:18432
	s_waitcnt vmcnt(2)
	ds_write_b128 v101, v[86:89] offset:27648
	s_waitcnt lgkmcnt(0)
	s_barrier
	v_mad_u64_u32 v[36:37], s[12:13], s14, v231, v[104:105]
	global_load_dwordx4 v[82:85], v[34:35], off
	global_load_dwordx4 v[86:89], v[36:37], off
	s_cmp_ge_i32 s23, s17
	s_cbranch_scc1 .LBB0_932
	ds_read_b64 v[34:35], v109 offset:8
	ds_read_b128 v[118:121], v113 offset:18432
	ds_read_b128 v[182:185], v113 offset:23040
	ds_read_b128 v[122:125], v113 offset:18464
	ds_read_b128 v[186:189], v113 offset:23072
	ds_read_b128 v[126:129], v113 offset:18496
	ds_read_b128 v[190:193], v113 offset:23104
	ds_read_b128 v[130:133], v113 offset:18528
	ds_read_b128 v[242:245], v113 offset:23136
	v_sub_f32_e32 v1, 0, v112
	s_xor_b64 s[10:11], s[10:11], -1
	s_waitcnt lgkmcnt(8)
	v_lshrrev_b64 v[114:115], v100, v[34:35]
	v_lshrrev_b64 v[116:117], v106, v[34:35]
	v_bfe_i32 v34, v114, 0, 1
	v_bfe_i32 v50, v116, 0, 1
	v_bfe_i32 v35, v114, 1, 1
	v_bfe_i32 v51, v116, 1, 1
	v_bfe_i32 v36, v114, 2, 1
	v_bfe_i32 v52, v116, 2, 1
	v_bfe_i32 v37, v114, 3, 1
	v_bfe_i32 v53, v116, 3, 1
	v_bfe_i32 v38, v114, 8, 1
	v_bfe_i32 v54, v116, 8, 1
	v_bfe_i32 v39, v114, 9, 1
	v_bfe_i32 v55, v116, 9, 1
	v_bfe_i32 v40, v114, 10, 1
	v_bfe_i32 v56, v116, 10, 1
	v_bfe_i32 v41, v114, 11, 1
	v_bfe_i32 v57, v116, 11, 1
	v_bfe_i32 v42, v114, 16, 1
	v_bfe_i32 v58, v116, 16, 1
	v_bfe_i32 v43, v114, 17, 1
	v_bfe_i32 v59, v116, 17, 1
	v_bfe_i32 v44, v114, 18, 1
	v_bfe_i32 v60, v116, 18, 1
	v_bfe_i32 v45, v114, 19, 1
	v_bfe_i32 v61, v116, 19, 1
	v_bfe_i32 v46, v114, 24, 1
	v_bfe_i32 v62, v116, 24, 1
	v_bfe_i32 v47, v114, 25, 1
	v_bfe_i32 v63, v116, 25, 1
	v_bfe_i32 v48, v114, 26, 1
	v_bfe_i32 v64, v116, 26, 1
	v_bfe_i32 v49, v114, 27, 1
	v_bfe_i32 v65, v116, 27, 1
	v_bfi_b32 v34, v34, v1, v232
	v_bfi_b32 v35, v35, v1, v232
	v_bfi_b32 v36, v36, v1, v232
	v_bfi_b32 v37, v37, v1, v232
	v_bfi_b32 v38, v38, v1, v232
	v_bfi_b32 v39, v39, v1, v232
	v_bfi_b32 v40, v40, v1, v232
	v_bfi_b32 v41, v41, v1, v232
	v_bfi_b32 v42, v42, v1, v232
	v_bfi_b32 v43, v43, v1, v232
	v_bfi_b32 v44, v44, v1, v232
	v_bfi_b32 v45, v45, v1, v232
	v_bfi_b32 v46, v46, v1, v232
	v_bfi_b32 v47, v47, v1, v232
	v_bfi_b32 v48, v48, v1, v232
	v_bfi_b32 v49, v49, v1, v232
	v_bfi_b32 v50, v50, v1, v232
	v_bfi_b32 v51, v51, v1, v232
	v_bfi_b32 v52, v52, v1, v232
	v_bfi_b32 v53, v53, v1, v232
	v_bfi_b32 v54, v54, v1, v232
	v_bfi_b32 v55, v55, v1, v232
	v_bfi_b32 v56, v56, v1, v232
	v_bfi_b32 v57, v57, v1, v232
	v_bfi_b32 v58, v58, v1, v232
	v_bfi_b32 v59, v59, v1, v232
	v_bfi_b32 v60, v60, v1, v232
	v_bfi_b32 v61, v61, v1, v232
	v_bfi_b32 v62, v62, v1, v232
	v_bfi_b32 v63, v63, v1, v232
	v_bfi_b32 v64, v64, v1, v232
	v_bfi_b32 v65, v65, v1, v232
	s_waitcnt lgkmcnt(6)
	v_mfma_f32_32x32x16_bf16 v[34:49], v[118:121], v[74:77], v[34:49]
	v_mfma_f32_32x32x16_bf16 v[50:65], v[182:185], v[74:77], v[50:65]
	s_waitcnt lgkmcnt(4)
	v_mfma_f32_32x32x16_bf16 v[34:49], v[122:125], v[66:69], v[34:49]
	v_mfma_f32_32x32x16_bf16 v[50:65], v[186:189], v[66:69], v[50:65]
	s_waitcnt lgkmcnt(2)
	v_mfma_f32_32x32x16_bf16 v[34:49], v[126:129], v[70:73], v[34:49]
	v_mfma_f32_32x32x16_bf16 v[50:65], v[190:193], v[70:73], v[50:65]
	s_waitcnt lgkmcnt(0)
	v_mfma_f32_32x32x16_bf16 v[34:49], v[130:133], v[78:81], v[34:49]
	v_mfma_f32_32x32x16_bf16 v[50:65], v[242:245], v[78:81], v[50:65]
	ds_read_b64_tr_b16 v[198:199], v107 offset:27648
	ds_read_b64_tr_b16 v[200:201], v107 offset:28800
	ds_read_b64_tr_b16 v[202:203], v107 offset:29952
	ds_read_b64_tr_b16 v[204:205], v107 offset:31104
	ds_read_b64_tr_b16 v[206:207], v107 offset:32256
	ds_read_b64_tr_b16 v[208:209], v107 offset:33408
	ds_read_b64_tr_b16 v[210:211], v107 offset:34560
	ds_read_b64_tr_b16 v[212:213], v107 offset:35712
	ds_read_b64_tr_b16 v[214:215], v107 offset:27712
	ds_read_b64_tr_b16 v[216:217], v107 offset:28864
	ds_read_b64_tr_b16 v[218:219], v107 offset:30016
	ds_read_b64_tr_b16 v[220:221], v107 offset:31168
	ds_read_b64_tr_b16 v[234:235], v107 offset:32320
	ds_read_b64_tr_b16 v[236:237], v107 offset:33472
	ds_read_b64_tr_b16 v[238:239], v107 offset:34624
	ds_read_b64_tr_b16 v[240:241], v107 offset:35776
	v_max3_f32 v108, v34, v35, v36
	v_max3_f32 v110, v37, v38, v39
	v_max3_f32 v114, v40, v41, v42
	v_max3_f32 v1, v43, v44, v45
	v_max3_f32 v108, v108, v46, v47
	v_max3_f32 v110, v110, v48, v49
	v_max3_f32 v114, v114, v50, v51
	v_max3_f32 v1, v1, v52, v53
	v_max3_f32 v108, v108, v54, v55
	v_max3_f32 v110, v110, v56, v57
	v_max3_f32 v114, v114, v58, v59
	v_max3_f32 v1, v1, v60, v61
	v_max3_f32 v108, v108, v62, v63
	v_max3_f32 v110, v110, v64, v65
	v_max3_f32 v1, v1, v114, s82
	v_max3_f32 v1, v1, v108, v110
	v_and_b32_e32 v110, 64, v224
	v_xor_b32_e32 v108, 32, v224
	v_add_u32_e32 v110, 64, v110
	v_cmp_lt_i32_e32 vcc, v108, v110
	s_nop 1
	v_cndmask_b32_e32 v108, v224, v108, vcc
	v_lshlrev_b32_e32 v108, 2, v108
	ds_bpermute_b32 v108, v108, v1
	s_waitcnt lgkmcnt(0)
	v_max_f32_e32 v108, v108, v108
	v_max_f32_e32 v1, v1, v108
	s_and_saveexec_b64 s[12:13], s[10:11]
	s_xor_b64 s[10:11], exec, s[12:13]
	s_cbranch_execnz .LBB0_940
	s_or_saveexec_b64 s[12:13], s[10:11]
	s_mov_b64 s[10:11], 0
	s_xor_b64 exec, exec, s[12:13]
	s_cbranch_execnz .LBB0_943

; #define PG8_STAGE(bufoff, gbase, voff) do { _Pragma("unroll") for (int _i = 0; _i < 2; ++_i) \
;         __builtin_amdgcn_global_load_lds((const unsigned*)((const char*)(gbase) + (voff)[_i]), (PG8_LAS unsigned*)(lds + (bufoff) + ldsw + _i * 8192), 16, 0, 0); } while (0)
; #define PG8_LDA(dst, b, h) do { _Pragma("unroll") for (int m = 0; m < 4; ++m) _Pragma("unroll") for (int k = 0; k < 2; ++k) dst[m][k] = *(const PG8_LAS bf16x8*)(lds + PG8_SA(b, h) + aoff + m * 2048 + k * 1024); } while (0)
; #define PG8_LDB(dst, b, h) do { _Pragma("unroll") for (int n = 0; n < 2; ++n) _Pragma("unroll") for (int k = 0; k < 2; ++k) dst[n][k] = *(const PG8_LAS bf16x8*)(lds + PG8_SB(b, h) + boff + n * 2048 + k * 1024); } while (0)
; #define PG8_MMA(ai, bj, At, Bt) do { __builtin_amdgcn_s_setprio(1); _Pragma("unroll") for (int m = 0; m < 4; ++m) _Pragma("unroll") for (int n = 0; n < 2; ++n) _Pragma("unroll") for (int k = 0; k < 2; ++k) \
;         acc[ai][bj][m][n] = __builtin_amdgcn_mfma_f32_16x16x32_bf16(Bt[n][k], At[m][k], acc[ai][bj][m][n], 0, 0, 0); __builtin_amdgcn_s_setprio(0); } while (0)
; #define PG8_WAIT_V(n) asm volatile("s_waitcnt vmcnt(" #n ")" ::: "memory")
; #define PG8_BAR __builtin_amdgcn_s_barrier()
; template <class Epi, class Sched, bool ALIGN_EPI = false, bool SP2 = false>
; __device__ __forceinline__ void gemm_phase(PG8_LAS unsigned char* lds, const Gemm g, const Sched& S, const Epi& E) {
;     ...
;         for (int t = t0; t < t1; t += 2) {
;             const bool last = (t == nt - 2);
;             const char* a1 = cA + (size_t)(t + 1) * kstep;
;             const char* a2 = last ? nA : cA + (size_t)(t + 2) * kstep; const char* b2 = last ? nB : cB + (size_t)(t + 2) * kstep;
;             const char* a3 = a2 + kstep; const char* b3 = b2 + kstep;
;             if (last && has_next) S.a_ready(nxt);
;             if constexpr (SP2) {
;             PG8_LDB(B0, 0, 0); PG8_LDB(B1, 0, 1); PG8_SCHED; PG8_LDA(At, 0, 0); PG8_STAGE(PG8_SA(1, 1), a1 + hstep, voffA);
;             PG8_WAIT_V(8); PG8_WAIT_L(0); PG8_BAR; PG8_MMA(0, 0, At, B0); PG8_MMA(0, 1, At, B1); PG8_BAR; PG8_SCHED;
;     ...
; #pragma unroll
;         for (int a = 0; a < 2; ++a)
; #pragma unroll
;             for (int b = 0; b < 2; ++b)
; #pragma unroll
;                 for (int m = 0; m < 4; ++m)
; #pragma unroll
;                     for (int n = 0; n < 2; ++n) acc[a][b][m][n] = (f32x4){0.f, 0.f, 0.f, 0.f};
.LBB0_1015:
	s_and_b64 s[14:15], s[16:17], exec
	v_mov_b32_e32 v129, 0
	s_cselect_b32 s15, s5, s25
	s_cselect_b32 s14, s4, s24
	s_andn2_b64 vcc, exec, s[8:9]
	v_mov_b32_e32 v128, v129
	v_mov_b32_e32 v127, v129
	v_mov_b32_e32 v126, v129
	v_mov_b32_e32 v125, v129
	v_mov_b32_e32 v124, v129
	v_mov_b32_e32 v123, v129
	v_mov_b32_e32 v122, v129
	v_mov_b32_e32 v113, v129
	v_mov_b32_e32 v112, v129
	v_mov_b32_e32 v111, v129
	v_mov_b32_e32 v110, v129
	v_mov_b32_e32 v109, v129
	v_mov_b32_e32 v108, v129
	v_mov_b32_e32 v107, v129
	v_mov_b32_e32 v106, v129
	v_mov_b32_e32 v97, v129
	v_mov_b32_e32 v96, v129
	v_mov_b32_e32 v95, v129
	v_mov_b32_e32 v94, v129
	v_mov_b32_e32 v93, v129
	v_mov_b32_e32 v92, v129
	v_mov_b32_e32 v91, v129
	v_mov_b32_e32 v90, v129
	v_mov_b32_e32 v81, v129
	v_mov_b32_e32 v80, v129
	v_mov_b32_e32 v79, v129
	v_mov_b32_e32 v78, v129
	v_mov_b32_e32 v77, v129
	v_mov_b32_e32 v76, v129
	v_mov_b32_e32 v75, v129
	v_mov_b32_e32 v74, v129
	v_mov_b32_e32 v121, v129
	v_mov_b32_e32 v120, v129
	v_mov_b32_e32 v119, v129
	v_mov_b32_e32 v118, v129
	v_mov_b32_e32 v117, v129
	v_mov_b32_e32 v116, v129
	v_mov_b32_e32 v115, v129
	v_mov_b32_e32 v114, v129
	v_mov_b32_e32 v105, v129
	v_mov_b32_e32 v104, v129
	v_mov_b32_e32 v103, v129
	v_mov_b32_e32 v102, v129
	v_mov_b32_e32 v101, v129
	v_mov_b32_e32 v100, v129
	v_mov_b32_e32 v99, v129
	v_mov_b32_e32 v98, v129
	v_mov_b32_e32 v89, v129
	v_mov_b32_e32 v88, v129
	v_mov_b32_e32 v87, v129
	v_mov_b32_e32 v86, v129
	v_mov_b32_e32 v85, v129
	v_mov_b32_e32 v84, v129
	v_mov_b32_e32 v83, v129
	v_mov_b32_e32 v82, v129
	v_mov_b32_e32 v73, v129
	v_mov_b32_e32 v72, v129
	v_mov_b32_e32 v71, v129
	v_mov_b32_e32 v70, v129
	v_mov_b32_e32 v69, v129
	v_mov_b32_e32 v68, v129
	v_mov_b32_e32 v67, v129
	v_mov_b32_e32 v66, v129
	v_mov_b32_e32 v65, v129
	v_mov_b32_e32 v64, v129
	v_mov_b32_e32 v63, v129
	v_mov_b32_e32 v62, v129
	v_mov_b32_e32 v61, v129
	v_mov_b32_e32 v60, v129
	v_mov_b32_e32 v59, v129
	v_mov_b32_e32 v58, v129
	v_mov_b32_e32 v49, v129
	v_mov_b32_e32 v48, v129
	v_mov_b32_e32 v47, v129
	v_mov_b32_e32 v46, v129
	v_mov_b32_e32 v45, v129
	v_mov_b32_e32 v44, v129
	v_mov_b32_e32 v43, v129
	v_mov_b32_e32 v42, v129
	v_mov_b32_e32 v33, v129
	v_mov_b32_e32 v32, v129
	v_mov_b32_e32 v31, v129
	v_mov_b32_e32 v30, v129
	v_mov_b32_e32 v29, v129
	v_mov_b32_e32 v28, v129
	v_mov_b32_e32 v27, v129
	v_mov_b32_e32 v26, v129
	v_mov_b32_e32 v17, v129
	v_mov_b32_e32 v16, v129
	v_mov_b32_e32 v15, v129
	v_mov_b32_e32 v14, v129
	v_mov_b32_e32 v13, v129
	v_mov_b32_e32 v12, v129
	v_mov_b32_e32 v11, v129
	v_mov_b32_e32 v10, v129
	v_mov_b32_e32 v57, v129
	v_mov_b32_e32 v56, v129
	v_mov_b32_e32 v55, v129
	v_mov_b32_e32 v54, v129
	v_mov_b32_e32 v53, v129
	v_mov_b32_e32 v52, v129
	v_mov_b32_e32 v51, v129
	v_mov_b32_e32 v50, v129
	v_mov_b32_e32 v41, v129
	v_mov_b32_e32 v40, v129
	v_mov_b32_e32 v39, v129
	v_mov_b32_e32 v38, v129
	v_mov_b32_e32 v37, v129
	v_mov_b32_e32 v36, v129
	v_mov_b32_e32 v35, v129
	v_mov_b32_e32 v34, v129
	v_mov_b32_e32 v25, v129
	v_mov_b32_e32 v24, v129
	v_mov_b32_e32 v23, v129
	v_mov_b32_e32 v22, v129
	v_mov_b32_e32 v21, v129
	v_mov_b32_e32 v20, v129
	v_mov_b32_e32 v19, v129
	v_mov_b32_e32 v18, v129
	v_mov_b32_e32 v9, v129
	v_mov_b32_e32 v8, v129
	v_mov_b32_e32 v7, v129
	v_mov_b32_e32 v6, v129
	v_mov_b32_e32 v5, v129
	v_mov_b32_e32 v4, v129
	v_mov_b32_e32 v3, v129
	v_mov_b32_e32 v2, v129
	s_cbranch_vccnz .LBB0_1019
	s_add_u32 s50, s18, 0x100
	s_addc_u32 s51, s19, 0
	s_add_u32 s18, s24, 0x80
	v_mov_b32_e32 v2, 0
	s_mov_b32 s64, s52
	s_addc_u32 s19, s25, 0
	s_mov_b32 s24, 0
.LBB0_1017:
	s_add_i32 s52, s24, 2
	s_add_u32 s53, s18, 0x80
	s_addc_u32 s25, s19, 0
	s_add_i32 s56, 0, 0x10000
	s_cmp_eq_u32 s44, s24
	s_cselect_b32 s25, s15, s25
	s_cselect_b32 s24, s14, s53
	v_add_u32_e32 v145, s56, v142
	s_cselect_b32 s55, s13, s51
	s_cselect_b32 s54, s12, s50
	s_add_i32 s53, 0, 0x14000
	ds_read_b128 v[146:149], v145
	ds_read_b128 v[150:153], v145 offset:1024
	ds_read_b128 v[154:157], v145 offset:2048
	ds_read_b128 v[158:161], v145 offset:3072
	v_add_u32_e32 v145, s53, v142
	ds_read_b128 v[162:165], v145
	ds_read_b128 v[166:169], v145 offset:1024
	ds_read_b128 v[170:173], v145 offset:2048
	ds_read_b128 v[174:177], v145 offset:3072
	v_lshl_add_u64 v[214:215], s[18:19], 0, v[140:141]
	s_add_i32 m0, s29, 0xc000
	ds_read_b128 v[178:181], v144
	ds_read_b128 v[182:185], v144 offset:1024
	ds_read_b128 v[186:189], v144 offset:2048
	ds_read_b128 v[190:193], v144 offset:3072
	ds_read_b128 v[196:199], v144 offset:4096
	ds_read_b128 v[200:203], v144 offset:5120
	ds_read_b128 v[206:209], v144 offset:6144
	ds_read_b128 v[210:213], v144 offset:7168
	global_load_lds_dwordx4 v[214:215], off
	v_lshl_add_u64 v[214:215], s[18:19], 0, v[138:139]
	s_add_i32 m0, s29, 0xe000
	s_nop 0
	global_load_lds_dwordx4 v[214:215], off
	s_waitcnt vmcnt(8)
	s_waitcnt lgkmcnt(0)
	s_barrier
; #define PG8_STAGE(bufoff, gbase, voff) do { _Pragma("unroll") for (int _i = 0; _i < 2; ++_i) \
;         __builtin_amdgcn_global_load_lds((const unsigned*)((const char*)(gbase) + (voff)[_i]), (PG8_LAS unsigned*)(lds + (bufoff) + ldsw + _i * 8192), 16, 0, 0); } while (0)
; #define PG8_LDA(dst, b, h) do { _Pragma("unroll") for (int m = 0; m < 4; ++m) _Pragma("unroll") for (int k = 0; k < 2; ++k) dst[m][k] = *(const PG8_LAS bf16x8*)(lds + PG8_SA(b, h) + aoff + m * 2048 + k * 1024); } while (0)
; #define PG8_MMA(ai, bj, At, Bt) do { __builtin_amdgcn_s_setprio(1); _Pragma("unroll") for (int m = 0; m < 4; ++m) _Pragma("unroll") for (int n = 0; n < 2; ++n) _Pragma("unroll") for (int k = 0; k < 2; ++k) \
;         acc[ai][bj][m][n] = __builtin_amdgcn_mfma_f32_16x16x32_bf16(Bt[n][k], At[m][k], acc[ai][bj][m][n], 0, 0, 0); __builtin_amdgcn_s_setprio(0); } while (0)
; #define PG8_WAIT_V(n) asm volatile("s_waitcnt vmcnt(" #n ")" ::: "memory")
; #define PG8_WAIT_L(n) asm volatile("s_waitcnt lgkmcnt(" #n ")" ::: "memory")
; #define PG8_BAR __builtin_amdgcn_s_barrier()
; #define PG8_SCHED __builtin_amdgcn_sched_barrier(0)
; template <class Epi, class Sched, bool ALIGN_EPI = false, bool SP2 = false>
; __device__ __forceinline__ void gemm_phase(PG8_LAS unsigned char* lds, const Gemm g, const Sched& S, const Epi& E) {
;     ...
;             PG8_WAIT_V(8); PG8_WAIT_L(0); PG8_BAR; PG8_MMA(0, 0, At, B0); PG8_MMA(0, 1, At, B1); PG8_BAR; PG8_SCHED;
;             PG8_LDA(At, 0, 1); PG8_STAGE(PG8_SB(0, 0), b2, voffB); PG8_STAGE(PG8_SB(0, 1), b2 + hstep, voffB); PG8_STAGE(PG8_SA(0, 0), a2, voffA);
;             PG8_WAIT_V(8); PG8_WAIT_L(0); PG8_BAR; PG8_MMA(1, 0, At, B0); PG8_MMA(1, 1, At, B1); PG8_BAR; PG8_SCHED;
	s_setprio 1
	s_waitcnt lgkmcnt(0)
	v_mfma_f32_16x16x32_bf16 v[126:129], v[146:149], v[178:181], v[126:129]
	v_mfma_f32_16x16x32_bf16 v[122:125], v[154:157], v[178:181], v[122:125]
	v_mfma_f32_16x16x32_bf16 v[110:113], v[146:149], v[186:189], v[110:113]
	v_mfma_f32_16x16x32_bf16 v[106:109], v[154:157], v[186:189], v[106:109]
	v_mfma_f32_16x16x32_bf16 v[94:97], v[146:149], v[196:199], v[94:97]
	v_mfma_f32_16x16x32_bf16 v[90:93], v[154:157], v[196:199], v[90:93]
	v_mfma_f32_16x16x32_bf16 v[78:81], v[146:149], v[206:209], v[78:81]
	v_mfma_f32_16x16x32_bf16 v[74:77], v[154:157], v[206:209], v[74:77]
	v_mfma_f32_16x16x32_bf16 v[126:129], v[150:153], v[182:185], v[126:129]
	v_mfma_f32_16x16x32_bf16 v[122:125], v[158:161], v[182:185], v[122:125]
	v_mfma_f32_16x16x32_bf16 v[110:113], v[150:153], v[190:193], v[110:113]
	v_mfma_f32_16x16x32_bf16 v[106:109], v[158:161], v[190:193], v[106:109]
	v_mfma_f32_16x16x32_bf16 v[94:97], v[150:153], v[200:203], v[94:97]
	v_mfma_f32_16x16x32_bf16 v[90:93], v[158:161], v[200:203], v[90:93]
	v_mfma_f32_16x16x32_bf16 v[78:81], v[150:153], v[210:213], v[78:81]
	v_mfma_f32_16x16x32_bf16 v[74:77], v[158:161], v[210:213], v[74:77]
	s_setprio 0
	s_setprio 1
	v_mfma_f32_16x16x32_bf16 v[118:121], v[162:165], v[178:181], v[118:121]
	v_mfma_f32_16x16x32_bf16 v[114:117], v[170:173], v[178:181], v[114:117]
	v_mfma_f32_16x16x32_bf16 v[102:105], v[162:165], v[186:189], v[102:105]
	v_mfma_f32_16x16x32_bf16 v[98:101], v[170:173], v[186:189], v[98:101]
	v_mfma_f32_16x16x32_bf16 v[86:89], v[162:165], v[196:199], v[86:89]
	v_mfma_f32_16x16x32_bf16 v[82:85], v[170:173], v[196:199], v[82:85]
	v_mfma_f32_16x16x32_bf16 v[70:73], v[162:165], v[206:209], v[70:73]
	v_mfma_f32_16x16x32_bf16 v[66:69], v[170:173], v[206:209], v[66:69]
	v_mfma_f32_16x16x32_bf16 v[118:121], v[166:169], v[182:185], v[118:121]
	v_mfma_f32_16x16x32_bf16 v[114:117], v[174:177], v[182:185], v[114:117]
	v_mfma_f32_16x16x32_bf16 v[102:105], v[166:169], v[190:193], v[102:105]
	v_mfma_f32_16x16x32_bf16 v[98:101], v[174:177], v[190:193], v[98:101]
	v_mfma_f32_16x16x32_bf16 v[86:89], v[166:169], v[200:203], v[86:89]
	v_mfma_f32_16x16x32_bf16 v[82:85], v[174:177], v[200:203], v[82:85]
	v_mfma_f32_16x16x32_bf16 v[70:73], v[166:169], v[210:213], v[70:73]
	v_mfma_f32_16x16x32_bf16 v[66:69], v[174:177], v[210:213], v[66:69]
	s_setprio 0
	s_barrier
	s_add_i32 s56, s56, s28
	v_lshl_add_u64 v[214:215], s[54:55], 0, v[132:133]
	s_mov_b32 m0, s56
	ds_read_b128 v[178:181], v144 offset:16384
	ds_read_b128 v[182:185], v144 offset:17408
	ds_read_b128 v[186:189], v144 offset:18432
	ds_read_b128 v[190:193], v144 offset:19456
	ds_read_b128 v[196:199], v144 offset:20480
	ds_read_b128 v[200:203], v144 offset:21504
	ds_read_b128 v[206:209], v144 offset:22528
	ds_read_b128 v[210:213], v144 offset:23552
	global_load_lds_dwordx4 v[214:215], off
	s_add_i32 m0, s56, 0x2000
	v_lshl_add_u64 v[216:217], s[54:55], 0, v[136:137]
	s_add_u32 s54, s54, s2
	s_addc_u32 s55, s55, s3
	s_add_i32 s53, s53, s28
	global_load_lds_dwordx4 v[216:217], off
	v_lshl_add_u64 v[218:219], s[54:55], 0, v[132:133]
	s_mov_b32 m0, s53
	v_lshl_add_u64 v[234:235], s[54:55], 0, v[136:137]
	global_load_lds_dwordx4 v[218:219], off
	s_add_i32 m0, s53, 0x2000
	v_lshl_add_u64 v[236:237], s[24:25], 0, v[130:131]
	global_load_lds_dwordx4 v[234:235], off
	s_mov_b32 m0, s29
	v_lshl_add_u64 v[238:239], s[24:25], 0, v[134:135]
	global_load_lds_dwordx4 v[236:237], off
	s_mov_b32 m0, s30
	s_nop 0
	global_load_lds_dwordx4 v[238:239], off
	s_waitcnt vmcnt(8)
	s_waitcnt lgkmcnt(0)
	s_barrier
	s_setprio 1
	s_waitcnt lgkmcnt(0)
	v_mfma_f32_16x16x32_bf16 v[62:65], v[146:149], v[178:181], v[62:65]
	v_mfma_f32_16x16x32_bf16 v[58:61], v[154:157], v[178:181], v[58:61]
	v_mfma_f32_16x16x32_bf16 v[46:49], v[146:149], v[186:189], v[46:49]
	v_mfma_f32_16x16x32_bf16 v[42:45], v[154:157], v[186:189], v[42:45]
	v_mfma_f32_16x16x32_bf16 v[30:33], v[146:149], v[196:199], v[30:33]
	v_mfma_f32_16x16x32_bf16 v[26:29], v[154:157], v[196:199], v[26:29]
	v_mfma_f32_16x16x32_bf16 v[14:17], v[146:149], v[206:209], v[14:17]
	v_mfma_f32_16x16x32_bf16 v[10:13], v[154:157], v[206:209], v[10:13]
	v_mfma_f32_16x16x32_bf16 v[62:65], v[150:153], v[182:185], v[62:65]
	v_mfma_f32_16x16x32_bf16 v[58:61], v[158:161], v[182:185], v[58:61]
	v_mfma_f32_16x16x32_bf16 v[46:49], v[150:153], v[190:193], v[46:49]
	v_mfma_f32_16x16x32_bf16 v[42:45], v[158:161], v[190:193], v[42:45]
	v_mfma_f32_16x16x32_bf16 v[30:33], v[150:153], v[200:203], v[30:33]
	v_mfma_f32_16x16x32_bf16 v[26:29], v[158:161], v[200:203], v[26:29]
	v_mfma_f32_16x16x32_bf16 v[14:17], v[150:153], v[210:213], v[14:17]
	v_mfma_f32_16x16x32_bf16 v[10:13], v[158:161], v[210:213], v[10:13]
	s_setprio 0
	s_setprio 1
	v_mfma_f32_16x16x32_bf16 v[54:57], v[162:165], v[178:181], v[54:57]
	v_mfma_f32_16x16x32_bf16 v[50:53], v[170:173], v[178:181], v[50:53]
	v_mfma_f32_16x16x32_bf16 v[38:41], v[162:165], v[186:189], v[38:41]
	v_mfma_f32_16x16x32_bf16 v[34:37], v[170:173], v[186:189], v[34:37]
	v_mfma_f32_16x16x32_bf16 v[22:25], v[162:165], v[196:199], v[22:25]
	v_mfma_f32_16x16x32_bf16 v[18:21], v[170:173], v[196:199], v[18:21]
	v_mfma_f32_16x16x32_bf16 v[6:9], v[162:165], v[206:209], v[6:9]
	v_mfma_f32_16x16x32_bf16 v[2:5], v[170:173], v[206:209], v[2:5]
	v_mfma_f32_16x16x32_bf16 v[54:57], v[166:169], v[182:185], v[54:57]
	v_mfma_f32_16x16x32_bf16 v[50:53], v[174:177], v[182:185], v[50:53]
	v_mfma_f32_16x16x32_bf16 v[38:41], v[166:169], v[190:193], v[38:41]
	v_mfma_f32_16x16x32_bf16 v[34:37], v[174:177], v[190:193], v[34:37]
	v_mfma_f32_16x16x32_bf16 v[22:25], v[166:169], v[200:203], v[22:25]
	v_mfma_f32_16x16x32_bf16 v[18:21], v[174:177], v[200:203], v[18:21]
	v_mfma_f32_16x16x32_bf16 v[6:9], v[166:169], v[210:213], v[6:9]
	v_mfma_f32_16x16x32_bf16 v[2:5], v[174:177], v[210:213], v[2:5]
	s_setprio 0
	s_barrier
; #define PG8_STAGE(bufoff, gbase, voff) do { _Pragma("unroll") for (int _i = 0; _i < 2; ++_i) \
;         __builtin_amdgcn_global_load_lds((const unsigned*)((const char*)(gbase) + (voff)[_i]), (PG8_LAS unsigned*)(lds + (bufoff) + ldsw + _i * 8192), 16, 0, 0); } while (0)
; #define PG8_LDA(dst, b, h) do { _Pragma("unroll") for (int m = 0; m < 4; ++m) _Pragma("unroll") for (int k = 0; k < 2; ++k) dst[m][k] = *(const PG8_LAS bf16x8*)(lds + PG8_SA(b, h) + aoff + m * 2048 + k * 1024); } while (0)
; #define PG8_LDB(dst, b, h) do { _Pragma("unroll") for (int n = 0; n < 2; ++n) _Pragma("unroll") for (int k = 0; k < 2; ++k) dst[n][k] = *(const PG8_LAS bf16x8*)(lds + PG8_SB(b, h) + boff + n * 2048 + k * 1024); } while (0)
; #define PG8_MMA(ai, bj, At, Bt) do { __builtin_amdgcn_s_setprio(1); _Pragma("unroll") for (int m = 0; m < 4; ++m) _Pragma("unroll") for (int n = 0; n < 2; ++n) _Pragma("unroll") for (int k = 0; k < 2; ++k) \
;         acc[ai][bj][m][n] = __builtin_amdgcn_mfma_f32_16x16x32_bf16(Bt[n][k], At[m][k], acc[ai][bj][m][n], 0, 0, 0); __builtin_amdgcn_s_setprio(0); } while (0)
; #define PG8_WAIT_V(n) asm volatile("s_waitcnt vmcnt(" #n ")" ::: "memory")
; #define PG8_WAIT_L(n) asm volatile("s_waitcnt lgkmcnt(" #n ")" ::: "memory")
; #define PG8_BAR __builtin_amdgcn_s_barrier()
; #define PG8_SCHED __builtin_amdgcn_sched_barrier(0)
; template <class Epi, class Sched, bool ALIGN_EPI = false, bool SP2 = false>
; __device__ __forceinline__ void gemm_phase(PG8_LAS unsigned char* lds, const Gemm g, const Sched& S, const Epi& E) {
;     ...
;             PG8_LDB(B0, 1, 0); PG8_LDB(B1, 1, 1); PG8_SCHED; PG8_LDA(At, 1, 0); PG8_STAGE(PG8_SA(0, 1), a2 + hstep, voffA);
;             PG8_WAIT_V(8); PG8_WAIT_L(0); PG8_BAR; PG8_MMA(0, 0, At, B0); PG8_MMA(0, 1, At, B1); PG8_BAR; PG8_SCHED;
	s_add_i32 s53, 0, 0x18000
	v_add_u32_e32 v145, s53, v142
	s_add_i32 s54, 0, 0x1c000
	ds_read_b128 v[146:149], v145
	ds_read_b128 v[150:153], v145 offset:1024
	ds_read_b128 v[154:157], v145 offset:2048
	ds_read_b128 v[158:161], v145 offset:3072
	v_add_u32_e32 v145, s54, v142
	ds_read_b128 v[162:165], v145
	ds_read_b128 v[166:169], v145 offset:1024
	ds_read_b128 v[170:173], v145 offset:2048
	ds_read_b128 v[174:177], v145 offset:3072
	s_add_u32 s24, s24, s2
	s_addc_u32 s25, s25, s3
	s_mov_b32 m0, s35
	v_lshl_add_u64 v[240:241], s[24:25], 0, v[130:131]
	ds_read_b128 v[178:181], v144 offset:32768
	ds_read_b128 v[182:185], v144 offset:33792
	ds_read_b128 v[186:189], v144 offset:34816
	ds_read_b128 v[190:193], v144 offset:35840
	ds_read_b128 v[196:199], v144 offset:36864
	ds_read_b128 v[200:203], v144 offset:37888
	ds_read_b128 v[206:209], v144 offset:38912
	ds_read_b128 v[210:213], v144 offset:39936
	global_load_lds_dwordx4 v[240:241], off
	v_lshl_add_u64 v[240:241], s[24:25], 0, v[134:135]
	s_mov_b32 m0, s36
	s_nop 0
	global_load_lds_dwordx4 v[240:241], off
	s_waitcnt vmcnt(8)
	s_waitcnt lgkmcnt(0)
	s_barrier
	s_setprio 1
	s_waitcnt lgkmcnt(0)
	v_mfma_f32_16x16x32_bf16 v[126:129], v[146:149], v[178:181], v[126:129]
	v_mfma_f32_16x16x32_bf16 v[122:125], v[154:157], v[178:181], v[122:125]
	v_mfma_f32_16x16x32_bf16 v[110:113], v[146:149], v[186:189], v[110:113]
	v_mfma_f32_16x16x32_bf16 v[106:109], v[154:157], v[186:189], v[106:109]
	v_mfma_f32_16x16x32_bf16 v[94:97], v[146:149], v[196:199], v[94:97]
	v_mfma_f32_16x16x32_bf16 v[90:93], v[154:157], v[196:199], v[90:93]
	v_mfma_f32_16x16x32_bf16 v[78:81], v[146:149], v[206:209], v[78:81]
	v_mfma_f32_16x16x32_bf16 v[74:77], v[154:157], v[206:209], v[74:77]
	v_mfma_f32_16x16x32_bf16 v[126:129], v[150:153], v[182:185], v[126:129]
	v_mfma_f32_16x16x32_bf16 v[122:125], v[158:161], v[182:185], v[122:125]
	v_mfma_f32_16x16x32_bf16 v[110:113], v[150:153], v[190:193], v[110:113]
	v_mfma_f32_16x16x32_bf16 v[106:109], v[158:161], v[190:193], v[106:109]
	v_mfma_f32_16x16x32_bf16 v[94:97], v[150:153], v[200:203], v[94:97]
	v_mfma_f32_16x16x32_bf16 v[90:93], v[158:161], v[200:203], v[90:93]
	v_mfma_f32_16x16x32_bf16 v[78:81], v[150:153], v[210:213], v[78:81]
	v_mfma_f32_16x16x32_bf16 v[74:77], v[158:161], v[210:213], v[74:77]
	s_setprio 0
	s_setprio 1
	v_mfma_f32_16x16x32_bf16 v[118:121], v[162:165], v[178:181], v[118:121]
	v_mfma_f32_16x16x32_bf16 v[114:117], v[170:173], v[178:181], v[114:117]
	v_mfma_f32_16x16x32_bf16 v[102:105], v[162:165], v[186:189], v[102:105]
	v_mfma_f32_16x16x32_bf16 v[98:101], v[170:173], v[186:189], v[98:101]
	v_mfma_f32_16x16x32_bf16 v[86:89], v[162:165], v[196:199], v[86:89]
	v_mfma_f32_16x16x32_bf16 v[82:85], v[170:173], v[196:199], v[82:85]
	v_mfma_f32_16x16x32_bf16 v[70:73], v[162:165], v[206:209], v[70:73]
	v_mfma_f32_16x16x32_bf16 v[66:69], v[170:173], v[206:209], v[66:69]
	v_mfma_f32_16x16x32_bf16 v[118:121], v[166:169], v[182:185], v[118:121]
	v_mfma_f32_16x16x32_bf16 v[114:117], v[174:177], v[182:185], v[114:117]
	v_mfma_f32_16x16x32_bf16 v[102:105], v[166:169], v[190:193], v[102:105]
	v_mfma_f32_16x16x32_bf16 v[98:101], v[174:177], v[190:193], v[98:101]
	v_mfma_f32_16x16x32_bf16 v[86:89], v[166:169], v[200:203], v[86:89]
	v_mfma_f32_16x16x32_bf16 v[82:85], v[174:177], v[200:203], v[82:85]
	v_mfma_f32_16x16x32_bf16 v[70:73], v[166:169], v[210:213], v[70:73]
	v_mfma_f32_16x16x32_bf16 v[66:69], v[174:177], v[210:213], v[66:69]
	s_setprio 0
	s_barrier
; #define PG8_STAGE(bufoff, gbase, voff) do { _Pragma("unroll") for (int _i = 0; _i < 2; ++_i) \
;         __builtin_amdgcn_global_load_lds((const unsigned*)((const char*)(gbase) + (voff)[_i]), (PG8_LAS unsigned*)(lds + (bufoff) + ldsw + _i * 8192), 16, 0, 0); } while (0)
; #define PG8_LDA(dst, b, h) do { _Pragma("unroll") for (int m = 0; m < 4; ++m) _Pragma("unroll") for (int k = 0; k < 2; ++k) dst[m][k] = *(const PG8_LAS bf16x8*)(lds + PG8_SA(b, h) + aoff + m * 2048 + k * 1024); } while (0)
; #define PG8_MMA(ai, bj, At, Bt) do { __builtin_amdgcn_s_setprio(1); _Pragma("unroll") for (int m = 0; m < 4; ++m) _Pragma("unroll") for (int n = 0; n < 2; ++n) _Pragma("unroll") for (int k = 0; k < 2; ++k) \
;         acc[ai][bj][m][n] = __builtin_amdgcn_mfma_f32_16x16x32_bf16(Bt[n][k], At[m][k], acc[ai][bj][m][n], 0, 0, 0); __builtin_amdgcn_s_setprio(0); } while (0)
; #define PG8_WAIT_V(n) asm volatile("s_waitcnt vmcnt(" #n ")" ::: "memory")
; #define PG8_WAIT_L(n) asm volatile("s_waitcnt lgkmcnt(" #n ")" ::: "memory")
; #define PG8_BAR __builtin_amdgcn_s_barrier()
; #define PG8_SCHED __builtin_amdgcn_sched_barrier(0)
; template <class Epi, class Sched, bool ALIGN_EPI = false, bool SP2 = false>
; __device__ __forceinline__ void gemm_phase(PG8_LAS unsigned char* lds, const Gemm g, const Sched& S, const Epi& E) {
;     ...
;             PG8_LDA(At, 1, 1); PG8_STAGE(PG8_SB(1, 0), b3, voffB); PG8_STAGE(PG8_SB(1, 1), b3 + hstep, voffB); PG8_STAGE(PG8_SA(1, 0), a3, voffA);
;             PG8_WAIT_V(8); PG8_WAIT_L(0); PG8_BAR; PG8_MMA(1, 0, At, B0); PG8_MMA(1, 1, At, B1); PG8_BAR; PG8_SCHED;
	s_add_i32 s24, s53, s28
	v_lshl_add_u64 v[214:215], v[214:215], 0, s[20:21]
	s_mov_b32 m0, s24
	ds_read_b128 v[178:181], v144 offset:49152
	ds_read_b128 v[182:185], v144 offset:50176
	ds_read_b128 v[186:189], v144 offset:51200
	ds_read_b128 v[190:193], v144 offset:52224
	ds_read_b128 v[196:199], v144 offset:53248
	ds_read_b128 v[200:203], v144 offset:54272
	ds_read_b128 v[206:209], v144 offset:55296
	ds_read_b128 v[210:213], v144 offset:56320
	global_load_lds_dwordx4 v[214:215], off
	v_lshl_add_u64 v[214:215], v[216:217], 0, s[20:21]
	s_add_i32 m0, s24, 0x2000
	s_add_i32 s24, s54, s28
	global_load_lds_dwordx4 v[214:215], off
	v_lshl_add_u64 v[214:215], v[218:219], 0, s[20:21]
	s_mov_b32 m0, s24
	s_nop 0
	global_load_lds_dwordx4 v[214:215], off
	v_lshl_add_u64 v[214:215], v[234:235], 0, s[20:21]
	s_add_i32 m0, s24, 0x2000
	s_nop 0
	global_load_lds_dwordx4 v[214:215], off
	v_lshl_add_u64 v[214:215], v[236:237], 0, s[20:21]
	s_mov_b32 m0, s40
	s_nop 0
	global_load_lds_dwordx4 v[214:215], off
	v_lshl_add_u64 v[214:215], v[238:239], 0, s[20:21]
	s_mov_b32 m0, s43
	s_nop 0
	global_load_lds_dwordx4 v[214:215], off
	s_waitcnt vmcnt(8)
	s_waitcnt lgkmcnt(0)
	s_barrier
	s_setprio 1
	s_waitcnt lgkmcnt(0)
	v_mfma_f32_16x16x32_bf16 v[62:65], v[146:149], v[178:181], v[62:65]
	v_mfma_f32_16x16x32_bf16 v[58:61], v[154:157], v[178:181], v[58:61]
	v_mfma_f32_16x16x32_bf16 v[46:49], v[146:149], v[186:189], v[46:49]
	v_mfma_f32_16x16x32_bf16 v[42:45], v[154:157], v[186:189], v[42:45]
	v_mfma_f32_16x16x32_bf16 v[30:33], v[146:149], v[196:199], v[30:33]
	v_mfma_f32_16x16x32_bf16 v[26:29], v[154:157], v[196:199], v[26:29]
	v_mfma_f32_16x16x32_bf16 v[14:17], v[146:149], v[206:209], v[14:17]
	v_mfma_f32_16x16x32_bf16 v[10:13], v[154:157], v[206:209], v[10:13]
	v_mfma_f32_16x16x32_bf16 v[62:65], v[150:153], v[182:185], v[62:65]
	v_mfma_f32_16x16x32_bf16 v[58:61], v[158:161], v[182:185], v[58:61]
	v_mfma_f32_16x16x32_bf16 v[46:49], v[150:153], v[190:193], v[46:49]
	v_mfma_f32_16x16x32_bf16 v[42:45], v[158:161], v[190:193], v[42:45]
	v_mfma_f32_16x16x32_bf16 v[30:33], v[150:153], v[200:203], v[30:33]
	v_mfma_f32_16x16x32_bf16 v[26:29], v[158:161], v[200:203], v[26:29]
	v_mfma_f32_16x16x32_bf16 v[14:17], v[150:153], v[210:213], v[14:17]
	v_mfma_f32_16x16x32_bf16 v[10:13], v[158:161], v[210:213], v[10:13]
	s_setprio 0
	s_setprio 1
	v_mfma_f32_16x16x32_bf16 v[54:57], v[162:165], v[178:181], v[54:57]
	v_mfma_f32_16x16x32_bf16 v[50:53], v[170:173], v[178:181], v[50:53]
	v_mfma_f32_16x16x32_bf16 v[38:41], v[162:165], v[186:189], v[38:41]
	v_mfma_f32_16x16x32_bf16 v[34:37], v[170:173], v[186:189], v[34:37]
	v_mfma_f32_16x16x32_bf16 v[22:25], v[162:165], v[196:199], v[22:25]
	v_mfma_f32_16x16x32_bf16 v[18:21], v[170:173], v[196:199], v[18:21]
	v_mfma_f32_16x16x32_bf16 v[6:9], v[162:165], v[206:209], v[6:9]
	v_mfma_f32_16x16x32_bf16 v[2:5], v[170:173], v[206:209], v[2:5]
	v_mfma_f32_16x16x32_bf16 v[54:57], v[166:169], v[182:185], v[54:57]
	v_mfma_f32_16x16x32_bf16 v[50:53], v[174:177], v[182:185], v[50:53]
	v_mfma_f32_16x16x32_bf16 v[38:41], v[166:169], v[190:193], v[38:41]
	v_mfma_f32_16x16x32_bf16 v[34:37], v[174:177], v[190:193], v[34:37]
	v_mfma_f32_16x16x32_bf16 v[22:25], v[166:169], v[200:203], v[22:25]
	v_mfma_f32_16x16x32_bf16 v[18:21], v[174:177], v[200:203], v[18:21]
	v_mfma_f32_16x16x32_bf16 v[6:9], v[166:169], v[210:213], v[6:9]
	v_mfma_f32_16x16x32_bf16 v[2:5], v[174:177], v[210:213], v[2:5]
	s_setprio 0
	s_barrier
	s_add_u32 s50, s50, 0x100
	s_addc_u32 s51, s51, 0
	s_add_u32 s18, s18, 0x100
	s_addc_u32 s19, s19, 0
	s_cmp_ge_i32 s52, s39
	s_mov_b32 s24, s52
	s_cbranch_scc0 .LBB0_1017
	s_mov_b32 s52, s64

; #define PG8_STAGE(bufoff, gbase, voff) do { _Pragma("unroll") for (int _i = 0; _i < 2; ++_i) \
;         __builtin_amdgcn_global_load_lds((const unsigned*)((const char*)(gbase) + (voff)[_i]), (PG8_LAS unsigned*)(lds + (bufoff) + ldsw + _i * 8192), 16, 0, 0); } while (0)
; #define PG8_LDA(dst, b, h) do { _Pragma("unroll") for (int m = 0; m < 4; ++m) _Pragma("unroll") for (int k = 0; k < 2; ++k) dst[m][k] = *(const PG8_LAS bf16x8*)(lds + PG8_SA(b, h) + aoff + m * 2048 + k * 1024); } while (0)
; #define PG8_LDB(dst, b, h) do { _Pragma("unroll") for (int n = 0; n < 2; ++n) _Pragma("unroll") for (int k = 0; k < 2; ++k) dst[n][k] = *(const PG8_LAS bf16x8*)(lds + PG8_SB(b, h) + boff + n * 2048 + k * 1024); } while (0)
; #define PG8_MMA(ai, bj, At, Bt) do { __builtin_amdgcn_s_setprio(1); _Pragma("unroll") for (int m = 0; m < 4; ++m) _Pragma("unroll") for (int n = 0; n < 2; ++n) _Pragma("unroll") for (int k = 0; k < 2; ++k) \
;         acc[ai][bj][m][n] = __builtin_amdgcn_mfma_f32_16x16x32_bf16(Bt[n][k], At[m][k], acc[ai][bj][m][n], 0, 0, 0); __builtin_amdgcn_s_setprio(0); } while (0)
; #define PG8_WAIT_V(n) asm volatile("s_waitcnt vmcnt(" #n ")" ::: "memory")
; #define PG8_BAR __builtin_amdgcn_s_barrier()
; template <class Epi, class Sched, bool ALIGN_EPI = false, bool SP2 = false>
; __device__ __forceinline__ void gemm_phase(PG8_LAS unsigned char* lds, const Gemm g, const Sched& S, const Epi& E) {
;     ...
;         for (int t = t0; t < t1; t += 2) {
;             const bool last = (t == nt - 2);
;             const char* a1 = cA + (size_t)(t + 1) * kstep;
;             const char* a2 = last ? nA : cA + (size_t)(t + 2) * kstep; const char* b2 = last ? nB : cB + (size_t)(t + 2) * kstep;
;             const char* a3 = a2 + kstep; const char* b3 = b2 + kstep;
;             if (last && has_next) S.a_ready(nxt);
;             if constexpr (SP2) {
;             PG8_LDB(B0, 0, 0); PG8_LDB(B1, 0, 1); PG8_SCHED; PG8_LDA(At, 0, 0); PG8_STAGE(PG8_SA(1, 1), a1 + hstep, voffA);
;             PG8_WAIT_V(8); PG8_WAIT_L(0); PG8_BAR; PG8_MMA(0, 0, At, B0); PG8_MMA(0, 1, At, B1); PG8_BAR; PG8_SCHED;
;     ...
; #pragma unroll
;         for (int a = 0; a < 2; ++a)
; #pragma unroll
;             for (int b = 0; b < 2; ++b)
; #pragma unroll
;                 for (int m = 0; m < 4; ++m)
; #pragma unroll
;                     for (int n = 0; n < 2; ++n) acc[a][b][m][n] = (f32x4){0.f, 0.f, 0.f, 0.f};
.LBB0_1121:
	v_mov_b32_e32 v131, 0
	s_andn2_b64 vcc, exec, s[24:25]
	v_mov_b32_e32 v130, v131
	v_mov_b32_e32 v129, v131
	v_mov_b32_e32 v128, v131
	v_mov_b32_e32 v127, v131
	v_mov_b32_e32 v126, v131
	v_mov_b32_e32 v125, v131
	v_mov_b32_e32 v124, v131
	v_mov_b32_e32 v115, v131
	v_mov_b32_e32 v114, v131
	v_mov_b32_e32 v113, v131
	v_mov_b32_e32 v112, v131
	v_mov_b32_e32 v111, v131
	v_mov_b32_e32 v110, v131
	v_mov_b32_e32 v109, v131
	v_mov_b32_e32 v108, v131
	v_mov_b32_e32 v99, v131
	v_mov_b32_e32 v98, v131
	v_mov_b32_e32 v97, v131
	v_mov_b32_e32 v96, v131
	v_mov_b32_e32 v95, v131
	v_mov_b32_e32 v94, v131
	v_mov_b32_e32 v93, v131
	v_mov_b32_e32 v92, v131
	v_mov_b32_e32 v83, v131
	v_mov_b32_e32 v82, v131
	v_mov_b32_e32 v81, v131
	v_mov_b32_e32 v80, v131
	v_mov_b32_e32 v79, v131
	v_mov_b32_e32 v78, v131
	v_mov_b32_e32 v77, v131
	v_mov_b32_e32 v76, v131
	v_mov_b32_e32 v123, v131
	v_mov_b32_e32 v122, v131
	v_mov_b32_e32 v121, v131
	v_mov_b32_e32 v120, v131
	v_mov_b32_e32 v119, v131
	v_mov_b32_e32 v118, v131
	v_mov_b32_e32 v117, v131
	v_mov_b32_e32 v116, v131
	v_mov_b32_e32 v107, v131
	v_mov_b32_e32 v106, v131
	v_mov_b32_e32 v105, v131
	v_mov_b32_e32 v104, v131
	v_mov_b32_e32 v103, v131
	v_mov_b32_e32 v102, v131
	v_mov_b32_e32 v101, v131
	v_mov_b32_e32 v100, v131
	v_mov_b32_e32 v91, v131
	v_mov_b32_e32 v90, v131
	v_mov_b32_e32 v89, v131
	v_mov_b32_e32 v88, v131
	v_mov_b32_e32 v87, v131
	v_mov_b32_e32 v86, v131
	v_mov_b32_e32 v85, v131
	v_mov_b32_e32 v84, v131
	v_mov_b32_e32 v75, v131
	v_mov_b32_e32 v74, v131
	v_mov_b32_e32 v73, v131
	v_mov_b32_e32 v72, v131
	v_mov_b32_e32 v71, v131
	v_mov_b32_e32 v70, v131
	v_mov_b32_e32 v69, v131
	v_mov_b32_e32 v68, v131
	v_mov_b32_e32 v67, v131
	v_mov_b32_e32 v66, v131
	v_mov_b32_e32 v65, v131
	v_mov_b32_e32 v64, v131
	v_mov_b32_e32 v63, v131
	v_mov_b32_e32 v62, v131
	v_mov_b32_e32 v61, v131
	v_mov_b32_e32 v60, v131
	v_mov_b32_e32 v51, v131
	v_mov_b32_e32 v50, v131
	v_mov_b32_e32 v49, v131
	v_mov_b32_e32 v48, v131
	v_mov_b32_e32 v47, v131
	v_mov_b32_e32 v46, v131
	v_mov_b32_e32 v45, v131
	v_mov_b32_e32 v44, v131
	v_mov_b32_e32 v35, v131
	v_mov_b32_e32 v34, v131
	v_mov_b32_e32 v33, v131
	v_mov_b32_e32 v32, v131
	v_mov_b32_e32 v31, v131
	v_mov_b32_e32 v30, v131
	v_mov_b32_e32 v29, v131
	v_mov_b32_e32 v28, v131
	v_mov_b32_e32 v19, v131
	v_mov_b32_e32 v18, v131
	v_mov_b32_e32 v17, v131
	v_mov_b32_e32 v16, v131
	v_mov_b32_e32 v15, v131
	v_mov_b32_e32 v14, v131
	v_mov_b32_e32 v13, v131
	v_mov_b32_e32 v12, v131
	v_mov_b32_e32 v59, v131
	v_mov_b32_e32 v58, v131
	v_mov_b32_e32 v57, v131
	v_mov_b32_e32 v56, v131
	v_mov_b32_e32 v55, v131
	v_mov_b32_e32 v54, v131
	v_mov_b32_e32 v53, v131
	v_mov_b32_e32 v52, v131
	v_mov_b32_e32 v43, v131
	v_mov_b32_e32 v42, v131
	v_mov_b32_e32 v41, v131
	v_mov_b32_e32 v40, v131
	v_mov_b32_e32 v39, v131
	v_mov_b32_e32 v38, v131
	v_mov_b32_e32 v37, v131
	v_mov_b32_e32 v36, v131
	v_mov_b32_e32 v27, v131
	v_mov_b32_e32 v26, v131
	v_mov_b32_e32 v25, v131
	v_mov_b32_e32 v24, v131
	v_mov_b32_e32 v23, v131
	v_mov_b32_e32 v22, v131
	v_mov_b32_e32 v21, v131
	v_mov_b32_e32 v20, v131
	v_mov_b32_e32 v11, v131
	v_mov_b32_e32 v10, v131
	v_mov_b32_e32 v9, v131
	v_mov_b32_e32 v8, v131
	v_mov_b32_e32 v7, v131
	v_mov_b32_e32 v6, v131
	v_mov_b32_e32 v5, v131
	v_mov_b32_e32 v4, v131
	s_cbranch_vccnz .LBB0_1125
	s_add_u32 s65, s4, 0x100
	s_addc_u32 s66, s5, 0
	s_add_u32 s2, s38, 0x80
	v_mov_b32_e32 v4, 0
	s_addc_u32 s3, s39, 0
	s_mov_b32 s4, 0
.LBB0_1123:
	s_add_i32 s38, s4, 2
	s_add_u32 s39, s2, 0x80
	s_addc_u32 s5, s3, 0
	s_add_i32 s67, 0, 0x10000
	s_cmp_eq_u32 s52, s4
	s_cselect_b32 s5, s35, s5
	s_cselect_b32 s4, s34, s39
	v_add_u32_e32 v1, s67, v202
	s_cselect_b32 s69, s37, s66
	s_cselect_b32 s68, s36, s65
	s_add_i32 s39, 0, 0x14000
	ds_read_b128 v[132:135], v1
	ds_read_b128 v[136:139], v1 offset:1024
	ds_read_b128 v[140:143], v1 offset:2048
	ds_read_b128 v[144:147], v1 offset:3072
	v_add_u32_e32 v1, s39, v202
	ds_read_b128 v[148:151], v1
	ds_read_b128 v[152:155], v1 offset:1024
	ds_read_b128 v[156:159], v1 offset:2048
	ds_read_b128 v[160:163], v1 offset:3072
	v_lshl_add_u64 v[2:3], s[2:3], 0, v[190:191]
	s_add_i32 m0, s45, 0xc000
	ds_read_b128 v[164:167], v204
	ds_read_b128 v[168:171], v204 offset:1024
	ds_read_b128 v[172:175], v204 offset:2048
	ds_read_b128 v[176:179], v204 offset:3072
	ds_read_b128 v[196:199], v204 offset:4096
	ds_read_b128 v[206:209], v204 offset:5120
	ds_read_b128 v[210:213], v204 offset:6144
	ds_read_b128 v[214:217], v204 offset:7168
	global_load_lds_dwordx4 v[2:3], off
	v_lshl_add_u64 v[2:3], s[2:3], 0, v[188:189]
	s_add_i32 m0, s45, 0xe000
	s_nop 0
	global_load_lds_dwordx4 v[2:3], off
	s_waitcnt vmcnt(8)
	s_waitcnt lgkmcnt(0)
	s_barrier
; #define PG8_STAGE(bufoff, gbase, voff) do { _Pragma("unroll") for (int _i = 0; _i < 2; ++_i) \
;         __builtin_amdgcn_global_load_lds((const unsigned*)((const char*)(gbase) + (voff)[_i]), (PG8_LAS unsigned*)(lds + (bufoff) + ldsw + _i * 8192), 16, 0, 0); } while (0)
; #define PG8_LDA(dst, b, h) do { _Pragma("unroll") for (int m = 0; m < 4; ++m) _Pragma("unroll") for (int k = 0; k < 2; ++k) dst[m][k] = *(const PG8_LAS bf16x8*)(lds + PG8_SA(b, h) + aoff + m * 2048 + k * 1024); } while (0)
; #define PG8_MMA(ai, bj, At, Bt) do { __builtin_amdgcn_s_setprio(1); _Pragma("unroll") for (int m = 0; m < 4; ++m) _Pragma("unroll") for (int n = 0; n < 2; ++n) _Pragma("unroll") for (int k = 0; k < 2; ++k) \
;         acc[ai][bj][m][n] = __builtin_amdgcn_mfma_f32_16x16x32_bf16(Bt[n][k], At[m][k], acc[ai][bj][m][n], 0, 0, 0); __builtin_amdgcn_s_setprio(0); } while (0)
; #define PG8_WAIT_V(n) asm volatile("s_waitcnt vmcnt(" #n ")" ::: "memory")
; #define PG8_WAIT_L(n) asm volatile("s_waitcnt lgkmcnt(" #n ")" ::: "memory")
; #define PG8_BAR __builtin_amdgcn_s_barrier()
; #define PG8_SCHED __builtin_amdgcn_sched_barrier(0)
; template <class Epi, class Sched, bool ALIGN_EPI = false, bool SP2 = false>
; __device__ __forceinline__ void gemm_phase(PG8_LAS unsigned char* lds, const Gemm g, const Sched& S, const Epi& E) {
;     ...
;             PG8_WAIT_V(8); PG8_WAIT_L(0); PG8_BAR; PG8_MMA(0, 0, At, B0); PG8_MMA(0, 1, At, B1); PG8_BAR; PG8_SCHED;
;             PG8_LDA(At, 0, 1); PG8_STAGE(PG8_SB(0, 0), b2, voffB); PG8_STAGE(PG8_SB(0, 1), b2 + hstep, voffB); PG8_STAGE(PG8_SA(0, 0), a2, voffA);
;             PG8_WAIT_V(8); PG8_WAIT_L(0); PG8_BAR; PG8_MMA(1, 0, At, B0); PG8_MMA(1, 1, At, B1); PG8_BAR; PG8_SCHED;
	s_setprio 1
	s_waitcnt lgkmcnt(0)
	v_mfma_f32_16x16x32_bf16 v[128:131], v[132:135], v[164:167], v[128:131]
	v_mfma_f32_16x16x32_bf16 v[124:127], v[140:143], v[164:167], v[124:127]
	v_mfma_f32_16x16x32_bf16 v[112:115], v[132:135], v[172:175], v[112:115]
	v_mfma_f32_16x16x32_bf16 v[108:111], v[140:143], v[172:175], v[108:111]
	v_mfma_f32_16x16x32_bf16 v[96:99], v[132:135], v[196:199], v[96:99]
	v_mfma_f32_16x16x32_bf16 v[92:95], v[140:143], v[196:199], v[92:95]
	v_mfma_f32_16x16x32_bf16 v[80:83], v[132:135], v[210:213], v[80:83]
	v_mfma_f32_16x16x32_bf16 v[76:79], v[140:143], v[210:213], v[76:79]
	v_mfma_f32_16x16x32_bf16 v[128:131], v[136:139], v[168:171], v[128:131]
	v_mfma_f32_16x16x32_bf16 v[124:127], v[144:147], v[168:171], v[124:127]
	v_mfma_f32_16x16x32_bf16 v[112:115], v[136:139], v[176:179], v[112:115]
	v_mfma_f32_16x16x32_bf16 v[108:111], v[144:147], v[176:179], v[108:111]
	v_mfma_f32_16x16x32_bf16 v[96:99], v[136:139], v[206:209], v[96:99]
	v_mfma_f32_16x16x32_bf16 v[92:95], v[144:147], v[206:209], v[92:95]
	v_mfma_f32_16x16x32_bf16 v[80:83], v[136:139], v[214:217], v[80:83]
	v_mfma_f32_16x16x32_bf16 v[76:79], v[144:147], v[214:217], v[76:79]
	s_setprio 0
	s_setprio 1
	v_mfma_f32_16x16x32_bf16 v[120:123], v[148:151], v[164:167], v[120:123]
	v_mfma_f32_16x16x32_bf16 v[116:119], v[156:159], v[164:167], v[116:119]
	v_mfma_f32_16x16x32_bf16 v[104:107], v[148:151], v[172:175], v[104:107]
	v_mfma_f32_16x16x32_bf16 v[100:103], v[156:159], v[172:175], v[100:103]
	v_mfma_f32_16x16x32_bf16 v[88:91], v[148:151], v[196:199], v[88:91]
	v_mfma_f32_16x16x32_bf16 v[84:87], v[156:159], v[196:199], v[84:87]
	v_mfma_f32_16x16x32_bf16 v[72:75], v[148:151], v[210:213], v[72:75]
	v_mfma_f32_16x16x32_bf16 v[68:71], v[156:159], v[210:213], v[68:71]
	v_mfma_f32_16x16x32_bf16 v[120:123], v[152:155], v[168:171], v[120:123]
	v_mfma_f32_16x16x32_bf16 v[116:119], v[160:163], v[168:171], v[116:119]
	v_mfma_f32_16x16x32_bf16 v[104:107], v[152:155], v[176:179], v[104:107]
	v_mfma_f32_16x16x32_bf16 v[100:103], v[160:163], v[176:179], v[100:103]
	v_mfma_f32_16x16x32_bf16 v[88:91], v[152:155], v[206:209], v[88:91]
	v_mfma_f32_16x16x32_bf16 v[84:87], v[160:163], v[206:209], v[84:87]
	v_mfma_f32_16x16x32_bf16 v[72:75], v[152:155], v[214:217], v[72:75]
	v_mfma_f32_16x16x32_bf16 v[68:71], v[160:163], v[214:217], v[68:71]
	s_setprio 0
	s_barrier
	s_add_i32 s67, s67, s40
	v_lshl_add_u64 v[192:193], s[68:69], 0, v[182:183]
	s_mov_b32 m0, s67
	ds_read_b128 v[164:167], v204 offset:16384
	ds_read_b128 v[168:171], v204 offset:17408
	ds_read_b128 v[172:175], v204 offset:18432
	ds_read_b128 v[176:179], v204 offset:19456
	ds_read_b128 v[196:199], v204 offset:20480
	ds_read_b128 v[206:209], v204 offset:21504
	ds_read_b128 v[210:213], v204 offset:22528
	ds_read_b128 v[214:217], v204 offset:23552
	global_load_lds_dwordx4 v[192:193], off
	s_add_i32 m0, s67, 0x2000
	v_lshl_add_u64 v[200:201], s[68:69], 0, v[186:187]
	s_add_u32 s68, s68, s10
	s_addc_u32 s69, s69, s11
	s_add_i32 s39, s39, s40
	global_load_lds_dwordx4 v[200:201], off
	v_lshl_add_u64 v[218:219], s[68:69], 0, v[182:183]
	s_mov_b32 m0, s39
	v_lshl_add_u64 v[220:221], s[68:69], 0, v[186:187]
	global_load_lds_dwordx4 v[218:219], off
	s_add_i32 m0, s39, 0x2000
	v_lshl_add_u64 v[228:229], s[4:5], 0, v[180:181]
	global_load_lds_dwordx4 v[220:221], off
	s_mov_b32 m0, s45
	v_lshl_add_u64 v[234:235], s[4:5], 0, v[184:185]
	global_load_lds_dwordx4 v[228:229], off
	s_mov_b32 m0, s46
	s_nop 0
	global_load_lds_dwordx4 v[234:235], off
	s_waitcnt vmcnt(8)
	s_waitcnt lgkmcnt(0)
	s_barrier
	s_setprio 1
	s_waitcnt lgkmcnt(0)
	v_mfma_f32_16x16x32_bf16 v[64:67], v[132:135], v[164:167], v[64:67]
	v_mfma_f32_16x16x32_bf16 v[60:63], v[140:143], v[164:167], v[60:63]
	v_mfma_f32_16x16x32_bf16 v[48:51], v[132:135], v[172:175], v[48:51]
	v_mfma_f32_16x16x32_bf16 v[44:47], v[140:143], v[172:175], v[44:47]
	v_mfma_f32_16x16x32_bf16 v[32:35], v[132:135], v[196:199], v[32:35]
	v_mfma_f32_16x16x32_bf16 v[28:31], v[140:143], v[196:199], v[28:31]
	v_mfma_f32_16x16x32_bf16 v[16:19], v[132:135], v[210:213], v[16:19]
	v_mfma_f32_16x16x32_bf16 v[12:15], v[140:143], v[210:213], v[12:15]
	v_mfma_f32_16x16x32_bf16 v[64:67], v[136:139], v[168:171], v[64:67]
	v_mfma_f32_16x16x32_bf16 v[60:63], v[144:147], v[168:171], v[60:63]
	v_mfma_f32_16x16x32_bf16 v[48:51], v[136:139], v[176:179], v[48:51]
	v_mfma_f32_16x16x32_bf16 v[44:47], v[144:147], v[176:179], v[44:47]
	v_mfma_f32_16x16x32_bf16 v[32:35], v[136:139], v[206:209], v[32:35]
	v_mfma_f32_16x16x32_bf16 v[28:31], v[144:147], v[206:209], v[28:31]
	v_mfma_f32_16x16x32_bf16 v[16:19], v[136:139], v[214:217], v[16:19]
	v_mfma_f32_16x16x32_bf16 v[12:15], v[144:147], v[214:217], v[12:15]
	s_setprio 0
	s_setprio 1
	v_mfma_f32_16x16x32_bf16 v[56:59], v[148:151], v[164:167], v[56:59]
	v_mfma_f32_16x16x32_bf16 v[52:55], v[156:159], v[164:167], v[52:55]
	v_mfma_f32_16x16x32_bf16 v[40:43], v[148:151], v[172:175], v[40:43]
	v_mfma_f32_16x16x32_bf16 v[36:39], v[156:159], v[172:175], v[36:39]
	v_mfma_f32_16x16x32_bf16 v[24:27], v[148:151], v[196:199], v[24:27]
	v_mfma_f32_16x16x32_bf16 v[20:23], v[156:159], v[196:199], v[20:23]
	v_mfma_f32_16x16x32_bf16 v[8:11], v[148:151], v[210:213], v[8:11]
	v_mfma_f32_16x16x32_bf16 v[2:5], v[156:159], v[210:213], v[4:7]
	v_mfma_f32_16x16x32_bf16 v[56:59], v[152:155], v[168:171], v[56:59]
	v_mfma_f32_16x16x32_bf16 v[52:55], v[160:163], v[168:171], v[52:55]
	v_mfma_f32_16x16x32_bf16 v[40:43], v[152:155], v[176:179], v[40:43]
	v_mfma_f32_16x16x32_bf16 v[36:39], v[160:163], v[176:179], v[36:39]
	v_mfma_f32_16x16x32_bf16 v[24:27], v[152:155], v[206:209], v[24:27]
	v_mfma_f32_16x16x32_bf16 v[20:23], v[160:163], v[206:209], v[20:23]
	v_mfma_f32_16x16x32_bf16 v[8:11], v[152:155], v[214:217], v[8:11]
	v_mfma_f32_16x16x32_bf16 v[2:5], v[160:163], v[214:217], v[2:5]
	s_setprio 0
	s_barrier
; #define PG8_STAGE(bufoff, gbase, voff) do { _Pragma("unroll") for (int _i = 0; _i < 2; ++_i) \
;         __builtin_amdgcn_global_load_lds((const unsigned*)((const char*)(gbase) + (voff)[_i]), (PG8_LAS unsigned*)(lds + (bufoff) + ldsw + _i * 8192), 16, 0, 0); } while (0)
; #define PG8_LDA(dst, b, h) do { _Pragma("unroll") for (int m = 0; m < 4; ++m) _Pragma("unroll") for (int k = 0; k < 2; ++k) dst[m][k] = *(const PG8_LAS bf16x8*)(lds + PG8_SA(b, h) + aoff + m * 2048 + k * 1024); } while (0)
; #define PG8_LDB(dst, b, h) do { _Pragma("unroll") for (int n = 0; n < 2; ++n) _Pragma("unroll") for (int k = 0; k < 2; ++k) dst[n][k] = *(const PG8_LAS bf16x8*)(lds + PG8_SB(b, h) + boff + n * 2048 + k * 1024); } while (0)
; #define PG8_MMA(ai, bj, At, Bt) do { __builtin_amdgcn_s_setprio(1); _Pragma("unroll") for (int m = 0; m < 4; ++m) _Pragma("unroll") for (int n = 0; n < 2; ++n) _Pragma("unroll") for (int k = 0; k < 2; ++k) \
;         acc[ai][bj][m][n] = __builtin_amdgcn_mfma_f32_16x16x32_bf16(Bt[n][k], At[m][k], acc[ai][bj][m][n], 0, 0, 0); __builtin_amdgcn_s_setprio(0); } while (0)
; #define PG8_WAIT_V(n) asm volatile("s_waitcnt vmcnt(" #n ")" ::: "memory")
; #define PG8_WAIT_L(n) asm volatile("s_waitcnt lgkmcnt(" #n ")" ::: "memory")
; #define PG8_BAR __builtin_amdgcn_s_barrier()
; #define PG8_SCHED __builtin_amdgcn_sched_barrier(0)
; template <class Epi, class Sched, bool ALIGN_EPI = false, bool SP2 = false>
; __device__ __forceinline__ void gemm_phase(PG8_LAS unsigned char* lds, const Gemm g, const Sched& S, const Epi& E) {
;     ...
;             PG8_LDB(B0, 1, 0); PG8_LDB(B1, 1, 1); PG8_SCHED; PG8_LDA(At, 1, 0); PG8_STAGE(PG8_SA(0, 1), a2 + hstep, voffA);
;             PG8_WAIT_V(8); PG8_WAIT_L(0); PG8_BAR; PG8_MMA(0, 0, At, B0); PG8_MMA(0, 1, At, B1); PG8_BAR; PG8_SCHED;
	s_add_i32 s39, 0, 0x18000
	v_add_u32_e32 v1, s39, v202
	s_add_i32 s67, 0, 0x1c000
	ds_read_b128 v[132:135], v1
	ds_read_b128 v[136:139], v1 offset:1024
	ds_read_b128 v[140:143], v1 offset:2048
	ds_read_b128 v[144:147], v1 offset:3072
	v_add_u32_e32 v1, s67, v202
	ds_read_b128 v[148:151], v1
	ds_read_b128 v[152:155], v1 offset:1024
	ds_read_b128 v[156:159], v1 offset:2048
	ds_read_b128 v[160:163], v1 offset:3072
	s_add_u32 s4, s4, s10
	s_addc_u32 s5, s5, s11
	s_mov_b32 m0, s47
	v_lshl_add_u64 v[6:7], s[4:5], 0, v[180:181]
	ds_read_b128 v[164:167], v204 offset:32768
	ds_read_b128 v[168:171], v204 offset:33792
	ds_read_b128 v[172:175], v204 offset:34816
	ds_read_b128 v[176:179], v204 offset:35840
	ds_read_b128 v[196:199], v204 offset:36864
	ds_read_b128 v[206:209], v204 offset:37888
	ds_read_b128 v[210:213], v204 offset:38912
	ds_read_b128 v[214:217], v204 offset:39936
	global_load_lds_dwordx4 v[6:7], off
	v_lshl_add_u64 v[6:7], s[4:5], 0, v[184:185]
	s_mov_b32 m0, s48
	s_nop 0
	global_load_lds_dwordx4 v[6:7], off
	s_waitcnt vmcnt(8)
	s_waitcnt lgkmcnt(0)
	s_barrier
	s_setprio 1
	s_waitcnt lgkmcnt(0)
	v_mfma_f32_16x16x32_bf16 v[128:131], v[132:135], v[164:167], v[128:131]
	v_mfma_f32_16x16x32_bf16 v[124:127], v[140:143], v[164:167], v[124:127]
	v_mfma_f32_16x16x32_bf16 v[112:115], v[132:135], v[172:175], v[112:115]
	v_mfma_f32_16x16x32_bf16 v[108:111], v[140:143], v[172:175], v[108:111]
	v_mfma_f32_16x16x32_bf16 v[96:99], v[132:135], v[196:199], v[96:99]
	v_mfma_f32_16x16x32_bf16 v[92:95], v[140:143], v[196:199], v[92:95]
	v_mfma_f32_16x16x32_bf16 v[80:83], v[132:135], v[210:213], v[80:83]
	v_mfma_f32_16x16x32_bf16 v[76:79], v[140:143], v[210:213], v[76:79]
	v_mfma_f32_16x16x32_bf16 v[128:131], v[136:139], v[168:171], v[128:131]
	v_mfma_f32_16x16x32_bf16 v[124:127], v[144:147], v[168:171], v[124:127]
	v_mfma_f32_16x16x32_bf16 v[112:115], v[136:139], v[176:179], v[112:115]
	v_mfma_f32_16x16x32_bf16 v[108:111], v[144:147], v[176:179], v[108:111]
	v_mfma_f32_16x16x32_bf16 v[96:99], v[136:139], v[206:209], v[96:99]
	v_mfma_f32_16x16x32_bf16 v[92:95], v[144:147], v[206:209], v[92:95]
	v_mfma_f32_16x16x32_bf16 v[80:83], v[136:139], v[214:217], v[80:83]
	v_mfma_f32_16x16x32_bf16 v[76:79], v[144:147], v[214:217], v[76:79]
	s_setprio 0
	s_setprio 1
	v_mfma_f32_16x16x32_bf16 v[120:123], v[148:151], v[164:167], v[120:123]
	v_mfma_f32_16x16x32_bf16 v[116:119], v[156:159], v[164:167], v[116:119]
	v_mfma_f32_16x16x32_bf16 v[104:107], v[148:151], v[172:175], v[104:107]
	v_mfma_f32_16x16x32_bf16 v[100:103], v[156:159], v[172:175], v[100:103]
	v_mfma_f32_16x16x32_bf16 v[88:91], v[148:151], v[196:199], v[88:91]
	v_mfma_f32_16x16x32_bf16 v[84:87], v[156:159], v[196:199], v[84:87]
	v_mfma_f32_16x16x32_bf16 v[72:75], v[148:151], v[210:213], v[72:75]
	v_mfma_f32_16x16x32_bf16 v[68:71], v[156:159], v[210:213], v[68:71]
	v_mfma_f32_16x16x32_bf16 v[120:123], v[152:155], v[168:171], v[120:123]
	v_mfma_f32_16x16x32_bf16 v[116:119], v[160:163], v[168:171], v[116:119]
	v_mfma_f32_16x16x32_bf16 v[104:107], v[152:155], v[176:179], v[104:107]
	v_mfma_f32_16x16x32_bf16 v[100:103], v[160:163], v[176:179], v[100:103]
	v_mfma_f32_16x16x32_bf16 v[88:91], v[152:155], v[206:209], v[88:91]
	v_mfma_f32_16x16x32_bf16 v[84:87], v[160:163], v[206:209], v[84:87]
	v_mfma_f32_16x16x32_bf16 v[72:75], v[152:155], v[214:217], v[72:75]
	v_mfma_f32_16x16x32_bf16 v[68:71], v[160:163], v[214:217], v[68:71]
	s_setprio 0
	s_barrier
; #define PG8_STAGE(bufoff, gbase, voff) do { _Pragma("unroll") for (int _i = 0; _i < 2; ++_i) \
;         __builtin_amdgcn_global_load_lds((const unsigned*)((const char*)(gbase) + (voff)[_i]), (PG8_LAS unsigned*)(lds + (bufoff) + ldsw + _i * 8192), 16, 0, 0); } while (0)
; #define PG8_LDA(dst, b, h) do { _Pragma("unroll") for (int m = 0; m < 4; ++m) _Pragma("unroll") for (int k = 0; k < 2; ++k) dst[m][k] = *(const PG8_LAS bf16x8*)(lds + PG8_SA(b, h) + aoff + m * 2048 + k * 1024); } while (0)
; #define PG8_MMA(ai, bj, At, Bt) do { __builtin_amdgcn_s_setprio(1); _Pragma("unroll") for (int m = 0; m < 4; ++m) _Pragma("unroll") for (int n = 0; n < 2; ++n) _Pragma("unroll") for (int k = 0; k < 2; ++k) \
;         acc[ai][bj][m][n] = __builtin_amdgcn_mfma_f32_16x16x32_bf16(Bt[n][k], At[m][k], acc[ai][bj][m][n], 0, 0, 0); __builtin_amdgcn_s_setprio(0); } while (0)
; #define PG8_WAIT_V(n) asm volatile("s_waitcnt vmcnt(" #n ")" ::: "memory")
; #define PG8_WAIT_L(n) asm volatile("s_waitcnt lgkmcnt(" #n ")" ::: "memory")
; #define PG8_BAR __builtin_amdgcn_s_barrier()
; #define PG8_SCHED __builtin_amdgcn_sched_barrier(0)
; template <class Epi, class Sched, bool ALIGN_EPI = false, bool SP2 = false>
; __device__ __forceinline__ void gemm_phase(PG8_LAS unsigned char* lds, const Gemm g, const Sched& S, const Epi& E) {
;     ...
;             PG8_LDA(At, 1, 1); PG8_STAGE(PG8_SB(1, 0), b3, voffB); PG8_STAGE(PG8_SB(1, 1), b3 + hstep, voffB); PG8_STAGE(PG8_SA(1, 0), a3, voffA);
;             PG8_WAIT_V(8); PG8_WAIT_L(0); PG8_BAR; PG8_MMA(1, 0, At, B0); PG8_MMA(1, 1, At, B1); PG8_BAR; PG8_SCHED;
	s_add_i32 s4, s39, s40
	v_lshl_add_u64 v[6:7], v[192:193], 0, s[20:21]
	s_mov_b32 m0, s4
	ds_read_b128 v[164:167], v204 offset:49152
	ds_read_b128 v[168:171], v204 offset:50176
	ds_read_b128 v[172:175], v204 offset:51200
	ds_read_b128 v[176:179], v204 offset:52224
	ds_read_b128 v[196:199], v204 offset:53248
	ds_read_b128 v[206:209], v204 offset:54272
	ds_read_b128 v[210:213], v204 offset:55296
	ds_read_b128 v[214:217], v204 offset:56320
	global_load_lds_dwordx4 v[6:7], off
	v_lshl_add_u64 v[6:7], v[200:201], 0, s[20:21]
	s_add_i32 m0, s4, 0x2000
	s_add_i32 s4, s67, s40
	global_load_lds_dwordx4 v[6:7], off
	v_lshl_add_u64 v[6:7], v[218:219], 0, s[20:21]
	s_mov_b32 m0, s4
	s_nop 0
	global_load_lds_dwordx4 v[6:7], off
	v_lshl_add_u64 v[6:7], v[220:221], 0, s[20:21]
	s_add_i32 m0, s4, 0x2000
	s_nop 0
	global_load_lds_dwordx4 v[6:7], off
	v_lshl_add_u64 v[6:7], v[228:229], 0, s[20:21]
	s_mov_b32 m0, s50
	s_nop 0
	global_load_lds_dwordx4 v[6:7], off
	v_lshl_add_u64 v[6:7], v[234:235], 0, s[20:21]
	s_mov_b32 m0, s51
	s_nop 0
	global_load_lds_dwordx4 v[6:7], off
	s_waitcnt vmcnt(8)
	s_waitcnt lgkmcnt(0)
	s_barrier
	s_setprio 1
	s_waitcnt lgkmcnt(0)
	v_mfma_f32_16x16x32_bf16 v[64:67], v[132:135], v[164:167], v[64:67]
	v_mfma_f32_16x16x32_bf16 v[60:63], v[140:143], v[164:167], v[60:63]
	v_mfma_f32_16x16x32_bf16 v[48:51], v[132:135], v[172:175], v[48:51]
	v_mfma_f32_16x16x32_bf16 v[44:47], v[140:143], v[172:175], v[44:47]
	v_mfma_f32_16x16x32_bf16 v[32:35], v[132:135], v[196:199], v[32:35]
	v_mfma_f32_16x16x32_bf16 v[28:31], v[140:143], v[196:199], v[28:31]
	v_mfma_f32_16x16x32_bf16 v[16:19], v[132:135], v[210:213], v[16:19]
	v_mfma_f32_16x16x32_bf16 v[12:15], v[140:143], v[210:213], v[12:15]
	v_mfma_f32_16x16x32_bf16 v[64:67], v[136:139], v[168:171], v[64:67]
	v_mfma_f32_16x16x32_bf16 v[60:63], v[144:147], v[168:171], v[60:63]
	v_mfma_f32_16x16x32_bf16 v[48:51], v[136:139], v[176:179], v[48:51]
	v_mfma_f32_16x16x32_bf16 v[44:47], v[144:147], v[176:179], v[44:47]
	v_mfma_f32_16x16x32_bf16 v[32:35], v[136:139], v[206:209], v[32:35]
	v_mfma_f32_16x16x32_bf16 v[28:31], v[144:147], v[206:209], v[28:31]
	v_mfma_f32_16x16x32_bf16 v[16:19], v[136:139], v[214:217], v[16:19]
	v_mfma_f32_16x16x32_bf16 v[12:15], v[144:147], v[214:217], v[12:15]
	s_setprio 0
	s_setprio 1
	v_mfma_f32_16x16x32_bf16 v[56:59], v[148:151], v[164:167], v[56:59]
	v_mfma_f32_16x16x32_bf16 v[52:55], v[156:159], v[164:167], v[52:55]
	v_mfma_f32_16x16x32_bf16 v[40:43], v[148:151], v[172:175], v[40:43]
	v_mfma_f32_16x16x32_bf16 v[36:39], v[156:159], v[172:175], v[36:39]
	v_mfma_f32_16x16x32_bf16 v[24:27], v[148:151], v[196:199], v[24:27]
	v_mfma_f32_16x16x32_bf16 v[20:23], v[156:159], v[196:199], v[20:23]
	v_mfma_f32_16x16x32_bf16 v[6:9], v[148:151], v[210:213], v[8:11]
	v_mfma_f32_16x16x32_bf16 v[2:5], v[156:159], v[210:213], v[2:5]
	v_mfma_f32_16x16x32_bf16 v[56:59], v[152:155], v[168:171], v[56:59]
	v_mfma_f32_16x16x32_bf16 v[52:55], v[160:163], v[168:171], v[52:55]
	v_mfma_f32_16x16x32_bf16 v[40:43], v[152:155], v[176:179], v[40:43]
	v_mfma_f32_16x16x32_bf16 v[36:39], v[160:163], v[176:179], v[36:39]
	v_mfma_f32_16x16x32_bf16 v[24:27], v[152:155], v[206:209], v[24:27]
	v_mfma_f32_16x16x32_bf16 v[20:23], v[160:163], v[206:209], v[20:23]
	v_mfma_f32_16x16x32_bf16 v[8:11], v[152:155], v[214:217], v[6:9]
	v_mfma_f32_16x16x32_bf16 v[4:7], v[160:163], v[214:217], v[2:5]
	s_setprio 0
	s_barrier
	s_add_u32 s65, s65, 0x100
	s_addc_u32 s66, s66, 0
	s_add_u32 s2, s2, 0x100
	s_addc_u32 s3, s3, 0
	s_cmp_ge_i32 s38, s49
	s_mov_b32 s4, s38
	s_cbranch_scc0 .LBB0_1123
	s_mov_b32 s68, 0x8000
	s_mov_b32 s69, 0x9000

; #define PG8_STAGE(bufoff, gbase, voff) do { _Pragma("unroll") for (int _i = 0; _i < 2; ++_i) \
;         __builtin_amdgcn_global_load_lds((const unsigned*)((const char*)(gbase) + (voff)[_i]), (PG8_LAS unsigned*)(lds + (bufoff) + ldsw + _i * 8192), 16, 0, 0); } while (0)
; #define PG8_LDA(dst, b, h) do { _Pragma("unroll") for (int m = 0; m < 4; ++m) _Pragma("unroll") for (int k = 0; k < 2; ++k) dst[m][k] = *(const PG8_LAS bf16x8*)(lds + PG8_SA(b, h) + aoff + m * 2048 + k * 1024); } while (0)
; #define PG8_LDB(dst, b, h) do { _Pragma("unroll") for (int n = 0; n < 2; ++n) _Pragma("unroll") for (int k = 0; k < 2; ++k) dst[n][k] = *(const PG8_LAS bf16x8*)(lds + PG8_SB(b, h) + boff + n * 2048 + k * 1024); } while (0)
; #define PG8_MMA(ai, bj, At, Bt) do { __builtin_amdgcn_s_setprio(1); _Pragma("unroll") for (int m = 0; m < 4; ++m) _Pragma("unroll") for (int n = 0; n < 2; ++n) _Pragma("unroll") for (int k = 0; k < 2; ++k) \
;         acc[ai][bj][m][n] = __builtin_amdgcn_mfma_f32_16x16x32_bf16(Bt[n][k], At[m][k], acc[ai][bj][m][n], 0, 0, 0); __builtin_amdgcn_s_setprio(0); } while (0)
; #define PG8_WAIT_V(n) asm volatile("s_waitcnt vmcnt(" #n ")" ::: "memory")
; #define PG8_BAR __builtin_amdgcn_s_barrier()
; template <class Epi, class Sched, bool ALIGN_EPI = false, bool SP2 = false>
; __device__ __forceinline__ void gemm_phase(PG8_LAS unsigned char* lds, const Gemm g, const Sched& S, const Epi& E) {
;     ...
;         for (int t = t0; t < t1; t += 2) {
;             const bool last = (t == nt - 2);
;             const char* a1 = cA + (size_t)(t + 1) * kstep;
;             const char* a2 = last ? nA : cA + (size_t)(t + 2) * kstep; const char* b2 = last ? nB : cB + (size_t)(t + 2) * kstep;
;             const char* a3 = a2 + kstep; const char* b3 = b2 + kstep;
;             if (last && has_next) S.a_ready(nxt);
;             if constexpr (SP2) {
;             PG8_LDB(B0, 0, 0); PG8_LDB(B1, 0, 1); PG8_SCHED; PG8_LDA(At, 0, 0); PG8_STAGE(PG8_SA(1, 1), a1 + hstep, voffA);
;             PG8_WAIT_V(8); PG8_WAIT_L(0); PG8_BAR; PG8_MMA(0, 0, At, B0); PG8_MMA(0, 1, At, B1); PG8_BAR; PG8_SCHED;
;     ...
; #pragma unroll
;         for (int a = 0; a < 2; ++a)
; #pragma unroll
;             for (int b = 0; b < 2; ++b)
; #pragma unroll
;                 for (int m = 0; m < 4; ++m)
; #pragma unroll
;                     for (int n = 0; n < 2; ++n) acc[a][b][m][n] = (f32x4){0.f, 0.f, 0.f, 0.f};
.LBB0_1369:
	v_mov_b32_e32 v129, 0
	s_andn2_b64 vcc, exec, s[18:19]
	v_mov_b32_e32 v128, v129
	v_mov_b32_e32 v127, v129
	v_mov_b32_e32 v126, v129
	v_mov_b32_e32 v125, v129
	v_mov_b32_e32 v124, v129
	v_mov_b32_e32 v123, v129
	v_mov_b32_e32 v122, v129
	v_mov_b32_e32 v113, v129
	v_mov_b32_e32 v112, v129
	v_mov_b32_e32 v111, v129
	v_mov_b32_e32 v110, v129
	v_mov_b32_e32 v109, v129
	v_mov_b32_e32 v108, v129
	v_mov_b32_e32 v107, v129
	v_mov_b32_e32 v106, v129
	v_mov_b32_e32 v97, v129
	v_mov_b32_e32 v96, v129
	v_mov_b32_e32 v95, v129
	v_mov_b32_e32 v94, v129
	v_mov_b32_e32 v93, v129
	v_mov_b32_e32 v92, v129
	v_mov_b32_e32 v91, v129
	v_mov_b32_e32 v90, v129
	v_mov_b32_e32 v81, v129
	v_mov_b32_e32 v80, v129
	v_mov_b32_e32 v79, v129
	v_mov_b32_e32 v78, v129
	v_mov_b32_e32 v77, v129
	v_mov_b32_e32 v76, v129
	v_mov_b32_e32 v75, v129
	v_mov_b32_e32 v74, v129
	v_mov_b32_e32 v121, v129
	v_mov_b32_e32 v120, v129
	v_mov_b32_e32 v119, v129
	v_mov_b32_e32 v118, v129
	v_mov_b32_e32 v117, v129
	v_mov_b32_e32 v116, v129
	v_mov_b32_e32 v115, v129
	v_mov_b32_e32 v114, v129
	v_mov_b32_e32 v105, v129
	v_mov_b32_e32 v104, v129
	v_mov_b32_e32 v103, v129
	v_mov_b32_e32 v102, v129
	v_mov_b32_e32 v101, v129
	v_mov_b32_e32 v100, v129
	v_mov_b32_e32 v99, v129
	v_mov_b32_e32 v98, v129
	v_mov_b32_e32 v89, v129
	v_mov_b32_e32 v88, v129
	v_mov_b32_e32 v87, v129
	v_mov_b32_e32 v86, v129
	v_mov_b32_e32 v85, v129
	v_mov_b32_e32 v84, v129
	v_mov_b32_e32 v83, v129
	v_mov_b32_e32 v82, v129
	v_mov_b32_e32 v73, v129
	v_mov_b32_e32 v72, v129
	v_mov_b32_e32 v71, v129
	v_mov_b32_e32 v70, v129
	v_mov_b32_e32 v69, v129
	v_mov_b32_e32 v68, v129
	v_mov_b32_e32 v67, v129
	v_mov_b32_e32 v66, v129
	v_mov_b32_e32 v65, v129
	v_mov_b32_e32 v64, v129
	v_mov_b32_e32 v63, v129
	v_mov_b32_e32 v62, v129
	v_mov_b32_e32 v61, v129
	v_mov_b32_e32 v60, v129
	v_mov_b32_e32 v59, v129
	v_mov_b32_e32 v58, v129
	v_mov_b32_e32 v49, v129
	v_mov_b32_e32 v48, v129
	v_mov_b32_e32 v47, v129
	v_mov_b32_e32 v46, v129
	v_mov_b32_e32 v45, v129
	v_mov_b32_e32 v44, v129
	v_mov_b32_e32 v43, v129
	v_mov_b32_e32 v42, v129
	v_mov_b32_e32 v33, v129
	v_mov_b32_e32 v32, v129
	v_mov_b32_e32 v31, v129
	v_mov_b32_e32 v30, v129
	v_mov_b32_e32 v29, v129
	v_mov_b32_e32 v28, v129
	v_mov_b32_e32 v27, v129
	v_mov_b32_e32 v26, v129
	v_mov_b32_e32 v17, v129
	v_mov_b32_e32 v16, v129
	v_mov_b32_e32 v15, v129
	v_mov_b32_e32 v14, v129
	v_mov_b32_e32 v13, v129
	v_mov_b32_e32 v12, v129
	v_mov_b32_e32 v11, v129
	v_mov_b32_e32 v10, v129
	v_mov_b32_e32 v57, v129
	v_mov_b32_e32 v56, v129
	v_mov_b32_e32 v55, v129
	v_mov_b32_e32 v54, v129
	v_mov_b32_e32 v53, v129
	v_mov_b32_e32 v52, v129
	v_mov_b32_e32 v51, v129
	v_mov_b32_e32 v50, v129
	v_mov_b32_e32 v41, v129
	v_mov_b32_e32 v40, v129
	v_mov_b32_e32 v39, v129
	v_mov_b32_e32 v38, v129
	v_mov_b32_e32 v37, v129
	v_mov_b32_e32 v36, v129
	v_mov_b32_e32 v35, v129
	v_mov_b32_e32 v34, v129
	v_mov_b32_e32 v25, v129
	v_mov_b32_e32 v24, v129
	v_mov_b32_e32 v23, v129
	v_mov_b32_e32 v22, v129
	v_mov_b32_e32 v21, v129
	v_mov_b32_e32 v20, v129
	v_mov_b32_e32 v19, v129
	v_mov_b32_e32 v18, v129
	v_mov_b32_e32 v9, v129
	v_mov_b32_e32 v8, v129
	v_mov_b32_e32 v7, v129
	v_mov_b32_e32 v6, v129
	v_mov_b32_e32 v5, v129
	v_mov_b32_e32 v4, v129
	v_mov_b32_e32 v3, v129
	v_mov_b32_e32 v2, v129
	s_cbranch_vccnz .LBB0_1373
	s_add_u32 s59, s4, 0x100
	s_addc_u32 s60, s5, 0
	s_add_u32 s2, s30, 0x80
	v_mov_b32_e32 v2, 0
	s_addc_u32 s3, s31, 0
	s_mov_b32 s4, 0
.LBB0_1371:
	s_add_i32 s30, s4, 2
	s_add_u32 s31, s2, 0x80
	s_addc_u32 s5, s3, 0
	s_add_i32 s61, 0, 0x10000
	s_cmp_eq_u32 s46, s4
	s_cselect_b32 s5, s27, s5
	s_cselect_b32 s4, s26, s31
	v_add_u32_e32 v146, s61, v149
	s_cselect_b32 s63, s29, s60
	s_cselect_b32 s62, s28, s59
	s_add_i32 s31, 0, 0x14000
	ds_read_b128 v[142:145], v146
	ds_read_b128 v[152:155], v146 offset:1024
	ds_read_b128 v[156:159], v146 offset:2048
	ds_read_b128 v[160:163], v146 offset:3072
	v_add_u32_e32 v146, s31, v149
	ds_read_b128 v[164:167], v146
	ds_read_b128 v[168:171], v146 offset:1024
	ds_read_b128 v[172:175], v146 offset:2048
	ds_read_b128 v[176:179], v146 offset:3072
	v_lshl_add_u64 v[146:147], s[2:3], 0, v[140:141]
	s_add_i32 m0, s39, 0xc000
	ds_read_b128 v[180:183], v151
	ds_read_b128 v[184:187], v151 offset:1024
	ds_read_b128 v[188:191], v151 offset:2048
	ds_read_b128 v[196:199], v151 offset:3072
	ds_read_b128 v[200:203], v151 offset:4096
	ds_read_b128 v[206:209], v151 offset:5120
	ds_read_b128 v[210:213], v151 offset:6144
	ds_read_b128 v[214:217], v151 offset:7168
	global_load_lds_dwordx4 v[146:147], off
	v_lshl_add_u64 v[146:147], s[2:3], 0, v[138:139]
	s_add_i32 m0, s39, 0xe000
	s_nop 0
	global_load_lds_dwordx4 v[146:147], off
	s_waitcnt vmcnt(8)
	s_waitcnt lgkmcnt(0)
	s_barrier
; #define PG8_STAGE(bufoff, gbase, voff) do { _Pragma("unroll") for (int _i = 0; _i < 2; ++_i) \
;         __builtin_amdgcn_global_load_lds((const unsigned*)((const char*)(gbase) + (voff)[_i]), (PG8_LAS unsigned*)(lds + (bufoff) + ldsw + _i * 8192), 16, 0, 0); } while (0)
; #define PG8_LDA(dst, b, h) do { _Pragma("unroll") for (int m = 0; m < 4; ++m) _Pragma("unroll") for (int k = 0; k < 2; ++k) dst[m][k] = *(const PG8_LAS bf16x8*)(lds + PG8_SA(b, h) + aoff + m * 2048 + k * 1024); } while (0)
; #define PG8_MMA(ai, bj, At, Bt) do { __builtin_amdgcn_s_setprio(1); _Pragma("unroll") for (int m = 0; m < 4; ++m) _Pragma("unroll") for (int n = 0; n < 2; ++n) _Pragma("unroll") for (int k = 0; k < 2; ++k) \
;         acc[ai][bj][m][n] = __builtin_amdgcn_mfma_f32_16x16x32_bf16(Bt[n][k], At[m][k], acc[ai][bj][m][n], 0, 0, 0); __builtin_amdgcn_s_setprio(0); } while (0)
; #define PG8_WAIT_V(n) asm volatile("s_waitcnt vmcnt(" #n ")" ::: "memory")
; #define PG8_WAIT_L(n) asm volatile("s_waitcnt lgkmcnt(" #n ")" ::: "memory")
; #define PG8_BAR __builtin_amdgcn_s_barrier()
; #define PG8_SCHED __builtin_amdgcn_sched_barrier(0)
; template <class Epi, class Sched, bool ALIGN_EPI = false, bool SP2 = false>
; __device__ __forceinline__ void gemm_phase(PG8_LAS unsigned char* lds, const Gemm g, const Sched& S, const Epi& E) {
;     ...
;             PG8_WAIT_V(8); PG8_WAIT_L(0); PG8_BAR; PG8_MMA(0, 0, At, B0); PG8_MMA(0, 1, At, B1); PG8_BAR; PG8_SCHED;
;             PG8_LDA(At, 0, 1); PG8_STAGE(PG8_SB(0, 0), b2, voffB); PG8_STAGE(PG8_SB(0, 1), b2 + hstep, voffB); PG8_STAGE(PG8_SA(0, 0), a2, voffA);
;             PG8_WAIT_V(8); PG8_WAIT_L(0); PG8_BAR; PG8_MMA(1, 0, At, B0); PG8_MMA(1, 1, At, B1); PG8_BAR; PG8_SCHED;
	s_setprio 1
	s_waitcnt lgkmcnt(0)
	v_mfma_f32_16x16x32_bf16 v[126:129], v[142:145], v[180:183], v[126:129]
	v_mfma_f32_16x16x32_bf16 v[122:125], v[156:159], v[180:183], v[122:125]
	v_mfma_f32_16x16x32_bf16 v[110:113], v[142:145], v[188:191], v[110:113]
	v_mfma_f32_16x16x32_bf16 v[106:109], v[156:159], v[188:191], v[106:109]
	v_mfma_f32_16x16x32_bf16 v[94:97], v[142:145], v[200:203], v[94:97]
	v_mfma_f32_16x16x32_bf16 v[90:93], v[156:159], v[200:203], v[90:93]
	v_mfma_f32_16x16x32_bf16 v[78:81], v[142:145], v[210:213], v[78:81]
	v_mfma_f32_16x16x32_bf16 v[74:77], v[156:159], v[210:213], v[74:77]
	v_mfma_f32_16x16x32_bf16 v[126:129], v[152:155], v[184:187], v[126:129]
	v_mfma_f32_16x16x32_bf16 v[122:125], v[160:163], v[184:187], v[122:125]
	v_mfma_f32_16x16x32_bf16 v[110:113], v[152:155], v[196:199], v[110:113]
	v_mfma_f32_16x16x32_bf16 v[106:109], v[160:163], v[196:199], v[106:109]
	v_mfma_f32_16x16x32_bf16 v[94:97], v[152:155], v[206:209], v[94:97]
	v_mfma_f32_16x16x32_bf16 v[90:93], v[160:163], v[206:209], v[90:93]
	v_mfma_f32_16x16x32_bf16 v[78:81], v[152:155], v[214:217], v[78:81]
	v_mfma_f32_16x16x32_bf16 v[74:77], v[160:163], v[214:217], v[74:77]
	s_setprio 0
	s_setprio 1
	v_mfma_f32_16x16x32_bf16 v[118:121], v[164:167], v[180:183], v[118:121]
	v_mfma_f32_16x16x32_bf16 v[114:117], v[172:175], v[180:183], v[114:117]
	v_mfma_f32_16x16x32_bf16 v[102:105], v[164:167], v[188:191], v[102:105]
	v_mfma_f32_16x16x32_bf16 v[98:101], v[172:175], v[188:191], v[98:101]
	v_mfma_f32_16x16x32_bf16 v[86:89], v[164:167], v[200:203], v[86:89]
	v_mfma_f32_16x16x32_bf16 v[82:85], v[172:175], v[200:203], v[82:85]
	v_mfma_f32_16x16x32_bf16 v[70:73], v[164:167], v[210:213], v[70:73]
	v_mfma_f32_16x16x32_bf16 v[66:69], v[172:175], v[210:213], v[66:69]
	v_mfma_f32_16x16x32_bf16 v[118:121], v[168:171], v[184:187], v[118:121]
	v_mfma_f32_16x16x32_bf16 v[114:117], v[176:179], v[184:187], v[114:117]
	v_mfma_f32_16x16x32_bf16 v[102:105], v[168:171], v[196:199], v[102:105]
	v_mfma_f32_16x16x32_bf16 v[98:101], v[176:179], v[196:199], v[98:101]
	v_mfma_f32_16x16x32_bf16 v[86:89], v[168:171], v[206:209], v[86:89]
	v_mfma_f32_16x16x32_bf16 v[82:85], v[176:179], v[206:209], v[82:85]
	v_mfma_f32_16x16x32_bf16 v[70:73], v[168:171], v[214:217], v[70:73]
	v_mfma_f32_16x16x32_bf16 v[66:69], v[176:179], v[214:217], v[66:69]
	s_setprio 0
	s_barrier
	s_add_i32 s61, s61, s38
	v_lshl_add_u64 v[146:147], s[62:63], 0, v[132:133]
	s_mov_b32 m0, s61
	ds_read_b128 v[180:183], v151 offset:16384
	ds_read_b128 v[184:187], v151 offset:17408
	ds_read_b128 v[188:191], v151 offset:18432
	ds_read_b128 v[196:199], v151 offset:19456
	ds_read_b128 v[200:203], v151 offset:20480
	ds_read_b128 v[206:209], v151 offset:21504
	ds_read_b128 v[210:213], v151 offset:22528
	ds_read_b128 v[214:217], v151 offset:23552
	global_load_lds_dwordx4 v[146:147], off
	s_add_i32 m0, s61, 0x2000
	v_lshl_add_u64 v[192:193], s[62:63], 0, v[136:137]
	s_add_u32 s62, s62, s8
	s_addc_u32 s63, s63, s9
	s_add_i32 s31, s31, s38
	global_load_lds_dwordx4 v[192:193], off
	v_lshl_add_u64 v[204:205], s[62:63], 0, v[132:133]
	s_mov_b32 m0, s31
	v_lshl_add_u64 v[218:219], s[62:63], 0, v[136:137]
	global_load_lds_dwordx4 v[204:205], off
	s_add_i32 m0, s31, 0x2000
	v_lshl_add_u64 v[220:221], s[4:5], 0, v[130:131]
	global_load_lds_dwordx4 v[218:219], off
	s_mov_b32 m0, s39
	v_lshl_add_u64 v[228:229], s[4:5], 0, v[134:135]
	global_load_lds_dwordx4 v[220:221], off
	s_mov_b32 m0, s40
	s_nop 0
	global_load_lds_dwordx4 v[228:229], off
	s_waitcnt vmcnt(8)
	s_waitcnt lgkmcnt(0)
	s_barrier
	s_setprio 1
	s_waitcnt lgkmcnt(0)
	v_mfma_f32_16x16x32_bf16 v[62:65], v[142:145], v[180:183], v[62:65]
	v_mfma_f32_16x16x32_bf16 v[58:61], v[156:159], v[180:183], v[58:61]
	v_mfma_f32_16x16x32_bf16 v[46:49], v[142:145], v[188:191], v[46:49]
	v_mfma_f32_16x16x32_bf16 v[42:45], v[156:159], v[188:191], v[42:45]
	v_mfma_f32_16x16x32_bf16 v[30:33], v[142:145], v[200:203], v[30:33]
	v_mfma_f32_16x16x32_bf16 v[26:29], v[156:159], v[200:203], v[26:29]
	v_mfma_f32_16x16x32_bf16 v[14:17], v[142:145], v[210:213], v[14:17]
	v_mfma_f32_16x16x32_bf16 v[10:13], v[156:159], v[210:213], v[10:13]
	v_mfma_f32_16x16x32_bf16 v[62:65], v[152:155], v[184:187], v[62:65]
	v_mfma_f32_16x16x32_bf16 v[58:61], v[160:163], v[184:187], v[58:61]
	v_mfma_f32_16x16x32_bf16 v[46:49], v[152:155], v[196:199], v[46:49]
	v_mfma_f32_16x16x32_bf16 v[42:45], v[160:163], v[196:199], v[42:45]
	v_mfma_f32_16x16x32_bf16 v[30:33], v[152:155], v[206:209], v[30:33]
	v_mfma_f32_16x16x32_bf16 v[26:29], v[160:163], v[206:209], v[26:29]
	v_mfma_f32_16x16x32_bf16 v[14:17], v[152:155], v[214:217], v[14:17]
	v_mfma_f32_16x16x32_bf16 v[10:13], v[160:163], v[214:217], v[10:13]
	s_setprio 0
	s_setprio 1
	v_mfma_f32_16x16x32_bf16 v[54:57], v[164:167], v[180:183], v[54:57]
	v_mfma_f32_16x16x32_bf16 v[50:53], v[172:175], v[180:183], v[50:53]
	v_mfma_f32_16x16x32_bf16 v[38:41], v[164:167], v[188:191], v[38:41]
	v_mfma_f32_16x16x32_bf16 v[34:37], v[172:175], v[188:191], v[34:37]
	v_mfma_f32_16x16x32_bf16 v[22:25], v[164:167], v[200:203], v[22:25]
	v_mfma_f32_16x16x32_bf16 v[18:21], v[172:175], v[200:203], v[18:21]
	v_mfma_f32_16x16x32_bf16 v[6:9], v[164:167], v[210:213], v[6:9]
	v_mfma_f32_16x16x32_bf16 v[2:5], v[172:175], v[210:213], v[2:5]
	v_mfma_f32_16x16x32_bf16 v[54:57], v[168:171], v[184:187], v[54:57]
	v_mfma_f32_16x16x32_bf16 v[50:53], v[176:179], v[184:187], v[50:53]
	v_mfma_f32_16x16x32_bf16 v[38:41], v[168:171], v[196:199], v[38:41]
	v_mfma_f32_16x16x32_bf16 v[34:37], v[176:179], v[196:199], v[34:37]
	v_mfma_f32_16x16x32_bf16 v[22:25], v[168:171], v[206:209], v[22:25]
	v_mfma_f32_16x16x32_bf16 v[18:21], v[176:179], v[206:209], v[18:21]
	v_mfma_f32_16x16x32_bf16 v[6:9], v[168:171], v[214:217], v[6:9]
	v_mfma_f32_16x16x32_bf16 v[2:5], v[176:179], v[214:217], v[2:5]
	s_setprio 0
	s_barrier
; #define PG8_STAGE(bufoff, gbase, voff) do { _Pragma("unroll") for (int _i = 0; _i < 2; ++_i) \
;         __builtin_amdgcn_global_load_lds((const unsigned*)((const char*)(gbase) + (voff)[_i]), (PG8_LAS unsigned*)(lds + (bufoff) + ldsw + _i * 8192), 16, 0, 0); } while (0)
; #define PG8_LDA(dst, b, h) do { _Pragma("unroll") for (int m = 0; m < 4; ++m) _Pragma("unroll") for (int k = 0; k < 2; ++k) dst[m][k] = *(const PG8_LAS bf16x8*)(lds + PG8_SA(b, h) + aoff + m * 2048 + k * 1024); } while (0)
; #define PG8_LDB(dst, b, h) do { _Pragma("unroll") for (int n = 0; n < 2; ++n) _Pragma("unroll") for (int k = 0; k < 2; ++k) dst[n][k] = *(const PG8_LAS bf16x8*)(lds + PG8_SB(b, h) + boff + n * 2048 + k * 1024); } while (0)
; #define PG8_MMA(ai, bj, At, Bt) do { __builtin_amdgcn_s_setprio(1); _Pragma("unroll") for (int m = 0; m < 4; ++m) _Pragma("unroll") for (int n = 0; n < 2; ++n) _Pragma("unroll") for (int k = 0; k < 2; ++k) \
;         acc[ai][bj][m][n] = __builtin_amdgcn_mfma_f32_16x16x32_bf16(Bt[n][k], At[m][k], acc[ai][bj][m][n], 0, 0, 0); __builtin_amdgcn_s_setprio(0); } while (0)
; #define PG8_WAIT_V(n) asm volatile("s_waitcnt vmcnt(" #n ")" ::: "memory")
; #define PG8_WAIT_L(n) asm volatile("s_waitcnt lgkmcnt(" #n ")" ::: "memory")
; #define PG8_BAR __builtin_amdgcn_s_barrier()
; #define PG8_SCHED __builtin_amdgcn_sched_barrier(0)
; template <class Epi, class Sched, bool ALIGN_EPI = false, bool SP2 = false>
; __device__ __forceinline__ void gemm_phase(PG8_LAS unsigned char* lds, const Gemm g, const Sched& S, const Epi& E) {
;     ...
;             PG8_LDB(B0, 1, 0); PG8_LDB(B1, 1, 1); PG8_SCHED; PG8_LDA(At, 1, 0); PG8_STAGE(PG8_SA(0, 1), a2 + hstep, voffA);
;             PG8_WAIT_V(8); PG8_WAIT_L(0); PG8_BAR; PG8_MMA(0, 0, At, B0); PG8_MMA(0, 1, At, B1); PG8_BAR; PG8_SCHED;
	s_add_i32 s31, 0, 0x18000
	s_add_i32 s61, 0, 0x1c000
	v_add_u32_e32 v160, s31, v149
	v_add_u32_e32 v176, s61, v149
	ds_read_b128 v[142:145], v160
	ds_read_b128 v[152:155], v160 offset:1024
	ds_read_b128 v[156:159], v160 offset:2048
	ds_read_b128 v[160:163], v160 offset:3072
	ds_read_b128 v[164:167], v176
	ds_read_b128 v[168:171], v176 offset:1024
	ds_read_b128 v[172:175], v176 offset:2048
	ds_read_b128 v[176:179], v176 offset:3072
	s_add_u32 s4, s4, s8
	s_addc_u32 s5, s5, s9
	s_mov_b32 m0, s41
	v_lshl_add_u64 v[240:241], s[4:5], 0, v[130:131]
	ds_read_b128 v[180:183], v151 offset:32768
	ds_read_b128 v[184:187], v151 offset:33792
	ds_read_b128 v[188:191], v151 offset:34816
	ds_read_b128 v[196:199], v151 offset:35840
	ds_read_b128 v[200:203], v151 offset:36864
	ds_read_b128 v[206:209], v151 offset:37888
	ds_read_b128 v[210:213], v151 offset:38912
	ds_read_b128 v[214:217], v151 offset:39936
	global_load_lds_dwordx4 v[240:241], off
	v_lshl_add_u64 v[240:241], s[4:5], 0, v[134:135]
	s_mov_b32 m0, s42
	s_nop 0
	global_load_lds_dwordx4 v[240:241], off
	s_waitcnt vmcnt(8)
	s_waitcnt lgkmcnt(0)
	s_barrier
	s_setprio 1
	s_waitcnt lgkmcnt(0)
	v_mfma_f32_16x16x32_bf16 v[126:129], v[142:145], v[180:183], v[126:129]
	v_mfma_f32_16x16x32_bf16 v[122:125], v[156:159], v[180:183], v[122:125]
	v_mfma_f32_16x16x32_bf16 v[110:113], v[142:145], v[188:191], v[110:113]
	v_mfma_f32_16x16x32_bf16 v[106:109], v[156:159], v[188:191], v[106:109]
	v_mfma_f32_16x16x32_bf16 v[94:97], v[142:145], v[200:203], v[94:97]
	v_mfma_f32_16x16x32_bf16 v[90:93], v[156:159], v[200:203], v[90:93]
	v_mfma_f32_16x16x32_bf16 v[78:81], v[142:145], v[210:213], v[78:81]
	v_mfma_f32_16x16x32_bf16 v[74:77], v[156:159], v[210:213], v[74:77]
	v_mfma_f32_16x16x32_bf16 v[126:129], v[152:155], v[184:187], v[126:129]
	v_mfma_f32_16x16x32_bf16 v[122:125], v[160:163], v[184:187], v[122:125]
	v_mfma_f32_16x16x32_bf16 v[110:113], v[152:155], v[196:199], v[110:113]
	v_mfma_f32_16x16x32_bf16 v[106:109], v[160:163], v[196:199], v[106:109]
	v_mfma_f32_16x16x32_bf16 v[94:97], v[152:155], v[206:209], v[94:97]
	v_mfma_f32_16x16x32_bf16 v[90:93], v[160:163], v[206:209], v[90:93]
	v_mfma_f32_16x16x32_bf16 v[78:81], v[152:155], v[214:217], v[78:81]
	v_mfma_f32_16x16x32_bf16 v[74:77], v[160:163], v[214:217], v[74:77]
	s_setprio 0
	s_setprio 1
	v_mfma_f32_16x16x32_bf16 v[118:121], v[164:167], v[180:183], v[118:121]
	v_mfma_f32_16x16x32_bf16 v[114:117], v[172:175], v[180:183], v[114:117]
	v_mfma_f32_16x16x32_bf16 v[102:105], v[164:167], v[188:191], v[102:105]
	v_mfma_f32_16x16x32_bf16 v[98:101], v[172:175], v[188:191], v[98:101]
	v_mfma_f32_16x16x32_bf16 v[86:89], v[164:167], v[200:203], v[86:89]
	v_mfma_f32_16x16x32_bf16 v[82:85], v[172:175], v[200:203], v[82:85]
	v_mfma_f32_16x16x32_bf16 v[70:73], v[164:167], v[210:213], v[70:73]
	v_mfma_f32_16x16x32_bf16 v[66:69], v[172:175], v[210:213], v[66:69]
	v_mfma_f32_16x16x32_bf16 v[118:121], v[168:171], v[184:187], v[118:121]
	v_mfma_f32_16x16x32_bf16 v[114:117], v[176:179], v[184:187], v[114:117]
	v_mfma_f32_16x16x32_bf16 v[102:105], v[168:171], v[196:199], v[102:105]
	v_mfma_f32_16x16x32_bf16 v[98:101], v[176:179], v[196:199], v[98:101]
	v_mfma_f32_16x16x32_bf16 v[86:89], v[168:171], v[206:209], v[86:89]
	v_mfma_f32_16x16x32_bf16 v[82:85], v[176:179], v[206:209], v[82:85]
	v_mfma_f32_16x16x32_bf16 v[70:73], v[168:171], v[214:217], v[70:73]
	v_mfma_f32_16x16x32_bf16 v[66:69], v[176:179], v[214:217], v[66:69]
	s_setprio 0
	s_barrier
; #define PG8_STAGE(bufoff, gbase, voff) do { _Pragma("unroll") for (int _i = 0; _i < 2; ++_i) \
;         __builtin_amdgcn_global_load_lds((const unsigned*)((const char*)(gbase) + (voff)[_i]), (PG8_LAS unsigned*)(lds + (bufoff) + ldsw + _i * 8192), 16, 0, 0); } while (0)
; #define PG8_LDA(dst, b, h) do { _Pragma("unroll") for (int m = 0; m < 4; ++m) _Pragma("unroll") for (int k = 0; k < 2; ++k) dst[m][k] = *(const PG8_LAS bf16x8*)(lds + PG8_SA(b, h) + aoff + m * 2048 + k * 1024); } while (0)
; #define PG8_MMA(ai, bj, At, Bt) do { __builtin_amdgcn_s_setprio(1); _Pragma("unroll") for (int m = 0; m < 4; ++m) _Pragma("unroll") for (int n = 0; n < 2; ++n) _Pragma("unroll") for (int k = 0; k < 2; ++k) \
;         acc[ai][bj][m][n] = __builtin_amdgcn_mfma_f32_16x16x32_bf16(Bt[n][k], At[m][k], acc[ai][bj][m][n], 0, 0, 0); __builtin_amdgcn_s_setprio(0); } while (0)
; #define PG8_WAIT_V(n) asm volatile("s_waitcnt vmcnt(" #n ")" ::: "memory")
; #define PG8_WAIT_L(n) asm volatile("s_waitcnt lgkmcnt(" #n ")" ::: "memory")
; #define PG8_BAR __builtin_amdgcn_s_barrier()
; #define PG8_SCHED __builtin_amdgcn_sched_barrier(0)
; template <class Epi, class Sched, bool ALIGN_EPI = false, bool SP2 = false>
; __device__ __forceinline__ void gemm_phase(PG8_LAS unsigned char* lds, const Gemm g, const Sched& S, const Epi& E) {
;     ...
;             PG8_LDA(At, 1, 1); PG8_STAGE(PG8_SB(1, 0), b3, voffB); PG8_STAGE(PG8_SB(1, 1), b3 + hstep, voffB); PG8_STAGE(PG8_SA(1, 0), a3, voffA);
;             PG8_WAIT_V(8); PG8_WAIT_L(0); PG8_BAR; PG8_MMA(1, 0, At, B0); PG8_MMA(1, 1, At, B1); PG8_BAR; PG8_SCHED;
	s_add_i32 s4, s31, s38
	v_lshl_add_u64 v[146:147], v[146:147], 0, s[20:21]
	s_mov_b32 m0, s4
	ds_read_b128 v[180:183], v151 offset:49152
	ds_read_b128 v[184:187], v151 offset:50176
	ds_read_b128 v[188:191], v151 offset:51200
	ds_read_b128 v[196:199], v151 offset:52224
	ds_read_b128 v[200:203], v151 offset:53248
	ds_read_b128 v[206:209], v151 offset:54272
	ds_read_b128 v[210:213], v151 offset:55296
	ds_read_b128 v[214:217], v151 offset:56320
	global_load_lds_dwordx4 v[146:147], off
	v_lshl_add_u64 v[146:147], v[192:193], 0, s[20:21]
	s_add_i32 m0, s4, 0x2000
	s_add_i32 s4, s61, s38
	global_load_lds_dwordx4 v[146:147], off
	v_lshl_add_u64 v[146:147], v[204:205], 0, s[20:21]
	s_mov_b32 m0, s4
	s_nop 0
	global_load_lds_dwordx4 v[146:147], off
	v_lshl_add_u64 v[146:147], v[218:219], 0, s[20:21]
	s_add_i32 m0, s4, 0x2000
	s_nop 0
	global_load_lds_dwordx4 v[146:147], off
	v_lshl_add_u64 v[146:147], v[220:221], 0, s[20:21]
	s_mov_b32 m0, s44
	s_nop 0
	global_load_lds_dwordx4 v[146:147], off
	v_lshl_add_u64 v[146:147], v[228:229], 0, s[20:21]
	s_mov_b32 m0, s45
	s_nop 0
	global_load_lds_dwordx4 v[146:147], off
	s_waitcnt vmcnt(8)
	s_waitcnt lgkmcnt(0)
	s_barrier
	s_setprio 1
	s_waitcnt lgkmcnt(0)
	v_mfma_f32_16x16x32_bf16 v[62:65], v[142:145], v[180:183], v[62:65]
	v_mfma_f32_16x16x32_bf16 v[58:61], v[156:159], v[180:183], v[58:61]
	v_mfma_f32_16x16x32_bf16 v[46:49], v[142:145], v[188:191], v[46:49]
	v_mfma_f32_16x16x32_bf16 v[42:45], v[156:159], v[188:191], v[42:45]
	v_mfma_f32_16x16x32_bf16 v[30:33], v[142:145], v[200:203], v[30:33]
	v_mfma_f32_16x16x32_bf16 v[26:29], v[156:159], v[200:203], v[26:29]
	v_mfma_f32_16x16x32_bf16 v[14:17], v[142:145], v[210:213], v[14:17]
	v_mfma_f32_16x16x32_bf16 v[10:13], v[156:159], v[210:213], v[10:13]
	v_mfma_f32_16x16x32_bf16 v[62:65], v[152:155], v[184:187], v[62:65]
	v_mfma_f32_16x16x32_bf16 v[58:61], v[160:163], v[184:187], v[58:61]
	v_mfma_f32_16x16x32_bf16 v[46:49], v[152:155], v[196:199], v[46:49]
	v_mfma_f32_16x16x32_bf16 v[42:45], v[160:163], v[196:199], v[42:45]
	v_mfma_f32_16x16x32_bf16 v[30:33], v[152:155], v[206:209], v[30:33]
	v_mfma_f32_16x16x32_bf16 v[26:29], v[160:163], v[206:209], v[26:29]
	v_mfma_f32_16x16x32_bf16 v[14:17], v[152:155], v[214:217], v[14:17]
	v_mfma_f32_16x16x32_bf16 v[10:13], v[160:163], v[214:217], v[10:13]
	s_setprio 0
	s_setprio 1
	v_mfma_f32_16x16x32_bf16 v[54:57], v[164:167], v[180:183], v[54:57]
	v_mfma_f32_16x16x32_bf16 v[50:53], v[172:175], v[180:183], v[50:53]
	v_mfma_f32_16x16x32_bf16 v[38:41], v[164:167], v[188:191], v[38:41]
	v_mfma_f32_16x16x32_bf16 v[34:37], v[172:175], v[188:191], v[34:37]
	v_mfma_f32_16x16x32_bf16 v[22:25], v[164:167], v[200:203], v[22:25]
	v_mfma_f32_16x16x32_bf16 v[18:21], v[172:175], v[200:203], v[18:21]
	v_mfma_f32_16x16x32_bf16 v[6:9], v[164:167], v[210:213], v[6:9]
	v_mfma_f32_16x16x32_bf16 v[2:5], v[172:175], v[210:213], v[2:5]
	v_mfma_f32_16x16x32_bf16 v[54:57], v[168:171], v[184:187], v[54:57]
	v_mfma_f32_16x16x32_bf16 v[50:53], v[176:179], v[184:187], v[50:53]
	v_mfma_f32_16x16x32_bf16 v[38:41], v[168:171], v[196:199], v[38:41]
	v_mfma_f32_16x16x32_bf16 v[34:37], v[176:179], v[196:199], v[34:37]
	v_mfma_f32_16x16x32_bf16 v[22:25], v[168:171], v[206:209], v[22:25]
	v_mfma_f32_16x16x32_bf16 v[18:21], v[176:179], v[206:209], v[18:21]
	v_mfma_f32_16x16x32_bf16 v[6:9], v[168:171], v[214:217], v[6:9]
	v_mfma_f32_16x16x32_bf16 v[2:5], v[176:179], v[214:217], v[2:5]
	s_setprio 0
	s_barrier
	s_add_u32 s59, s59, 0x100
	s_addc_u32 s60, s60, 0
	s_add_u32 s2, s2, 0x100
	s_addc_u32 s3, s3, 0
	s_cmp_ge_i32 s30, s43
	s_mov_b32 s4, s30
	s_cbranch_scc0 .LBB0_1371
	v_readlane_b32 s60, v252, 48
	v_readlane_b32 s61, v252, 49
	s_mov_b32 s62, 0xa000
	s_movk_i32 s63, 0x100
